# v50 + agent-scope write-through (sc1) on the full-line row stores of EMBED and the three NORM phases (less dirty L2 at the following grid barrier)
# baseline (speedup 1.0000x reference)
.LBB0_187:
	v_pk_mul_f32 v[174:175], v[148:149], v[148:149]
	v_pk_mul_f32 v[176:177], v[146:147], v[146:147]
	s_ashr_i32 s27, s26, 31
	v_pk_mov_b32 v[178:179], v[176:177], v[174:175] op_sel:[1,0]
	v_mov_b32_e32 v177, v175
	v_pk_add_f32 v[174:175], v[178:179], v[176:177]
	v_pk_mul_f32 v[176:177], v[152:153], v[152:153]
	v_pk_add_f32 v[174:175], v[174:175], v[174:175] op_sel_hi:[0,1]
	v_pk_mul_f32 v[178:179], v[150:151], v[150:151]
	v_mul_f32_e32 v174, v138, v138
	v_pk_mov_b32 v[180:181], v[178:179], v[176:177] op_sel:[1,0]
	v_mov_b32_e32 v179, v177
	v_pk_add_f32 v[176:177], v[180:181], v[178:179]
	v_pk_fma_f32 v[178:179], v[138:139], v[138:139], v[174:175] op_sel_hi:[1,1,0]
	v_mul_f32_e32 v174, v140, v140
	v_pk_add_f32 v[176:177], v[176:177], v[176:177] op_sel_hi:[0,1]
	v_pk_fma_f32 v[180:181], v[140:141], v[140:141], v[174:175] op_sel_hi:[1,1,0]
	v_mul_f32_e32 v178, v142, v142
	v_mul_f32_e32 v180, v143, v143
	v_mul_f32_e32 v176, v144, v144
	v_mul_f32_e32 v174, v145, v145
	v_pk_add_f32 v[178:179], v[178:179], v[180:181]
	v_pk_add_f32 v[174:175], v[176:177], v[174:175]
	s_lshl_b64 s[4:5], s[26:27], 11
	v_pk_add_f32 v[174:175], v[178:179], v[174:175]
	s_lshl_b64 s[18:19], s[26:27], 12
	v_add_f32_e32 v173, v174, v175
	ds_bpermute_b32 v174, v1, v173
	v_lshl_add_u64 v[178:179], v[162:163], 0, s[4:5]
	s_add_u32 s4, s54, s18
	s_addc_u32 s5, s55, s19
	s_add_i32 s8, s14, 0xc00
	s_waitcnt lgkmcnt(0)
	v_add_f32_e32 v173, v173, v174
	ds_bpermute_b32 v174, v155, v173
	s_and_b32 s8, s8, 0x400
	s_lshl_b32 s8, s8, 1
	s_add_u32 s4, s4, s8
	s_addc_u32 s5, s5, 0
	s_waitcnt lgkmcnt(0)
	v_add_f32_e32 v173, v173, v174
	ds_bpermute_b32 v174, v168, v173
	s_waitcnt lgkmcnt(0)
	v_add_f32_e32 v173, v173, v174
	ds_bpermute_b32 v174, v169, v173
	s_waitcnt lgkmcnt(0)
	v_add_f32_e32 v173, v173, v174
	ds_bpermute_b32 v174, v170, v173
	s_waitcnt lgkmcnt(0)
	v_add_f32_e32 v173, v173, v174
	ds_bpermute_b32 v174, v171, v173
	s_waitcnt lgkmcnt(0)
	v_add_f32_e32 v173, v173, v174
	v_fmamk_f32 v173, v173, 0x3a800000, v172
	v_mul_f32_e32 v174, 0x4b800000, v173
	v_cmp_gt_f32_e32 vcc, s15, v173
	s_nop 1
	v_cndmask_b32_e32 v173, v173, v174, vcc
	v_rsq_f32_e32 v173, v173
	s_nop 0
	v_mul_f32_e32 v174, 0x45800000, v173
	v_cndmask_b32_e32 v180, v173, v174, vcc
	v_pk_mul_f32 v[174:175], v[146:147], v[180:181] op_sel_hi:[1,0]
	v_pk_mul_f32 v[176:177], v[148:149], v[180:181] op_sel_hi:[1,0]
	v_pk_mul_f32 v[182:183], v[150:151], v[180:181] op_sel_hi:[1,0]
	v_pk_mul_f32 v[184:185], v[152:153], v[180:181] op_sel_hi:[1,0]
	s_waitcnt vmcnt(2)
	v_pk_fma_f32 v[176:177], v[124:125], v[176:177], v[112:113]
	v_pk_fma_f32 v[174:175], v[122:123], v[174:175], v[110:111]
	v_pk_fma_f32 v[184:185], v[128:129], v[184:185], v[108:109]
	v_pk_fma_f32 v[182:183], v[126:127], v[182:183], v[106:107]
	v_lshlrev_b32_e32 v173, 1, v154
	v_cvt_pk_bf16_f32 v174, v174, v175
	v_cvt_pk_bf16_f32 v175, v176, v177
	v_cvt_pk_bf16_f32 v176, v182, v183
	v_cvt_pk_bf16_f32 v177, v184, v185
	v_cvt_pk_bf16_f32 v146, v146, v147
	v_cvt_pk_bf16_f32 v147, v148, v149
	v_cvt_pk_bf16_f32 v148, v150, v151
	v_cvt_pk_bf16_f32 v149, v152, v153
	global_store_dwordx4 v[178:179], v[174:177], off sc1
	global_store_dwordx4 v173, v[146:149], s[4:5] nt
	v_pk_mul_f32 v[150:151], v[142:143], v[180:181] op_sel_hi:[1,0]
	v_pk_mul_f32 v[152:153], v[144:145], v[180:181] op_sel_hi:[1,0]
	v_pk_mul_f32 v[146:147], v[138:139], v[180:181] op_sel_hi:[1,0]
	v_pk_mul_f32 v[148:149], v[140:141], v[180:181] op_sel_hi:[1,0]
	s_waitcnt vmcnt(2)
	v_pk_fma_f32 v[146:147], v[130:131], v[146:147], v[118:119]
	v_pk_fma_f32 v[148:149], v[132:133], v[148:149], v[120:121]
	v_pk_fma_f32 v[152:153], v[136:137], v[152:153], v[116:117]
	v_pk_fma_f32 v[150:151], v[134:135], v[150:151], v[114:115]
	v_cvt_pk_bf16_f32 v146, v146, v147
	v_cvt_pk_bf16_f32 v147, v148, v149
	v_cvt_pk_bf16_f32 v148, v150, v151
	v_cvt_pk_bf16_f32 v149, v152, v153
	v_cvt_pk_bf16_f32 v138, v138, v139
	v_cvt_pk_bf16_f32 v139, v140, v141
	v_cvt_pk_bf16_f32 v140, v142, v143
	v_cvt_pk_bf16_f32 v141, v144, v145
	global_store_dwordx4 v[178:179], v[146:149], off offset:1024 sc1
	global_store_dwordx4 v173, v[138:141], s[4:5] offset:1024 nt

.LBB0_206:
	s_waitcnt vmcnt(2)
	v_pk_mul_f32 v[174:175], v[152:153], v[152:153]
	v_pk_mul_f32 v[176:177], v[150:151], v[150:151]
	s_lshl_b32 s4, s14, 1
	v_pk_mov_b32 v[178:179], v[176:177], v[174:175] op_sel:[1,0]
	v_mov_b32_e32 v177, v175
	v_pk_add_f32 v[174:175], v[178:179], v[176:177]
	v_pk_mul_f32 v[176:177], v[148:149], v[148:149]
	v_pk_add_f32 v[174:175], v[174:175], v[174:175] op_sel_hi:[0,1]
	v_pk_mul_f32 v[178:179], v[146:147], v[146:147]
	s_waitcnt vmcnt(0)
	v_mul_f32_e32 v174, v142, v142
	v_pk_mov_b32 v[180:181], v[178:179], v[176:177] op_sel:[1,0]
	v_mov_b32_e32 v179, v177
	v_pk_add_f32 v[176:177], v[180:181], v[178:179]
	v_pk_fma_f32 v[178:179], v[142:143], v[142:143], v[174:175] op_sel_hi:[1,1,0]
	v_mul_f32_e32 v174, v144, v144
	v_pk_add_f32 v[176:177], v[176:177], v[176:177] op_sel_hi:[0,1]
	v_pk_fma_f32 v[180:181], v[144:145], v[144:145], v[174:175] op_sel_hi:[1,1,0]
	v_mul_f32_e32 v178, v138, v138
	v_mul_f32_e32 v180, v139, v139
	v_mul_f32_e32 v176, v140, v140
	v_mul_f32_e32 v174, v141, v141
	v_pk_add_f32 v[178:179], v[178:179], v[180:181]
	v_pk_add_f32 v[174:175], v[176:177], v[174:175]
	s_and_b32 s8, s4, 0x800
	v_pk_add_f32 v[174:175], v[178:179], v[174:175]
	v_lshl_add_u64 v[178:179], v[166:167], 0, s[8:9]
	v_add_f32_e32 v173, v174, v175
	ds_bpermute_b32 v174, v1, v173
	s_waitcnt lgkmcnt(0)
	v_add_f32_e32 v173, v173, v174
	ds_bpermute_b32 v174, v155, v173
	s_waitcnt lgkmcnt(0)
	v_add_f32_e32 v173, v173, v174
	ds_bpermute_b32 v174, v168, v173
	s_waitcnt lgkmcnt(0)
	v_add_f32_e32 v173, v173, v174
	ds_bpermute_b32 v174, v169, v173
	s_waitcnt lgkmcnt(0)
	v_add_f32_e32 v173, v173, v174
	ds_bpermute_b32 v174, v170, v173
	s_waitcnt lgkmcnt(0)
	v_add_f32_e32 v173, v173, v174
	ds_bpermute_b32 v174, v171, v173
	s_waitcnt lgkmcnt(0)
	v_add_f32_e32 v173, v173, v174
	v_fmamk_f32 v173, v173, 0x3a800000, v172
	v_mul_f32_e32 v174, 0x4b800000, v173
	v_cmp_gt_f32_e32 vcc, s15, v173
	s_nop 1
	v_cndmask_b32_e32 v173, v173, v174, vcc
	v_rsq_f32_e32 v173, v173
	s_nop 0
	v_mul_f32_e32 v174, 0x45800000, v173
	v_cndmask_b32_e32 v180, v173, v174, vcc
	v_pk_mul_f32 v[174:175], v[150:151], v[180:181] op_sel_hi:[1,0]
	v_pk_mul_f32 v[176:177], v[152:153], v[180:181] op_sel_hi:[1,0]
	v_pk_mul_f32 v[182:183], v[146:147], v[180:181] op_sel_hi:[1,0]
	v_pk_mul_f32 v[184:185], v[148:149], v[180:181] op_sel_hi:[1,0]
	v_pk_fma_f32 v[176:177], v[124:125], v[176:177], v[112:113]
	v_pk_fma_f32 v[174:175], v[122:123], v[174:175], v[110:111]
	v_pk_fma_f32 v[184:185], v[128:129], v[184:185], v[108:109]
	v_pk_fma_f32 v[182:183], v[126:127], v[182:183], v[106:107]
	v_cvt_pk_bf16_f32 v174, v174, v175
	v_cvt_pk_bf16_f32 v175, v176, v177
	v_cvt_pk_bf16_f32 v176, v182, v183
	v_cvt_pk_bf16_f32 v177, v184, v185
	v_cvt_pk_bf16_f32 v150, v150, v151
	v_cvt_pk_bf16_f32 v151, v152, v153
	v_cvt_pk_bf16_f32 v152, v146, v147
	v_cvt_pk_bf16_f32 v153, v148, v149
	global_store_dwordx4 v[164:165], v[174:177], off sc1
	global_store_dwordx4 v[178:179], v[150:153], off offset:-1024 nt
	v_pk_mul_f32 v[146:147], v[142:143], v[180:181] op_sel_hi:[1,0]
	v_pk_mul_f32 v[148:149], v[144:145], v[180:181] op_sel_hi:[1,0]
	v_pk_mul_f32 v[150:151], v[138:139], v[180:181] op_sel_hi:[1,0]
	v_pk_mul_f32 v[152:153], v[140:141], v[180:181] op_sel_hi:[1,0]
	v_pk_fma_f32 v[148:149], v[132:133], v[148:149], v[120:121]
	v_pk_fma_f32 v[146:147], v[130:131], v[146:147], v[118:119]
	v_pk_fma_f32 v[152:153], v[136:137], v[152:153], v[116:117]
	v_pk_fma_f32 v[150:151], v[134:135], v[150:151], v[114:115]
	v_cvt_pk_bf16_f32 v142, v142, v143
	v_cvt_pk_bf16_f32 v143, v144, v145
	v_cvt_pk_bf16_f32 v144, v138, v139
	v_cndmask_b32_e64 v138, 0, 1, s[64:65]
	v_cvt_pk_bf16_f32 v146, v146, v147
	v_cvt_pk_bf16_f32 v147, v148, v149
	v_cvt_pk_bf16_f32 v148, v150, v151
	v_cvt_pk_bf16_f32 v149, v152, v153
	v_cvt_pk_bf16_f32 v145, v140, v141
	v_cmp_ne_u32_e64 s[4:5], 1, v138
	s_andn2_b64 vcc, exec, s[64:65]
	global_store_dwordx4 v[164:165], v[146:149], off offset:1024 sc1
	global_store_dwordx4 v[178:179], v[142:145], off nt
	s_cbranch_vccnz .LBB0_213
	s_ashr_i32 s8, s48, 12
	v_readlane_b32 s64, v249, 10
	s_cmp_eq_u32 s8, s17
	v_readlane_b32 s65, v249, 11
	v_readlane_b32 s72, v249, 18
	v_readlane_b32 s73, v249, 19
	v_readlane_b32 s76, v249, 22
	v_readlane_b32 s77, v249, 23
	v_readlane_b32 s78, v249, 24
	v_readlane_b32 s79, v249, 25
	v_readlane_b32 s66, v249, 12
	v_readlane_b32 s67, v249, 13
	v_readlane_b32 s68, v249, 14
	v_readlane_b32 s69, v249, 15
	v_readlane_b32 s70, v249, 16
	v_readlane_b32 s71, v249, 17
	v_readlane_b32 s74, v249, 20
	v_readlane_b32 s75, v249, 21
	s_cbranch_scc1 .LBB0_209
	s_mul_i32 s18, s8, 12
	s_ashr_i32 s19, s18, 31
	s_lshl_b64 s[18:19], s[18:19], 12
	v_lshl_add_u64 v[118:119], v[158:159], 0, s[18:19]
	v_add_co_u32_e32 v106, vcc, 0x1000, v118
	v_lshl_add_u64 v[108:109], v[118:119], 0, s[10:11]
	s_nop 0
	v_addc_co_u32_e32 v107, vcc, 0, v119, vcc
	global_load_dwordx4 v[122:125], v[106:107], off
	global_load_dwordx4 v[126:129], v[108:109], off offset:16
	global_load_dwordx4 v[130:133], v[106:107], off offset:2048
	v_lshl_add_u64 v[106:107], v[118:119], 0, s[12:13]
	global_load_dwordx4 v[134:137], v[106:107], off offset:16
	s_nop 0
	global_load_dwordx4 v[106:109], v[118:119], off offset:16
	global_load_dwordx4 v[110:113], v[118:119], off
	global_load_dwordx4 v[114:117], v[118:119], off offset:2064
	s_nop 0
	global_load_dwordx4 v[118:121], v[118:119], off offset:2048
	s_mov_b32 s17, s8
	s_waitcnt vmcnt(4)
	v_pk_add_f32 v[136:137], v[136:137], 1.0 op_sel_hi:[1,0]
	v_pk_add_f32 v[124:125], v[124:125], 1.0 op_sel_hi:[1,0]
	v_pk_add_f32 v[122:123], v[122:123], 1.0 op_sel_hi:[1,0]
	v_pk_add_f32 v[128:129], v[128:129], 1.0 op_sel_hi:[1,0]
	v_pk_add_f32 v[126:127], v[126:127], 1.0 op_sel_hi:[1,0]
	v_pk_add_f32 v[132:133], v[132:133], 1.0 op_sel_hi:[1,0]
	v_pk_add_f32 v[130:131], v[130:131], 1.0 op_sel_hi:[1,0]
	v_pk_add_f32 v[134:135], v[134:135], 1.0 op_sel_hi:[1,0]
	v_pk_mul_f32 v[124:125], v[8:9], v[124:125]
	v_pk_mul_f32 v[122:123], v[6:7], v[122:123]
	v_pk_mul_f32 v[128:129], v[4:5], v[128:129]
	v_pk_mul_f32 v[126:127], v[2:3], v[126:127]
	v_pk_mul_f32 v[132:133], v[16:17], v[132:133]
	v_pk_mul_f32 v[130:131], v[14:15], v[130:131]
	v_pk_mul_f32 v[136:137], v[12:13], v[136:137]
	v_pk_mul_f32 v[134:135], v[10:11], v[134:135]

.LBB0_215:
	v_pk_mul_f32 v[174:175], v[148:149], v[148:149]
	v_pk_mul_f32 v[176:177], v[146:147], v[146:147]
	s_ashr_i32 s49, s48, 31
	v_pk_mov_b32 v[178:179], v[176:177], v[174:175] op_sel:[1,0]
	v_mov_b32_e32 v177, v175
	v_pk_add_f32 v[174:175], v[178:179], v[176:177]
	v_pk_mul_f32 v[176:177], v[152:153], v[152:153]
	v_pk_add_f32 v[174:175], v[174:175], v[174:175] op_sel_hi:[0,1]
	v_pk_mul_f32 v[178:179], v[150:151], v[150:151]
	v_mul_f32_e32 v174, v138, v138
	v_pk_mov_b32 v[180:181], v[178:179], v[176:177] op_sel:[1,0]
	v_mov_b32_e32 v179, v177
	v_pk_add_f32 v[176:177], v[180:181], v[178:179]
	v_pk_fma_f32 v[178:179], v[138:139], v[138:139], v[174:175] op_sel_hi:[1,1,0]
	v_mul_f32_e32 v174, v140, v140
	v_pk_add_f32 v[176:177], v[176:177], v[176:177] op_sel_hi:[0,1]
	v_pk_fma_f32 v[180:181], v[140:141], v[140:141], v[174:175] op_sel_hi:[1,1,0]
	v_mul_f32_e32 v178, v142, v142
	v_mul_f32_e32 v180, v143, v143
	v_mul_f32_e32 v176, v144, v144
	v_mul_f32_e32 v174, v145, v145
	v_pk_add_f32 v[178:179], v[178:179], v[180:181]
	v_pk_add_f32 v[174:175], v[176:177], v[174:175]
	s_lshl_b64 s[18:19], s[48:49], 11
	v_pk_add_f32 v[174:175], v[178:179], v[174:175]
	s_lshl_b64 s[24:25], s[48:49], 12
	v_add_f32_e32 v173, v174, v175
	ds_bpermute_b32 v174, v1, v173
	s_add_u32 s8, s54, s24
	v_lshl_add_u64 v[178:179], v[162:163], 0, s[18:19]
	s_addc_u32 s19, s55, s25
	s_add_i32 s18, s14, 0x400
	s_waitcnt lgkmcnt(0)
	v_add_f32_e32 v173, v173, v174
	ds_bpermute_b32 v174, v155, v173
	s_and_b32 s18, s18, 0x400
	s_lshl_b32 s18, s18, 1
	s_add_u32 s18, s8, s18
	s_addc_u32 s19, s19, 0
	s_waitcnt lgkmcnt(0)
	v_add_f32_e32 v173, v173, v174
	ds_bpermute_b32 v174, v168, v173
	s_waitcnt lgkmcnt(0)
	v_add_f32_e32 v173, v173, v174
	ds_bpermute_b32 v174, v169, v173
	s_waitcnt lgkmcnt(0)
	v_add_f32_e32 v173, v173, v174
	ds_bpermute_b32 v174, v170, v173
	s_waitcnt lgkmcnt(0)
	v_add_f32_e32 v173, v173, v174
	ds_bpermute_b32 v174, v171, v173
	s_waitcnt lgkmcnt(0)
	v_add_f32_e32 v173, v173, v174
	v_fmamk_f32 v173, v173, 0x3a800000, v172
	v_mul_f32_e32 v174, 0x4b800000, v173
	v_cmp_gt_f32_e32 vcc, s15, v173
	s_nop 1
	v_cndmask_b32_e32 v173, v173, v174, vcc
	v_rsq_f32_e32 v173, v173
	s_nop 0
	v_mul_f32_e32 v174, 0x45800000, v173
	v_cndmask_b32_e32 v180, v173, v174, vcc
	v_pk_mul_f32 v[174:175], v[146:147], v[180:181] op_sel_hi:[1,0]
	v_pk_mul_f32 v[176:177], v[148:149], v[180:181] op_sel_hi:[1,0]
	v_pk_mul_f32 v[182:183], v[150:151], v[180:181] op_sel_hi:[1,0]
	v_pk_mul_f32 v[184:185], v[152:153], v[180:181] op_sel_hi:[1,0]
	s_waitcnt vmcnt(2)
	v_pk_fma_f32 v[176:177], v[124:125], v[176:177], v[112:113]
	v_pk_fma_f32 v[174:175], v[122:123], v[174:175], v[110:111]
	v_pk_fma_f32 v[184:185], v[128:129], v[184:185], v[108:109]
	v_pk_fma_f32 v[182:183], v[126:127], v[182:183], v[106:107]
	v_lshlrev_b32_e32 v173, 1, v154
	v_cvt_pk_bf16_f32 v174, v174, v175
	v_cvt_pk_bf16_f32 v175, v176, v177
	v_cvt_pk_bf16_f32 v176, v182, v183
	v_cvt_pk_bf16_f32 v177, v184, v185
	v_cvt_pk_bf16_f32 v146, v146, v147
	v_cvt_pk_bf16_f32 v147, v148, v149
	v_cvt_pk_bf16_f32 v148, v150, v151
	v_cvt_pk_bf16_f32 v149, v152, v153
	global_store_dwordx4 v[178:179], v[174:177], off sc1
	global_store_dwordx4 v173, v[146:149], s[18:19] nt
	v_pk_mul_f32 v[150:151], v[142:143], v[180:181] op_sel_hi:[1,0]
	v_pk_mul_f32 v[152:153], v[144:145], v[180:181] op_sel_hi:[1,0]
	v_pk_mul_f32 v[146:147], v[138:139], v[180:181] op_sel_hi:[1,0]
	v_pk_mul_f32 v[148:149], v[140:141], v[180:181] op_sel_hi:[1,0]
	s_waitcnt vmcnt(2)
	v_pk_fma_f32 v[146:147], v[130:131], v[146:147], v[118:119]
	v_pk_fma_f32 v[148:149], v[132:133], v[148:149], v[120:121]
	v_pk_fma_f32 v[152:153], v[136:137], v[152:153], v[116:117]
	v_pk_fma_f32 v[150:151], v[134:135], v[150:151], v[114:115]
	v_cvt_pk_bf16_f32 v146, v146, v147
	v_cvt_pk_bf16_f32 v147, v148, v149
	v_cvt_pk_bf16_f32 v148, v150, v151
	v_cvt_pk_bf16_f32 v149, v152, v153
	v_cvt_pk_bf16_f32 v138, v138, v139
	v_cvt_pk_bf16_f32 v139, v140, v141
	v_cvt_pk_bf16_f32 v140, v142, v143
	v_cvt_pk_bf16_f32 v141, v144, v145
	global_store_dwordx4 v[178:179], v[146:149], off offset:1024 sc1
	global_store_dwordx4 v173, v[138:141], s[18:19] offset:1024 nt
	s_and_b64 vcc, exec, s[4:5]
	s_cbranch_vccnz .LBB0_188

.LBB0_224:
	v_pk_mul_f32 v[174:175], v[148:149], v[148:149]
	v_pk_mul_f32 v[176:177], v[146:147], v[146:147]
	s_ashr_i32 s45, s44, 31
	v_pk_mov_b32 v[178:179], v[176:177], v[174:175] op_sel:[1,0]
	v_mov_b32_e32 v177, v175
	v_pk_add_f32 v[174:175], v[178:179], v[176:177]
	v_pk_mul_f32 v[176:177], v[152:153], v[152:153]
	v_pk_add_f32 v[174:175], v[174:175], v[174:175] op_sel_hi:[0,1]
	v_pk_mul_f32 v[178:179], v[150:151], v[150:151]
	v_mul_f32_e32 v174, v138, v138
	v_pk_mov_b32 v[180:181], v[178:179], v[176:177] op_sel:[1,0]
	v_mov_b32_e32 v179, v177
	v_pk_add_f32 v[176:177], v[180:181], v[178:179]
	v_pk_fma_f32 v[178:179], v[138:139], v[138:139], v[174:175] op_sel_hi:[1,1,0]
	v_mul_f32_e32 v174, v140, v140
	v_pk_add_f32 v[176:177], v[176:177], v[176:177] op_sel_hi:[0,1]
	v_pk_fma_f32 v[180:181], v[140:141], v[140:141], v[174:175] op_sel_hi:[1,1,0]
	v_mul_f32_e32 v178, v142, v142
	v_mul_f32_e32 v180, v143, v143
	v_mul_f32_e32 v176, v144, v144
	v_mul_f32_e32 v174, v145, v145
	v_pk_add_f32 v[178:179], v[178:179], v[180:181]
	v_pk_add_f32 v[174:175], v[176:177], v[174:175]
	s_and_b32 s8, s14, 0x400
	v_pk_add_f32 v[174:175], v[178:179], v[174:175]
	s_lshl_b64 s[18:19], s[44:45], 11
	v_add_f32_e32 v173, v174, v175
	ds_bpermute_b32 v174, v1, v173
	s_lshl_b64 s[24:25], s[44:45], 12
	v_lshl_add_u64 v[178:179], v[162:163], 0, s[18:19]
	s_add_u32 s18, s54, s24
	s_addc_u32 s19, s55, s25
	s_waitcnt lgkmcnt(0)
	v_add_f32_e32 v173, v173, v174
	ds_bpermute_b32 v174, v155, v173
	s_lshl_b32 s8, s8, 1
	s_add_u32 s18, s18, s8
	s_addc_u32 s19, s19, 0
	s_waitcnt lgkmcnt(0)
	v_add_f32_e32 v173, v173, v174
	ds_bpermute_b32 v174, v168, v173
	s_waitcnt lgkmcnt(0)
	v_add_f32_e32 v173, v173, v174
	ds_bpermute_b32 v174, v169, v173
	s_waitcnt lgkmcnt(0)
	v_add_f32_e32 v173, v173, v174
	ds_bpermute_b32 v174, v170, v173
	s_waitcnt lgkmcnt(0)
	v_add_f32_e32 v173, v173, v174
	ds_bpermute_b32 v174, v171, v173
	s_waitcnt lgkmcnt(0)
	v_add_f32_e32 v173, v173, v174
	v_fmamk_f32 v173, v173, 0x3a800000, v172
	v_mul_f32_e32 v174, 0x4b800000, v173
	v_cmp_gt_f32_e32 vcc, s15, v173
	s_nop 1
	v_cndmask_b32_e32 v173, v173, v174, vcc
	v_rsq_f32_e32 v173, v173
	s_nop 0
	v_mul_f32_e32 v174, 0x45800000, v173
	v_cndmask_b32_e32 v180, v173, v174, vcc
	v_pk_mul_f32 v[174:175], v[146:147], v[180:181] op_sel_hi:[1,0]
	v_pk_mul_f32 v[176:177], v[148:149], v[180:181] op_sel_hi:[1,0]
	v_pk_mul_f32 v[182:183], v[150:151], v[180:181] op_sel_hi:[1,0]
	v_pk_mul_f32 v[184:185], v[152:153], v[180:181] op_sel_hi:[1,0]
	s_waitcnt vmcnt(2)
	v_pk_fma_f32 v[176:177], v[124:125], v[176:177], v[112:113]
	v_pk_fma_f32 v[174:175], v[122:123], v[174:175], v[110:111]
	v_pk_fma_f32 v[184:185], v[128:129], v[184:185], v[108:109]
	v_pk_fma_f32 v[182:183], v[126:127], v[182:183], v[106:107]
	v_lshlrev_b32_e32 v173, 1, v154
	v_cvt_pk_bf16_f32 v174, v174, v175
	v_cvt_pk_bf16_f32 v175, v176, v177
	v_cvt_pk_bf16_f32 v176, v182, v183
	v_cvt_pk_bf16_f32 v177, v184, v185
	v_cvt_pk_bf16_f32 v146, v146, v147
	v_cvt_pk_bf16_f32 v147, v148, v149
	v_cvt_pk_bf16_f32 v148, v150, v151
	v_cvt_pk_bf16_f32 v149, v152, v153
	global_store_dwordx4 v[178:179], v[174:177], off sc1
	global_store_dwordx4 v173, v[146:149], s[18:19] nt
	v_pk_mul_f32 v[150:151], v[142:143], v[180:181] op_sel_hi:[1,0]
	v_pk_mul_f32 v[152:153], v[144:145], v[180:181] op_sel_hi:[1,0]
	v_pk_mul_f32 v[146:147], v[138:139], v[180:181] op_sel_hi:[1,0]
	v_pk_mul_f32 v[148:149], v[140:141], v[180:181] op_sel_hi:[1,0]
	s_waitcnt vmcnt(2)
	v_pk_fma_f32 v[146:147], v[130:131], v[146:147], v[118:119]
	v_pk_fma_f32 v[148:149], v[132:133], v[148:149], v[120:121]
	v_pk_fma_f32 v[152:153], v[136:137], v[152:153], v[116:117]
	v_pk_fma_f32 v[150:151], v[134:135], v[150:151], v[114:115]
	v_cvt_pk_bf16_f32 v146, v146, v147
	v_cvt_pk_bf16_f32 v147, v148, v149
	v_cvt_pk_bf16_f32 v148, v150, v151
	v_cvt_pk_bf16_f32 v149, v152, v153
	v_cvt_pk_bf16_f32 v138, v138, v139
	v_cvt_pk_bf16_f32 v139, v140, v141
	v_cvt_pk_bf16_f32 v140, v142, v143
	v_cvt_pk_bf16_f32 v141, v144, v145
	global_store_dwordx4 v[178:179], v[146:149], off offset:1024 sc1
	global_store_dwordx4 v173, v[138:141], s[18:19] offset:1024 nt

.LBB0_610:
	s_or_b64 exec, exec, s[6:7]
	v_mul_f32_e32 v114, v109, v109
	v_mul_f32_e32 v128, v113, v113
	v_fmac_f32_e32 v114, v108, v108
	v_fmac_f32_e32 v128, v112, v112
	v_add_f32_e32 v114, v114, v128
	v_mul_f32_e32 v128, v111, v111
	v_mul_f32_e32 v129, v107, v107
	v_fmac_f32_e32 v128, v110, v110
	v_fmac_f32_e32 v129, v106, v106
	v_add_f32_e32 v128, v128, v129
	v_mov_b32_e32 v138, v135
	v_mov_b32_e32 v139, v131
	v_add_f32_e32 v114, v128, v114
	v_mov_b32_e32 v128, v134
	v_mov_b32_e32 v129, v130
	v_pk_mul_f32 v[138:139], v[138:139], v[138:139]
	v_mov_b32_e32 v146, v133
	v_mov_b32_e32 v147, v137
	v_pk_fma_f32 v[128:129], v[128:129], v[128:129], v[138:139]
	v_mov_b32_e32 v138, v132
	v_mov_b32_e32 v139, v136
	v_pk_mul_f32 v[146:147], v[146:147], v[146:147]
	s_lshl_b64 s[4:5], s[42:43], 11
	v_pk_fma_f32 v[138:139], v[138:139], v[138:139], v[146:147]
	s_nop 0
	v_pk_add_f32 v[128:129], v[128:129], v[138:139]
	s_nop 0
	v_add_f32_e32 v114, v114, v129
	v_add_f32_e32 v114, v128, v114
	ds_bpermute_b32 v128, v117, v114
	s_waitcnt lgkmcnt(0)
	v_add_f32_e32 v114, v114, v128
	ds_bpermute_b32 v128, v140, v114
	s_waitcnt lgkmcnt(0)
	v_add_f32_e32 v114, v114, v128
	ds_bpermute_b32 v128, v141, v114
	s_waitcnt lgkmcnt(0)
	v_add_f32_e32 v114, v114, v128
	ds_bpermute_b32 v128, v142, v114
	s_waitcnt lgkmcnt(0)
	v_add_f32_e32 v114, v114, v128
	ds_bpermute_b32 v128, v143, v114
	s_waitcnt lgkmcnt(0)
	v_add_f32_e32 v114, v114, v128
	ds_bpermute_b32 v128, v144, v114
	s_waitcnt lgkmcnt(0)
	v_add_f32_e32 v114, v114, v128
	v_fmamk_f32 v114, v114, 0x3a800000, v145
	v_mul_f32_e32 v128, 0x4b800000, v114
	v_cmp_gt_f32_e32 vcc, s72, v114
	s_nop 1
	v_cndmask_b32_e32 v114, v114, v128, vcc
	v_rsq_f32_e32 v114, v114
	v_lshl_add_u64 v[128:129], v[122:123], 0, s[4:5]
	v_mul_f32_e32 v138, 0x45800000, v114
	v_cndmask_b32_e32 v114, v114, v138, vcc
	v_pk_mul_f32 v[108:109], v[114:115], v[108:109] op_sel_hi:[0,1]
	v_pk_mul_f32 v[112:113], v[114:115], v[112:113] op_sel_hi:[0,1]
	v_pk_mul_f32 v[110:111], v[114:115], v[110:111] op_sel_hi:[0,1]
	v_pk_mul_f32 v[106:107], v[114:115], v[106:107] op_sel_hi:[0,1]
	s_waitcnt vmcnt(2)
	v_pk_fma_f32 v[112:113], v[92:93], v[112:113], v[80:81]
	v_pk_fma_f32 v[108:109], v[90:91], v[108:109], v[78:79]
	v_pk_fma_f32 v[138:139], v[96:97], v[106:107], v[76:77]
	v_pk_fma_f32 v[110:111], v[94:95], v[110:111], v[74:75]
	v_cvt_pk_bf16_f32 v106, v108, v109
	v_cvt_pk_bf16_f32 v107, v112, v113
	v_cvt_pk_bf16_f32 v108, v110, v111
	v_cvt_pk_bf16_f32 v109, v138, v139
	global_store_dwordx4 v[128:129], v[106:109], off sc1
	v_pk_mul_f32 v[110:111], v[114:115], v[134:135] op_sel_hi:[0,1]
	v_pk_mul_f32 v[112:113], v[114:115], v[132:133] op_sel_hi:[0,1]
	v_pk_mul_f32 v[106:107], v[114:115], v[130:131] op_sel_hi:[0,1]
	v_pk_mul_f32 v[108:109], v[114:115], v[136:137] op_sel_hi:[0,1]
	s_waitcnt vmcnt(1)
	v_pk_fma_f32 v[108:109], v[100:101], v[108:109], v[88:89]
	v_pk_fma_f32 v[106:107], v[98:99], v[106:107], v[86:87]
	v_pk_fma_f32 v[112:113], v[104:105], v[112:113], v[84:85]
	v_pk_fma_f32 v[110:111], v[102:103], v[110:111], v[82:83]
	v_cvt_pk_bf16_f32 v106, v106, v107
	v_cvt_pk_bf16_f32 v107, v108, v109
	v_cvt_pk_bf16_f32 v108, v110, v111
	v_cvt_pk_bf16_f32 v109, v112, v113
	global_store_dwordx4 v[128:129], v[106:109], off offset:1024 sc1

.LBB0_626:
	s_or_b64 exec, exec, s[14:15]
	s_waitcnt vmcnt(1)
	v_lshlrev_b32_e32 v130, 16, v110
	v_and_b32_e32 v131, 0xffff0000, v110
	v_lshlrev_b32_e32 v134, 16, v111
	v_and_b32_e32 v135, 0xffff0000, v111
	v_lshlrev_b32_e32 v132, 16, v112
	v_and_b32_e32 v133, 0xffff0000, v112
	v_lshlrev_b32_e32 v110, 16, v113
	v_and_b32_e32 v111, 0xffff0000, v113
	s_and_saveexec_b64 s[70:71], s[6:7]
	s_cbranch_execz .LBB0_628
	v_cvt_f32_f16_sdwa v113, v54 dst_sel:DWORD dst_unused:UNUSED_PAD src0_sel:WORD_1
	v_cvt_f32_f16_e32 v112, v54
	v_cvt_f32_f16_sdwa v137, v62 dst_sel:DWORD dst_unused:UNUSED_PAD src0_sel:WORD_1
	v_cvt_f32_f16_e32 v136, v62
	s_waitcnt vmcnt(0)
	v_cvt_f32_f16_sdwa v139, v70 dst_sel:DWORD dst_unused:UNUSED_PAD src0_sel:WORD_1
	v_cvt_f32_f16_e32 v138, v70
	v_cvt_f32_f16_sdwa v147, v55 dst_sel:DWORD dst_unused:UNUSED_PAD src0_sel:WORD_1
	v_cvt_f32_f16_e32 v146, v55
	v_pk_add_f32 v[112:113], v[130:131], v[112:113]
	s_nop 0
	v_pk_add_f32 v[112:113], v[112:113], v[136:137]
	v_cvt_f32_f16_sdwa v137, v71 dst_sel:DWORD dst_unused:UNUSED_PAD src0_sel:WORD_1
	v_pk_add_f32 v[130:131], v[112:113], v[138:139]
	v_pk_add_f32 v[112:113], v[134:135], v[146:147]
	v_cvt_f32_f16_sdwa v135, v63 dst_sel:DWORD dst_unused:UNUSED_PAD src0_sel:WORD_1
	v_cvt_f32_f16_e32 v134, v63
	v_cvt_f32_f16_e32 v136, v71
	v_cvt_f32_f16_sdwa v139, v56 dst_sel:DWORD dst_unused:UNUSED_PAD src0_sel:WORD_1
	v_cvt_f32_f16_e32 v138, v56
	v_cvt_f32_f16_sdwa v147, v64 dst_sel:DWORD dst_unused:UNUSED_PAD src0_sel:WORD_1
	v_cvt_f32_f16_e32 v146, v64
	v_pk_add_f32 v[112:113], v[112:113], v[134:135]
	s_nop 0
	v_pk_add_f32 v[134:135], v[112:113], v[136:137]
	v_cvt_f32_f16_sdwa v137, v57 dst_sel:DWORD dst_unused:UNUSED_PAD src0_sel:WORD_1
	v_cvt_f32_f16_e32 v136, v57
	v_pk_add_f32 v[112:113], v[132:133], v[138:139]
	v_cvt_f32_f16_sdwa v139, v65 dst_sel:DWORD dst_unused:UNUSED_PAD src0_sel:WORD_1
	v_cvt_f32_f16_e32 v138, v65
	v_pk_add_f32 v[112:113], v[112:113], v[146:147]
	v_cvt_f32_f16_sdwa v133, v72 dst_sel:DWORD dst_unused:UNUSED_PAD src0_sel:WORD_1
	v_cvt_f32_f16_e32 v132, v72
	v_cvt_f32_f16_sdwa v147, v73 dst_sel:DWORD dst_unused:UNUSED_PAD src0_sel:WORD_1
	v_cvt_f32_f16_e32 v146, v73
	v_pk_add_f32 v[110:111], v[110:111], v[136:137]
	v_pk_add_f32 v[132:133], v[112:113], v[132:133]
	v_pk_add_f32 v[110:111], v[110:111], v[138:139]
	v_cvt_pk_bf16_f32 v136, v130, v131
	v_pk_add_f32 v[110:111], v[110:111], v[146:147]
	v_cvt_pk_bf16_f32 v137, v134, v135
	v_cvt_pk_bf16_f32 v138, v132, v133
	v_cvt_pk_bf16_f32 v139, v110, v111
	global_store_dwordx4 v[128:129], v[136:139], off offset:-1024 sc1
.LBB0_628:
	s_or_b64 exec, exec, s[70:71]
	s_waitcnt vmcnt(0)
	v_lshlrev_b32_e32 v112, 16, v106
	v_and_b32_e32 v113, 0xffff0000, v106
	v_lshlrev_b32_e32 v138, 16, v107
	v_and_b32_e32 v139, 0xffff0000, v107
	v_lshlrev_b32_e32 v136, 16, v108
	v_and_b32_e32 v137, 0xffff0000, v108
	v_lshlrev_b32_e32 v106, 16, v109
	v_and_b32_e32 v107, 0xffff0000, v109
	s_and_saveexec_b64 s[6:7], s[4:5]
	s_cbranch_execz .LBB0_630
	v_cvt_f32_f16_sdwa v109, v50 dst_sel:DWORD dst_unused:UNUSED_PAD src0_sel:WORD_1
	v_cvt_f32_f16_e32 v108, v50
	v_cvt_f32_f16_sdwa v147, v58 dst_sel:DWORD dst_unused:UNUSED_PAD src0_sel:WORD_1
	v_cvt_f32_f16_e32 v146, v58
	v_cvt_f32_f16_sdwa v149, v66 dst_sel:DWORD dst_unused:UNUSED_PAD src0_sel:WORD_1
	v_cvt_f32_f16_e32 v148, v66
	v_cvt_f32_f16_sdwa v151, v51 dst_sel:DWORD dst_unused:UNUSED_PAD src0_sel:WORD_1
	v_cvt_f32_f16_e32 v150, v51
	v_pk_add_f32 v[108:109], v[112:113], v[108:109]
	s_nop 0
	v_pk_add_f32 v[108:109], v[108:109], v[146:147]
	v_cvt_f32_f16_sdwa v147, v67 dst_sel:DWORD dst_unused:UNUSED_PAD src0_sel:WORD_1
	v_pk_add_f32 v[112:113], v[108:109], v[148:149]
	v_pk_add_f32 v[108:109], v[138:139], v[150:151]
	v_cvt_f32_f16_sdwa v139, v59 dst_sel:DWORD dst_unused:UNUSED_PAD src0_sel:WORD_1
	v_cvt_f32_f16_e32 v138, v59
	v_cvt_f32_f16_e32 v146, v67
	v_cvt_f32_f16_sdwa v149, v52 dst_sel:DWORD dst_unused:UNUSED_PAD src0_sel:WORD_1
	v_cvt_f32_f16_e32 v148, v52
	v_cvt_f32_f16_sdwa v151, v60 dst_sel:DWORD dst_unused:UNUSED_PAD src0_sel:WORD_1
	v_cvt_f32_f16_e32 v150, v60
	v_pk_add_f32 v[108:109], v[108:109], v[138:139]
	s_nop 0
	v_pk_add_f32 v[138:139], v[108:109], v[146:147]
	v_cvt_f32_f16_sdwa v147, v53 dst_sel:DWORD dst_unused:UNUSED_PAD src0_sel:WORD_1
	v_cvt_f32_f16_e32 v146, v53
	v_pk_add_f32 v[108:109], v[136:137], v[148:149]
	v_cvt_f32_f16_sdwa v149, v61 dst_sel:DWORD dst_unused:UNUSED_PAD src0_sel:WORD_1
	v_cvt_f32_f16_e32 v148, v61
	v_pk_add_f32 v[108:109], v[108:109], v[150:151]
	v_cvt_f32_f16_sdwa v137, v68 dst_sel:DWORD dst_unused:UNUSED_PAD src0_sel:WORD_1
	v_cvt_f32_f16_e32 v136, v68
	v_cvt_f32_f16_sdwa v151, v69 dst_sel:DWORD dst_unused:UNUSED_PAD src0_sel:WORD_1
	v_cvt_f32_f16_e32 v150, v69
	v_pk_add_f32 v[106:107], v[106:107], v[146:147]
	v_pk_add_f32 v[136:137], v[108:109], v[136:137]
	v_pk_add_f32 v[106:107], v[106:107], v[148:149]
	v_cvt_pk_bf16_f32 v146, v112, v113
	v_pk_add_f32 v[106:107], v[106:107], v[150:151]
	v_cvt_pk_bf16_f32 v147, v138, v139
	v_cvt_pk_bf16_f32 v148, v136, v137
	v_cvt_pk_bf16_f32 v149, v106, v107
	global_store_dwordx4 v[128:129], v[146:149], off sc1
.LBB0_630:
	s_or_b64 exec, exec, s[6:7]
	v_mul_f32_e32 v108, v131, v131
	v_mul_f32_e32 v109, v135, v135
	v_fmac_f32_e32 v108, v130, v130
	v_fmac_f32_e32 v109, v134, v134
	v_add_f32_e32 v108, v108, v109
	v_mul_f32_e32 v109, v133, v133
	v_mul_f32_e32 v114, v111, v111
	v_fmac_f32_e32 v109, v132, v132
	v_fmac_f32_e32 v114, v110, v110
	v_add_f32_e32 v109, v109, v114
	v_mov_b32_e32 v128, v137
	v_mov_b32_e32 v129, v113
	v_add_f32_e32 v114, v109, v108
	v_mov_b32_e32 v108, v136
	v_mov_b32_e32 v109, v112
	v_pk_mul_f32 v[128:129], v[128:129], v[128:129]
	v_mov_b32_e32 v146, v107
	v_mov_b32_e32 v147, v139
	v_pk_fma_f32 v[108:109], v[108:109], v[108:109], v[128:129]
	v_mov_b32_e32 v128, v106
	v_mov_b32_e32 v129, v138
	v_pk_mul_f32 v[146:147], v[146:147], v[146:147]
	s_nop 0
	v_pk_fma_f32 v[128:129], v[128:129], v[128:129], v[146:147]
	s_nop 0
	v_pk_add_f32 v[108:109], v[108:109], v[128:129]
	s_nop 0
	v_add_f32_e32 v109, v114, v109
	v_add_f32_e32 v108, v108, v109
	ds_bpermute_b32 v109, v117, v108
	s_waitcnt lgkmcnt(0)
	v_add_f32_e32 v108, v108, v109
	ds_bpermute_b32 v109, v140, v108
	s_waitcnt lgkmcnt(0)
	v_add_f32_e32 v108, v108, v109
	ds_bpermute_b32 v109, v141, v108
	s_waitcnt lgkmcnt(0)
	v_add_f32_e32 v108, v108, v109
	ds_bpermute_b32 v109, v142, v108
	s_waitcnt lgkmcnt(0)
	v_add_f32_e32 v108, v108, v109
	ds_bpermute_b32 v109, v143, v108
	s_waitcnt lgkmcnt(0)
	v_add_f32_e32 v108, v108, v109
	ds_bpermute_b32 v109, v144, v108
	s_waitcnt lgkmcnt(0)
	v_add_f32_e32 v108, v108, v109
	v_fmamk_f32 v108, v108, 0x3a800000, v145
	v_mul_f32_e32 v109, 0x4b800000, v108
	v_cmp_gt_f32_e32 vcc, s72, v108
	s_nop 1
	v_cndmask_b32_e32 v108, v108, v109, vcc
	v_rsq_f32_e32 v108, v108
	s_nop 0
	v_mul_f32_e32 v109, 0x45800000, v108
	v_cndmask_b32_e32 v114, v108, v109, vcc
	v_pk_mul_f32 v[108:109], v[114:115], v[130:131] op_sel_hi:[0,1]
	v_pk_mul_f32 v[128:129], v[114:115], v[134:135] op_sel_hi:[0,1]
	v_pk_mul_f32 v[130:131], v[114:115], v[132:133] op_sel_hi:[0,1]
	v_pk_mul_f32 v[110:111], v[114:115], v[110:111] op_sel_hi:[0,1]
	v_pk_fma_f32 v[128:129], v[92:93], v[128:129], v[80:81]
	v_pk_fma_f32 v[108:109], v[90:91], v[108:109], v[78:79]
	v_pk_fma_f32 v[132:133], v[96:97], v[110:111], v[76:77]
	v_pk_fma_f32 v[110:111], v[94:95], v[130:131], v[74:75]
	v_cvt_pk_bf16_f32 v108, v108, v109
	v_cvt_pk_bf16_f32 v109, v128, v129
	v_cvt_pk_bf16_f32 v110, v110, v111
	v_cvt_pk_bf16_f32 v111, v132, v133
	global_store_dwordx4 v[124:125], v[108:111], off sc1
	v_pk_mul_f32 v[106:107], v[114:115], v[106:107] op_sel_hi:[0,1]
	v_pk_fma_f32 v[128:129], v[104:105], v[106:107], v[84:85]
	v_pk_mul_f32 v[110:111], v[114:115], v[138:139] op_sel_hi:[0,1]
	v_pk_mul_f32 v[108:109], v[114:115], v[112:113] op_sel_hi:[0,1]
	v_pk_fma_f32 v[110:111], v[100:101], v[110:111], v[88:89]
	v_pk_mul_f32 v[112:113], v[114:115], v[136:137] op_sel_hi:[0,1]
	v_pk_fma_f32 v[108:109], v[98:99], v[108:109], v[86:87]
	v_pk_fma_f32 v[112:113], v[102:103], v[112:113], v[82:83]
	v_cvt_pk_bf16_f32 v107, v110, v111
	v_cndmask_b32_e64 v110, 0, 1, s[8:9]
	v_cvt_pk_bf16_f32 v106, v108, v109
	v_cvt_pk_bf16_f32 v108, v112, v113
	v_cvt_pk_bf16_f32 v109, v128, v129
	v_cmp_ne_u32_e64 s[4:5], 1, v110
	s_andn2_b64 vcc, exec, s[8:9]
	global_store_dwordx4 v[124:125], v[106:109], off offset:1024 sc1
	s_cbranch_vccnz .LBB0_642
	s_ashr_i32 s2, s68, 12
	s_cmp_eq_u32 s2, s73
	s_cbranch_scc1 .LBB0_633
	s_mul_i32 s6, s2, 12
	s_ashr_i32 s7, s6, 31
	s_lshl_b64 s[6:7], s[6:7], 12
	v_lshl_add_u64 v[86:87], v[118:119], 0, s[6:7]
	v_add_co_u32_e32 v74, vcc, 0x1000, v86
	v_lshl_add_u64 v[76:77], v[86:87], 0, s[22:23]
	s_nop 0
	v_addc_co_u32_e32 v75, vcc, 0, v87, vcc
	global_load_dwordx4 v[90:93], v[74:75], off
	global_load_dwordx4 v[94:97], v[76:77], off offset:16
	global_load_dwordx4 v[98:101], v[74:75], off offset:2048
	v_lshl_add_u64 v[74:75], v[86:87], 0, s[26:27]
	global_load_dwordx4 v[102:105], v[74:75], off offset:16
	s_nop 0
	global_load_dwordx4 v[74:77], v[86:87], off offset:16
	global_load_dwordx4 v[78:81], v[86:87], off
	global_load_dwordx4 v[82:85], v[86:87], off offset:2064
	s_nop 0
	global_load_dwordx4 v[86:89], v[86:87], off offset:2048
	s_mov_b32 s73, s2
	s_waitcnt vmcnt(4)
	v_pk_add_f32 v[104:105], v[104:105], 1.0 op_sel_hi:[1,0]
	v_pk_add_f32 v[92:93], v[92:93], 1.0 op_sel_hi:[1,0]
	v_pk_add_f32 v[90:91], v[90:91], 1.0 op_sel_hi:[1,0]
	v_pk_add_f32 v[96:97], v[96:97], 1.0 op_sel_hi:[1,0]
	v_pk_add_f32 v[94:95], v[94:95], 1.0 op_sel_hi:[1,0]
	v_pk_add_f32 v[100:101], v[100:101], 1.0 op_sel_hi:[1,0]
	v_pk_add_f32 v[98:99], v[98:99], 1.0 op_sel_hi:[1,0]
	v_pk_add_f32 v[102:103], v[102:103], 1.0 op_sel_hi:[1,0]
	v_pk_mul_f32 v[92:93], v[8:9], v[92:93]
	v_pk_mul_f32 v[90:91], v[6:7], v[90:91]
	v_pk_mul_f32 v[96:97], v[4:5], v[96:97]
	v_pk_mul_f32 v[94:95], v[2:3], v[94:95]
	v_pk_mul_f32 v[100:101], v[16:17], v[100:101]
	v_pk_mul_f32 v[98:99], v[14:15], v[98:99]
	v_pk_mul_f32 v[104:105], v[12:13], v[104:105]
	v_pk_mul_f32 v[102:103], v[10:11], v[102:103]

.LBB0_637:
	s_or_b64 exec, exec, s[14:15]
	s_ashr_i32 s69, s68, 31
	s_lshl_b64 s[14:15], s[68:69], 12
	s_add_u32 s2, s54, s14
	s_addc_u32 s15, s55, s15
	s_add_i32 s14, s62, 0x400
	s_and_b32 s14, s14, 0x400
	s_lshl_b32 s14, s14, 1
	s_add_u32 s14, s2, s14
	s_addc_u32 s15, s15, 0
	v_lshlrev_b32_e32 v114, 1, v116
	v_lshl_add_u64 v[128:129], s[14:15], 0, v[114:115]
	v_lshlrev_b32_e32 v108, 16, v46
	v_and_b32_e32 v109, 0xffff0000, v46
	v_lshlrev_b32_e32 v112, 16, v47
	v_and_b32_e32 v113, 0xffff0000, v47
	v_lshlrev_b32_e32 v110, 16, v48
	v_and_b32_e32 v111, 0xffff0000, v48
	v_lshlrev_b32_e32 v106, 16, v49
	v_and_b32_e32 v107, 0xffff0000, v49
	s_and_saveexec_b64 s[70:71], s[8:9]
	s_cbranch_execz .LBB0_639
	s_waitcnt vmcnt(2)
	v_cvt_f32_f16_sdwa v131, v54 dst_sel:DWORD dst_unused:UNUSED_PAD src0_sel:WORD_1
	v_cvt_f32_f16_e32 v130, v54
	s_waitcnt vmcnt(1)
	v_cvt_f32_f16_sdwa v133, v62 dst_sel:DWORD dst_unused:UNUSED_PAD src0_sel:WORD_1
	v_cvt_f32_f16_e32 v132, v62
	s_waitcnt vmcnt(0)
	v_cvt_f32_f16_sdwa v135, v70 dst_sel:DWORD dst_unused:UNUSED_PAD src0_sel:WORD_1
	v_cvt_f32_f16_e32 v134, v70
	v_cvt_f32_f16_sdwa v137, v55 dst_sel:DWORD dst_unused:UNUSED_PAD src0_sel:WORD_1
	v_cvt_f32_f16_e32 v136, v55
	v_pk_add_f32 v[108:109], v[108:109], v[130:131]
	v_cvt_f32_f16_sdwa v131, v63 dst_sel:DWORD dst_unused:UNUSED_PAD src0_sel:WORD_1
	v_cvt_f32_f16_e32 v130, v63
	v_pk_add_f32 v[108:109], v[108:109], v[132:133]
	v_cvt_f32_f16_sdwa v133, v71 dst_sel:DWORD dst_unused:UNUSED_PAD src0_sel:WORD_1
	v_cvt_f32_f16_e32 v132, v71
	v_pk_add_f32 v[108:109], v[108:109], v[134:135]
	v_cvt_f32_f16_sdwa v135, v56 dst_sel:DWORD dst_unused:UNUSED_PAD src0_sel:WORD_1
	v_cvt_f32_f16_e32 v134, v56
	v_pk_add_f32 v[112:113], v[112:113], v[136:137]
	v_cvt_f32_f16_sdwa v137, v64 dst_sel:DWORD dst_unused:UNUSED_PAD src0_sel:WORD_1
	v_cvt_f32_f16_e32 v136, v64
	v_pk_add_f32 v[112:113], v[112:113], v[130:131]
	v_pk_add_f32 v[110:111], v[110:111], v[134:135]
	v_pk_add_f32 v[112:113], v[112:113], v[132:133]
	v_cvt_f32_f16_sdwa v133, v57 dst_sel:DWORD dst_unused:UNUSED_PAD src0_sel:WORD_1
	v_cvt_f32_f16_e32 v132, v57
	v_cvt_f32_f16_sdwa v135, v65 dst_sel:DWORD dst_unused:UNUSED_PAD src0_sel:WORD_1
	v_cvt_f32_f16_e32 v134, v65
	v_pk_add_f32 v[110:111], v[110:111], v[136:137]
	v_cvt_f32_f16_sdwa v131, v72 dst_sel:DWORD dst_unused:UNUSED_PAD src0_sel:WORD_1
	v_cvt_f32_f16_e32 v130, v72
	v_cvt_f32_f16_sdwa v137, v73 dst_sel:DWORD dst_unused:UNUSED_PAD src0_sel:WORD_1
	v_cvt_f32_f16_e32 v136, v73
	v_pk_add_f32 v[106:107], v[106:107], v[132:133]
	v_pk_add_f32 v[110:111], v[110:111], v[130:131]
	v_pk_add_f32 v[106:107], v[106:107], v[134:135]
	v_cvt_pk_bf16_f32 v130, v108, v109
	v_pk_add_f32 v[106:107], v[106:107], v[136:137]
	v_cvt_pk_bf16_f32 v131, v112, v113
	v_cvt_pk_bf16_f32 v132, v110, v111
	v_cvt_pk_bf16_f32 v133, v106, v107
	global_store_dwordx4 v[128:129], v[130:133], off sc1
.LBB0_639:
	s_or_b64 exec, exec, s[70:71]
	s_nop 0
	v_lshlrev_b32_e32 v130, 16, v42
	v_and_b32_e32 v131, 0xffff0000, v42
	v_lshlrev_b32_e32 v136, 16, v43
	v_and_b32_e32 v137, 0xffff0000, v43
	v_lshlrev_b32_e32 v134, 16, v44
	v_and_b32_e32 v135, 0xffff0000, v44
	v_lshlrev_b32_e32 v132, 16, v45
	v_and_b32_e32 v133, 0xffff0000, v45
	s_and_saveexec_b64 s[8:9], s[6:7]
	s_cbranch_execz .LBB0_641
	s_waitcnt vmcnt(2)
	v_cvt_f32_f16_sdwa v139, v50 dst_sel:DWORD dst_unused:UNUSED_PAD src0_sel:WORD_1
	v_cvt_f32_f16_e32 v138, v50
	s_waitcnt vmcnt(1)
	v_cvt_f32_f16_sdwa v147, v58 dst_sel:DWORD dst_unused:UNUSED_PAD src0_sel:WORD_1
	v_cvt_f32_f16_e32 v146, v58
	s_waitcnt vmcnt(0)
	v_cvt_f32_f16_sdwa v149, v66 dst_sel:DWORD dst_unused:UNUSED_PAD src0_sel:WORD_1
	v_cvt_f32_f16_e32 v148, v66
	v_cvt_f32_f16_sdwa v151, v51 dst_sel:DWORD dst_unused:UNUSED_PAD src0_sel:WORD_1
	v_cvt_f32_f16_e32 v150, v51
	v_pk_add_f32 v[130:131], v[130:131], v[138:139]
	v_cvt_f32_f16_sdwa v139, v59 dst_sel:DWORD dst_unused:UNUSED_PAD src0_sel:WORD_1
	v_cvt_f32_f16_e32 v138, v59
	v_pk_add_f32 v[130:131], v[130:131], v[146:147]
	v_cvt_f32_f16_sdwa v147, v67 dst_sel:DWORD dst_unused:UNUSED_PAD src0_sel:WORD_1
	v_cvt_f32_f16_e32 v146, v67
	v_pk_add_f32 v[130:131], v[130:131], v[148:149]
	v_cvt_f32_f16_sdwa v149, v52 dst_sel:DWORD dst_unused:UNUSED_PAD src0_sel:WORD_1
	v_cvt_f32_f16_e32 v148, v52
	v_pk_add_f32 v[136:137], v[136:137], v[150:151]
	v_cvt_f32_f16_sdwa v151, v60 dst_sel:DWORD dst_unused:UNUSED_PAD src0_sel:WORD_1
	v_cvt_f32_f16_e32 v150, v60
	v_pk_add_f32 v[136:137], v[136:137], v[138:139]
	v_pk_add_f32 v[134:135], v[134:135], v[148:149]
	v_pk_add_f32 v[136:137], v[136:137], v[146:147]
	v_cvt_f32_f16_sdwa v147, v53 dst_sel:DWORD dst_unused:UNUSED_PAD src0_sel:WORD_1
	v_cvt_f32_f16_e32 v146, v53
	v_cvt_f32_f16_sdwa v149, v61 dst_sel:DWORD dst_unused:UNUSED_PAD src0_sel:WORD_1
	v_cvt_f32_f16_e32 v148, v61
	v_pk_add_f32 v[134:135], v[134:135], v[150:151]
	v_cvt_f32_f16_sdwa v139, v68 dst_sel:DWORD dst_unused:UNUSED_PAD src0_sel:WORD_1
	v_cvt_f32_f16_e32 v138, v68
	v_cvt_f32_f16_sdwa v151, v69 dst_sel:DWORD dst_unused:UNUSED_PAD src0_sel:WORD_1
	v_cvt_f32_f16_e32 v150, v69
	v_pk_add_f32 v[132:133], v[132:133], v[146:147]
	v_pk_add_f32 v[134:135], v[134:135], v[138:139]
	v_pk_add_f32 v[132:133], v[132:133], v[148:149]
	v_cvt_pk_bf16_f32 v146, v130, v131
	v_pk_add_f32 v[132:133], v[132:133], v[150:151]
	v_cvt_pk_bf16_f32 v147, v136, v137
	v_cvt_pk_bf16_f32 v148, v134, v135
	v_cvt_pk_bf16_f32 v149, v132, v133
	global_store_dwordx4 v[128:129], v[146:149], off offset:1024 sc1
.LBB0_641:
	s_or_b64 exec, exec, s[8:9]
	v_mul_f32_e32 v114, v109, v109
	v_mul_f32_e32 v128, v113, v113
	v_fmac_f32_e32 v114, v108, v108
	v_fmac_f32_e32 v128, v112, v112
	v_add_f32_e32 v114, v114, v128
	v_mul_f32_e32 v128, v111, v111
	v_mul_f32_e32 v129, v107, v107
	v_fmac_f32_e32 v128, v110, v110
	v_fmac_f32_e32 v129, v106, v106
	v_add_f32_e32 v128, v128, v129
	v_mov_b32_e32 v138, v135
	v_mov_b32_e32 v139, v131
	v_add_f32_e32 v114, v128, v114
	v_mov_b32_e32 v128, v134
	v_mov_b32_e32 v129, v130
	v_pk_mul_f32 v[138:139], v[138:139], v[138:139]
	v_mov_b32_e32 v146, v133
	v_mov_b32_e32 v147, v137
	v_pk_fma_f32 v[128:129], v[128:129], v[128:129], v[138:139]
	v_mov_b32_e32 v138, v132
	v_mov_b32_e32 v139, v136
	v_pk_mul_f32 v[146:147], v[146:147], v[146:147]
	s_lshl_b64 s[6:7], s[68:69], 11
	v_pk_fma_f32 v[138:139], v[138:139], v[138:139], v[146:147]
	s_nop 0
	v_pk_add_f32 v[128:129], v[128:129], v[138:139]
	s_nop 0
	v_add_f32_e32 v114, v114, v129
	v_add_f32_e32 v114, v128, v114
	ds_bpermute_b32 v128, v117, v114
	s_waitcnt lgkmcnt(0)
	v_add_f32_e32 v114, v114, v128
	ds_bpermute_b32 v128, v140, v114
	s_waitcnt lgkmcnt(0)
	v_add_f32_e32 v114, v114, v128
	ds_bpermute_b32 v128, v141, v114
	s_waitcnt lgkmcnt(0)
	v_add_f32_e32 v114, v114, v128
	ds_bpermute_b32 v128, v142, v114
	s_waitcnt lgkmcnt(0)
	v_add_f32_e32 v114, v114, v128
	ds_bpermute_b32 v128, v143, v114
	s_waitcnt lgkmcnt(0)
	v_add_f32_e32 v114, v114, v128
	ds_bpermute_b32 v128, v144, v114
	s_waitcnt lgkmcnt(0)
	v_add_f32_e32 v114, v114, v128
	v_fmamk_f32 v114, v114, 0x3a800000, v145
	v_mul_f32_e32 v128, 0x4b800000, v114
	v_cmp_gt_f32_e32 vcc, s72, v114
	s_nop 1
	v_cndmask_b32_e32 v114, v114, v128, vcc
	v_rsq_f32_e32 v114, v114
	v_lshl_add_u64 v[128:129], v[122:123], 0, s[6:7]
	v_mul_f32_e32 v138, 0x45800000, v114
	v_cndmask_b32_e32 v114, v114, v138, vcc
	v_pk_mul_f32 v[108:109], v[114:115], v[108:109] op_sel_hi:[0,1]
	v_pk_mul_f32 v[112:113], v[114:115], v[112:113] op_sel_hi:[0,1]
	v_pk_mul_f32 v[110:111], v[114:115], v[110:111] op_sel_hi:[0,1]
	v_pk_mul_f32 v[106:107], v[114:115], v[106:107] op_sel_hi:[0,1]
	s_waitcnt vmcnt(2)
	v_pk_fma_f32 v[112:113], v[92:93], v[112:113], v[80:81]
	v_pk_fma_f32 v[108:109], v[90:91], v[108:109], v[78:79]
	v_pk_fma_f32 v[138:139], v[96:97], v[106:107], v[76:77]
	v_pk_fma_f32 v[110:111], v[94:95], v[110:111], v[74:75]
	v_cvt_pk_bf16_f32 v106, v108, v109
	v_cvt_pk_bf16_f32 v107, v112, v113
	v_cvt_pk_bf16_f32 v108, v110, v111
	v_cvt_pk_bf16_f32 v109, v138, v139
	global_store_dwordx4 v[128:129], v[106:109], off sc1
	v_pk_mul_f32 v[110:111], v[114:115], v[134:135] op_sel_hi:[0,1]
	v_pk_mul_f32 v[112:113], v[114:115], v[132:133] op_sel_hi:[0,1]
	v_pk_mul_f32 v[106:107], v[114:115], v[130:131] op_sel_hi:[0,1]
	v_pk_mul_f32 v[108:109], v[114:115], v[136:137] op_sel_hi:[0,1]
	s_waitcnt vmcnt(1)
	v_pk_fma_f32 v[108:109], v[100:101], v[108:109], v[88:89]
	v_pk_fma_f32 v[106:107], v[98:99], v[106:107], v[86:87]
	v_pk_fma_f32 v[112:113], v[104:105], v[112:113], v[84:85]
	v_pk_fma_f32 v[110:111], v[102:103], v[110:111], v[82:83]
	v_cvt_pk_bf16_f32 v106, v106, v107
	v_cvt_pk_bf16_f32 v107, v108, v109
	v_cvt_pk_bf16_f32 v108, v110, v111
	v_cvt_pk_bf16_f32 v109, v112, v113
	global_store_dwordx4 v[128:129], v[106:109], off offset:1024 sc1

.LBB0_650:
	s_or_b64 exec, exec, s[14:15]
	s_ashr_i32 s65, s64, 31
	s_lshl_b64 s[14:15], s[64:65], 12
	s_add_u32 s2, s54, s14
	s_addc_u32 s15, s55, s15
	s_lshl_b32 s14, s16, 1
	s_add_u32 s14, s2, s14
	s_addc_u32 s15, s15, 0
	v_lshlrev_b32_e32 v114, 1, v116
	v_lshl_add_u64 v[128:129], s[14:15], 0, v[114:115]
	v_lshlrev_b32_e32 v108, 16, v30
	v_and_b32_e32 v109, 0xffff0000, v30
	v_lshlrev_b32_e32 v112, 16, v31
	v_and_b32_e32 v113, 0xffff0000, v31
	v_lshlrev_b32_e32 v110, 16, v32
	v_and_b32_e32 v111, 0xffff0000, v32
	v_lshlrev_b32_e32 v106, 16, v33
	v_and_b32_e32 v107, 0xffff0000, v33
	s_and_saveexec_b64 s[66:67], s[8:9]
	s_cbranch_execz .LBB0_652
	s_waitcnt vmcnt(2)
	v_cvt_f32_f16_sdwa v131, v54 dst_sel:DWORD dst_unused:UNUSED_PAD src0_sel:WORD_1
	v_cvt_f32_f16_e32 v130, v54
	s_waitcnt vmcnt(1)
	v_cvt_f32_f16_sdwa v133, v62 dst_sel:DWORD dst_unused:UNUSED_PAD src0_sel:WORD_1
	v_cvt_f32_f16_e32 v132, v62
	s_waitcnt vmcnt(0)
	v_cvt_f32_f16_sdwa v135, v70 dst_sel:DWORD dst_unused:UNUSED_PAD src0_sel:WORD_1
	v_cvt_f32_f16_e32 v134, v70
	v_cvt_f32_f16_sdwa v137, v55 dst_sel:DWORD dst_unused:UNUSED_PAD src0_sel:WORD_1
	v_cvt_f32_f16_e32 v136, v55
	v_pk_add_f32 v[108:109], v[108:109], v[130:131]
	v_cvt_f32_f16_sdwa v131, v63 dst_sel:DWORD dst_unused:UNUSED_PAD src0_sel:WORD_1
	v_cvt_f32_f16_e32 v130, v63
	v_pk_add_f32 v[108:109], v[108:109], v[132:133]
	v_cvt_f32_f16_sdwa v133, v71 dst_sel:DWORD dst_unused:UNUSED_PAD src0_sel:WORD_1
	v_cvt_f32_f16_e32 v132, v71
	v_pk_add_f32 v[108:109], v[108:109], v[134:135]
	v_cvt_f32_f16_sdwa v135, v56 dst_sel:DWORD dst_unused:UNUSED_PAD src0_sel:WORD_1
	v_cvt_f32_f16_e32 v134, v56
	v_pk_add_f32 v[112:113], v[112:113], v[136:137]
	v_cvt_f32_f16_sdwa v137, v64 dst_sel:DWORD dst_unused:UNUSED_PAD src0_sel:WORD_1
	v_cvt_f32_f16_e32 v136, v64
	v_pk_add_f32 v[112:113], v[112:113], v[130:131]
	v_pk_add_f32 v[110:111], v[110:111], v[134:135]
	v_pk_add_f32 v[112:113], v[112:113], v[132:133]
	v_cvt_f32_f16_sdwa v133, v57 dst_sel:DWORD dst_unused:UNUSED_PAD src0_sel:WORD_1
	v_cvt_f32_f16_e32 v132, v57
	v_cvt_f32_f16_sdwa v135, v65 dst_sel:DWORD dst_unused:UNUSED_PAD src0_sel:WORD_1
	v_cvt_f32_f16_e32 v134, v65
	v_pk_add_f32 v[110:111], v[110:111], v[136:137]
	v_cvt_f32_f16_sdwa v131, v72 dst_sel:DWORD dst_unused:UNUSED_PAD src0_sel:WORD_1
	v_cvt_f32_f16_e32 v130, v72
	v_cvt_f32_f16_sdwa v137, v73 dst_sel:DWORD dst_unused:UNUSED_PAD src0_sel:WORD_1
	v_cvt_f32_f16_e32 v136, v73
	v_pk_add_f32 v[106:107], v[106:107], v[132:133]
	v_pk_add_f32 v[110:111], v[110:111], v[130:131]
	v_pk_add_f32 v[106:107], v[106:107], v[134:135]
	v_cvt_pk_bf16_f32 v130, v108, v109
	v_pk_add_f32 v[106:107], v[106:107], v[136:137]
	v_cvt_pk_bf16_f32 v131, v112, v113
	v_cvt_pk_bf16_f32 v132, v110, v111
	v_cvt_pk_bf16_f32 v133, v106, v107
	global_store_dwordx4 v[128:129], v[130:133], off sc1
.LBB0_652:
	s_or_b64 exec, exec, s[66:67]
	s_nop 0
	v_lshlrev_b32_e32 v130, 16, v26
	v_and_b32_e32 v131, 0xffff0000, v26
	v_lshlrev_b32_e32 v136, 16, v27
	v_and_b32_e32 v137, 0xffff0000, v27
	v_lshlrev_b32_e32 v134, 16, v28
	v_and_b32_e32 v135, 0xffff0000, v28
	v_lshlrev_b32_e32 v132, 16, v29
	v_and_b32_e32 v133, 0xffff0000, v29
	s_and_saveexec_b64 s[8:9], s[6:7]
	s_cbranch_execz .LBB0_654
	s_waitcnt vmcnt(2)
	v_cvt_f32_f16_sdwa v139, v50 dst_sel:DWORD dst_unused:UNUSED_PAD src0_sel:WORD_1
	v_cvt_f32_f16_e32 v138, v50
	s_waitcnt vmcnt(1)
	v_cvt_f32_f16_sdwa v147, v58 dst_sel:DWORD dst_unused:UNUSED_PAD src0_sel:WORD_1
	v_cvt_f32_f16_e32 v146, v58
	s_waitcnt vmcnt(0)
	v_cvt_f32_f16_sdwa v149, v66 dst_sel:DWORD dst_unused:UNUSED_PAD src0_sel:WORD_1
	v_cvt_f32_f16_e32 v148, v66
	v_cvt_f32_f16_sdwa v151, v51 dst_sel:DWORD dst_unused:UNUSED_PAD src0_sel:WORD_1
	v_cvt_f32_f16_e32 v150, v51
	v_pk_add_f32 v[130:131], v[130:131], v[138:139]
	v_cvt_f32_f16_sdwa v139, v59 dst_sel:DWORD dst_unused:UNUSED_PAD src0_sel:WORD_1
	v_cvt_f32_f16_e32 v138, v59
	v_pk_add_f32 v[130:131], v[130:131], v[146:147]
	v_cvt_f32_f16_sdwa v147, v67 dst_sel:DWORD dst_unused:UNUSED_PAD src0_sel:WORD_1
	v_cvt_f32_f16_e32 v146, v67
	v_pk_add_f32 v[130:131], v[130:131], v[148:149]
	v_cvt_f32_f16_sdwa v149, v52 dst_sel:DWORD dst_unused:UNUSED_PAD src0_sel:WORD_1
	v_cvt_f32_f16_e32 v148, v52
	v_pk_add_f32 v[136:137], v[136:137], v[150:151]
	v_cvt_f32_f16_sdwa v151, v60 dst_sel:DWORD dst_unused:UNUSED_PAD src0_sel:WORD_1
	v_cvt_f32_f16_e32 v150, v60
	v_pk_add_f32 v[136:137], v[136:137], v[138:139]
	v_pk_add_f32 v[134:135], v[134:135], v[148:149]
	v_pk_add_f32 v[136:137], v[136:137], v[146:147]
	v_cvt_f32_f16_sdwa v147, v53 dst_sel:DWORD dst_unused:UNUSED_PAD src0_sel:WORD_1
	v_cvt_f32_f16_e32 v146, v53
	v_cvt_f32_f16_sdwa v149, v61 dst_sel:DWORD dst_unused:UNUSED_PAD src0_sel:WORD_1
	v_cvt_f32_f16_e32 v148, v61
	v_pk_add_f32 v[134:135], v[134:135], v[150:151]
	v_cvt_f32_f16_sdwa v139, v68 dst_sel:DWORD dst_unused:UNUSED_PAD src0_sel:WORD_1
	v_cvt_f32_f16_e32 v138, v68
	v_cvt_f32_f16_sdwa v151, v69 dst_sel:DWORD dst_unused:UNUSED_PAD src0_sel:WORD_1
	v_cvt_f32_f16_e32 v150, v69
	v_pk_add_f32 v[132:133], v[132:133], v[146:147]
	v_pk_add_f32 v[134:135], v[134:135], v[138:139]
	v_pk_add_f32 v[132:133], v[132:133], v[148:149]
	v_cvt_pk_bf16_f32 v146, v130, v131
	v_pk_add_f32 v[132:133], v[132:133], v[150:151]
	v_cvt_pk_bf16_f32 v147, v136, v137
	v_cvt_pk_bf16_f32 v148, v134, v135
	v_cvt_pk_bf16_f32 v149, v132, v133
	global_store_dwordx4 v[128:129], v[146:149], off offset:1024 sc1
.LBB0_654:
	s_or_b64 exec, exec, s[8:9]
	v_mul_f32_e32 v114, v109, v109
	v_mul_f32_e32 v128, v113, v113
	v_fmac_f32_e32 v114, v108, v108
	v_fmac_f32_e32 v128, v112, v112
	v_add_f32_e32 v114, v114, v128
	v_mul_f32_e32 v128, v111, v111
	v_mul_f32_e32 v129, v107, v107
	v_fmac_f32_e32 v128, v110, v110
	v_fmac_f32_e32 v129, v106, v106
	v_add_f32_e32 v128, v128, v129
	v_mov_b32_e32 v138, v135
	v_mov_b32_e32 v139, v131
	v_add_f32_e32 v114, v128, v114
	v_mov_b32_e32 v128, v134
	v_mov_b32_e32 v129, v130
	v_pk_mul_f32 v[138:139], v[138:139], v[138:139]
	v_mov_b32_e32 v146, v133
	v_mov_b32_e32 v147, v137
	v_pk_fma_f32 v[128:129], v[128:129], v[128:129], v[138:139]
	v_mov_b32_e32 v138, v132
	v_mov_b32_e32 v139, v136
	v_pk_mul_f32 v[146:147], v[146:147], v[146:147]
	s_lshl_b64 s[6:7], s[64:65], 11
	v_pk_fma_f32 v[138:139], v[138:139], v[138:139], v[146:147]
	s_nop 0
	v_pk_add_f32 v[128:129], v[128:129], v[138:139]
	s_nop 0
	v_add_f32_e32 v114, v114, v129
	v_add_f32_e32 v114, v128, v114
	ds_bpermute_b32 v128, v117, v114
	s_waitcnt lgkmcnt(0)
	v_add_f32_e32 v114, v114, v128
	ds_bpermute_b32 v128, v140, v114
	s_waitcnt lgkmcnt(0)
	v_add_f32_e32 v114, v114, v128
	ds_bpermute_b32 v128, v141, v114
	s_waitcnt lgkmcnt(0)
	v_add_f32_e32 v114, v114, v128
	ds_bpermute_b32 v128, v142, v114
	s_waitcnt lgkmcnt(0)
	v_add_f32_e32 v114, v114, v128
	ds_bpermute_b32 v128, v143, v114
	s_waitcnt lgkmcnt(0)
	v_add_f32_e32 v114, v114, v128
	ds_bpermute_b32 v128, v144, v114
	s_waitcnt lgkmcnt(0)
	v_add_f32_e32 v114, v114, v128
	v_fmamk_f32 v114, v114, 0x3a800000, v145
	v_mul_f32_e32 v128, 0x4b800000, v114
	v_cmp_gt_f32_e32 vcc, s72, v114
	s_nop 1
	v_cndmask_b32_e32 v114, v114, v128, vcc
	v_rsq_f32_e32 v114, v114
	v_lshl_add_u64 v[128:129], v[122:123], 0, s[6:7]
	v_mul_f32_e32 v138, 0x45800000, v114
	v_cndmask_b32_e32 v114, v114, v138, vcc
	v_pk_mul_f32 v[108:109], v[114:115], v[108:109] op_sel_hi:[0,1]
	v_pk_mul_f32 v[112:113], v[114:115], v[112:113] op_sel_hi:[0,1]
	v_pk_mul_f32 v[110:111], v[114:115], v[110:111] op_sel_hi:[0,1]
	v_pk_mul_f32 v[106:107], v[114:115], v[106:107] op_sel_hi:[0,1]
	s_waitcnt vmcnt(2)
	v_pk_fma_f32 v[112:113], v[92:93], v[112:113], v[80:81]
	v_pk_fma_f32 v[108:109], v[90:91], v[108:109], v[78:79]
	v_pk_fma_f32 v[138:139], v[96:97], v[106:107], v[76:77]
	v_pk_fma_f32 v[110:111], v[94:95], v[110:111], v[74:75]
	v_cvt_pk_bf16_f32 v106, v108, v109
	v_cvt_pk_bf16_f32 v107, v112, v113
	v_cvt_pk_bf16_f32 v108, v110, v111
	v_cvt_pk_bf16_f32 v109, v138, v139
	global_store_dwordx4 v[128:129], v[106:109], off sc1
	v_pk_mul_f32 v[110:111], v[114:115], v[134:135] op_sel_hi:[0,1]
	v_pk_mul_f32 v[112:113], v[114:115], v[132:133] op_sel_hi:[0,1]
	v_pk_mul_f32 v[106:107], v[114:115], v[130:131] op_sel_hi:[0,1]
	v_pk_mul_f32 v[108:109], v[114:115], v[136:137] op_sel_hi:[0,1]
	s_waitcnt vmcnt(1)
	v_pk_fma_f32 v[108:109], v[100:101], v[108:109], v[88:89]
	v_pk_fma_f32 v[106:107], v[98:99], v[106:107], v[86:87]
	v_pk_fma_f32 v[112:113], v[104:105], v[112:113], v[84:85]
	v_pk_fma_f32 v[110:111], v[102:103], v[110:111], v[82:83]
	v_cvt_pk_bf16_f32 v106, v106, v107
	v_cvt_pk_bf16_f32 v107, v108, v109
	v_cvt_pk_bf16_f32 v108, v110, v111
	v_cvt_pk_bf16_f32 v109, v112, v113
	global_store_dwordx4 v[128:129], v[106:109], off offset:1024 sc1

.LBB0_663:
	s_or_b64 exec, exec, s[14:15]
	s_ashr_i32 s47, s46, 31
	s_lshl_b64 s[14:15], s[46:47], 12
	s_add_u32 s2, s54, s14
	s_addc_u32 s15, s55, s15
	s_add_i32 s14, s62, 0xc00
	s_and_b32 s14, s14, 0x400
	s_lshl_b32 s14, s14, 1
	s_add_u32 s14, s2, s14
	s_addc_u32 s15, s15, 0
	v_lshlrev_b32_e32 v114, 1, v116
	v_lshl_add_u64 v[128:129], s[14:15], 0, v[114:115]
	v_lshlrev_b32_e32 v108, 16, v38
	v_and_b32_e32 v109, 0xffff0000, v38
	v_lshlrev_b32_e32 v112, 16, v39
	v_and_b32_e32 v113, 0xffff0000, v39
	v_lshlrev_b32_e32 v110, 16, v40
	v_and_b32_e32 v111, 0xffff0000, v40
	v_lshlrev_b32_e32 v106, 16, v41
	v_and_b32_e32 v107, 0xffff0000, v41
	s_and_saveexec_b64 s[48:49], s[8:9]
	s_cbranch_execz .LBB0_665
	s_waitcnt vmcnt(2)
	v_cvt_f32_f16_sdwa v131, v54 dst_sel:DWORD dst_unused:UNUSED_PAD src0_sel:WORD_1
	v_cvt_f32_f16_e32 v130, v54
	s_waitcnt vmcnt(1)
	v_cvt_f32_f16_sdwa v133, v62 dst_sel:DWORD dst_unused:UNUSED_PAD src0_sel:WORD_1
	v_cvt_f32_f16_e32 v132, v62
	s_waitcnt vmcnt(0)
	v_cvt_f32_f16_sdwa v135, v70 dst_sel:DWORD dst_unused:UNUSED_PAD src0_sel:WORD_1
	v_cvt_f32_f16_e32 v134, v70
	v_cvt_f32_f16_sdwa v137, v55 dst_sel:DWORD dst_unused:UNUSED_PAD src0_sel:WORD_1
	v_cvt_f32_f16_e32 v136, v55
	v_pk_add_f32 v[108:109], v[108:109], v[130:131]
	v_cvt_f32_f16_sdwa v131, v63 dst_sel:DWORD dst_unused:UNUSED_PAD src0_sel:WORD_1
	v_cvt_f32_f16_e32 v130, v63
	v_pk_add_f32 v[108:109], v[108:109], v[132:133]
	v_cvt_f32_f16_sdwa v133, v71 dst_sel:DWORD dst_unused:UNUSED_PAD src0_sel:WORD_1
	v_cvt_f32_f16_e32 v132, v71
	v_pk_add_f32 v[108:109], v[108:109], v[134:135]
	v_cvt_f32_f16_sdwa v135, v56 dst_sel:DWORD dst_unused:UNUSED_PAD src0_sel:WORD_1
	v_cvt_f32_f16_e32 v134, v56
	v_pk_add_f32 v[112:113], v[112:113], v[136:137]
	v_cvt_f32_f16_sdwa v137, v64 dst_sel:DWORD dst_unused:UNUSED_PAD src0_sel:WORD_1
	v_cvt_f32_f16_e32 v136, v64
	v_pk_add_f32 v[112:113], v[112:113], v[130:131]
	v_pk_add_f32 v[110:111], v[110:111], v[134:135]
	v_pk_add_f32 v[112:113], v[112:113], v[132:133]
	v_cvt_f32_f16_sdwa v133, v57 dst_sel:DWORD dst_unused:UNUSED_PAD src0_sel:WORD_1
	v_cvt_f32_f16_e32 v132, v57
	v_cvt_f32_f16_sdwa v135, v65 dst_sel:DWORD dst_unused:UNUSED_PAD src0_sel:WORD_1
	v_cvt_f32_f16_e32 v134, v65
	v_pk_add_f32 v[110:111], v[110:111], v[136:137]
	v_cvt_f32_f16_sdwa v131, v72 dst_sel:DWORD dst_unused:UNUSED_PAD src0_sel:WORD_1
	v_cvt_f32_f16_e32 v130, v72
	v_cvt_f32_f16_sdwa v137, v73 dst_sel:DWORD dst_unused:UNUSED_PAD src0_sel:WORD_1
	v_cvt_f32_f16_e32 v136, v73
	v_pk_add_f32 v[106:107], v[106:107], v[132:133]
	v_pk_add_f32 v[110:111], v[110:111], v[130:131]
	v_pk_add_f32 v[106:107], v[106:107], v[134:135]
	v_cvt_pk_bf16_f32 v130, v108, v109
	v_pk_add_f32 v[106:107], v[106:107], v[136:137]
	v_cvt_pk_bf16_f32 v131, v112, v113
	v_cvt_pk_bf16_f32 v132, v110, v111
	v_cvt_pk_bf16_f32 v133, v106, v107
	global_store_dwordx4 v[128:129], v[130:133], off sc1
.LBB0_665:
	s_or_b64 exec, exec, s[48:49]
	s_nop 0
	v_lshlrev_b32_e32 v130, 16, v34
	v_and_b32_e32 v131, 0xffff0000, v34
	v_lshlrev_b32_e32 v136, 16, v35
	v_and_b32_e32 v137, 0xffff0000, v35
	v_lshlrev_b32_e32 v134, 16, v36
	v_and_b32_e32 v135, 0xffff0000, v36
	v_lshlrev_b32_e32 v132, 16, v37
	v_and_b32_e32 v133, 0xffff0000, v37
	s_and_saveexec_b64 s[8:9], s[6:7]
	s_cbranch_execz .LBB0_667
	s_waitcnt vmcnt(2)
	v_cvt_f32_f16_sdwa v139, v50 dst_sel:DWORD dst_unused:UNUSED_PAD src0_sel:WORD_1
	v_cvt_f32_f16_e32 v138, v50
	s_waitcnt vmcnt(1)
	v_cvt_f32_f16_sdwa v147, v58 dst_sel:DWORD dst_unused:UNUSED_PAD src0_sel:WORD_1
	v_cvt_f32_f16_e32 v146, v58
	s_waitcnt vmcnt(0)
	v_cvt_f32_f16_sdwa v149, v66 dst_sel:DWORD dst_unused:UNUSED_PAD src0_sel:WORD_1
	v_cvt_f32_f16_e32 v148, v66
	v_cvt_f32_f16_sdwa v151, v51 dst_sel:DWORD dst_unused:UNUSED_PAD src0_sel:WORD_1
	v_cvt_f32_f16_e32 v150, v51
	v_pk_add_f32 v[130:131], v[130:131], v[138:139]
	v_cvt_f32_f16_sdwa v139, v59 dst_sel:DWORD dst_unused:UNUSED_PAD src0_sel:WORD_1
	v_cvt_f32_f16_e32 v138, v59
	v_pk_add_f32 v[130:131], v[130:131], v[146:147]
	v_cvt_f32_f16_sdwa v147, v67 dst_sel:DWORD dst_unused:UNUSED_PAD src0_sel:WORD_1
	v_cvt_f32_f16_e32 v146, v67
	v_pk_add_f32 v[130:131], v[130:131], v[148:149]
	v_cvt_f32_f16_sdwa v149, v52 dst_sel:DWORD dst_unused:UNUSED_PAD src0_sel:WORD_1
	v_cvt_f32_f16_e32 v148, v52
	v_pk_add_f32 v[136:137], v[136:137], v[150:151]
	v_cvt_f32_f16_sdwa v151, v60 dst_sel:DWORD dst_unused:UNUSED_PAD src0_sel:WORD_1
	v_cvt_f32_f16_e32 v150, v60
	v_pk_add_f32 v[136:137], v[136:137], v[138:139]
	v_pk_add_f32 v[134:135], v[134:135], v[148:149]
	v_pk_add_f32 v[136:137], v[136:137], v[146:147]
	v_cvt_f32_f16_sdwa v147, v53 dst_sel:DWORD dst_unused:UNUSED_PAD src0_sel:WORD_1
	v_cvt_f32_f16_e32 v146, v53
	v_cvt_f32_f16_sdwa v149, v61 dst_sel:DWORD dst_unused:UNUSED_PAD src0_sel:WORD_1
	v_cvt_f32_f16_e32 v148, v61
	v_pk_add_f32 v[134:135], v[134:135], v[150:151]
	v_cvt_f32_f16_sdwa v139, v68 dst_sel:DWORD dst_unused:UNUSED_PAD src0_sel:WORD_1
	v_cvt_f32_f16_e32 v138, v68
	v_cvt_f32_f16_sdwa v151, v69 dst_sel:DWORD dst_unused:UNUSED_PAD src0_sel:WORD_1
	v_cvt_f32_f16_e32 v150, v69
	v_pk_add_f32 v[132:133], v[132:133], v[146:147]
	v_pk_add_f32 v[134:135], v[134:135], v[138:139]
	v_pk_add_f32 v[132:133], v[132:133], v[148:149]
	v_cvt_pk_bf16_f32 v146, v130, v131
	v_pk_add_f32 v[132:133], v[132:133], v[150:151]
	v_cvt_pk_bf16_f32 v147, v136, v137
	v_cvt_pk_bf16_f32 v148, v134, v135
	v_cvt_pk_bf16_f32 v149, v132, v133
	global_store_dwordx4 v[128:129], v[146:149], off offset:1024 sc1
.LBB0_667:
	s_or_b64 exec, exec, s[8:9]
	v_mul_f32_e32 v114, v109, v109
	v_mul_f32_e32 v128, v113, v113
	v_fmac_f32_e32 v114, v108, v108
	v_fmac_f32_e32 v128, v112, v112
	v_add_f32_e32 v114, v114, v128
	v_mul_f32_e32 v128, v111, v111
	v_mul_f32_e32 v129, v107, v107
	v_fmac_f32_e32 v128, v110, v110
	v_fmac_f32_e32 v129, v106, v106
	v_add_f32_e32 v128, v128, v129
	v_mov_b32_e32 v138, v135
	v_mov_b32_e32 v139, v131
	v_add_f32_e32 v114, v128, v114
	v_mov_b32_e32 v128, v134
	v_mov_b32_e32 v129, v130
	v_pk_mul_f32 v[138:139], v[138:139], v[138:139]
	v_mov_b32_e32 v146, v133
	v_mov_b32_e32 v147, v137
	v_pk_fma_f32 v[128:129], v[128:129], v[128:129], v[138:139]
	v_mov_b32_e32 v138, v132
	v_mov_b32_e32 v139, v136
	v_pk_mul_f32 v[146:147], v[146:147], v[146:147]
	s_lshl_b64 s[6:7], s[46:47], 11
	v_pk_fma_f32 v[138:139], v[138:139], v[138:139], v[146:147]
	s_nop 0
	v_pk_add_f32 v[128:129], v[128:129], v[138:139]
	s_nop 0
	v_add_f32_e32 v114, v114, v129
	v_add_f32_e32 v114, v128, v114
	ds_bpermute_b32 v128, v117, v114
	s_waitcnt lgkmcnt(0)
	v_add_f32_e32 v114, v114, v128
	ds_bpermute_b32 v128, v140, v114
	s_waitcnt lgkmcnt(0)
	v_add_f32_e32 v114, v114, v128
	ds_bpermute_b32 v128, v141, v114
	s_waitcnt lgkmcnt(0)
	v_add_f32_e32 v114, v114, v128
	ds_bpermute_b32 v128, v142, v114
	s_waitcnt lgkmcnt(0)
	v_add_f32_e32 v114, v114, v128
	ds_bpermute_b32 v128, v143, v114
	s_waitcnt lgkmcnt(0)
	v_add_f32_e32 v114, v114, v128
	ds_bpermute_b32 v128, v144, v114
	s_waitcnt lgkmcnt(0)
	v_add_f32_e32 v114, v114, v128
	v_fmamk_f32 v114, v114, 0x3a800000, v145
	v_mul_f32_e32 v128, 0x4b800000, v114
	v_cmp_gt_f32_e32 vcc, s72, v114
	s_nop 1
	v_cndmask_b32_e32 v114, v114, v128, vcc
	v_rsq_f32_e32 v114, v114
	v_lshl_add_u64 v[128:129], v[122:123], 0, s[6:7]
	v_mul_f32_e32 v138, 0x45800000, v114
	v_cndmask_b32_e32 v114, v114, v138, vcc
	v_pk_mul_f32 v[108:109], v[114:115], v[108:109] op_sel_hi:[0,1]
	v_pk_mul_f32 v[112:113], v[114:115], v[112:113] op_sel_hi:[0,1]
	v_pk_mul_f32 v[110:111], v[114:115], v[110:111] op_sel_hi:[0,1]
	v_pk_mul_f32 v[106:107], v[114:115], v[106:107] op_sel_hi:[0,1]
	s_waitcnt vmcnt(2)
	v_pk_fma_f32 v[112:113], v[92:93], v[112:113], v[80:81]
	v_pk_fma_f32 v[108:109], v[90:91], v[108:109], v[78:79]
	v_pk_fma_f32 v[138:139], v[96:97], v[106:107], v[76:77]
	v_pk_fma_f32 v[110:111], v[94:95], v[110:111], v[74:75]
	v_cvt_pk_bf16_f32 v106, v108, v109
	v_cvt_pk_bf16_f32 v107, v112, v113
	v_cvt_pk_bf16_f32 v108, v110, v111
	v_cvt_pk_bf16_f32 v109, v138, v139
	global_store_dwordx4 v[128:129], v[106:109], off sc1
	v_pk_mul_f32 v[110:111], v[114:115], v[134:135] op_sel_hi:[0,1]
	v_pk_mul_f32 v[112:113], v[114:115], v[132:133] op_sel_hi:[0,1]
	v_pk_mul_f32 v[106:107], v[114:115], v[130:131] op_sel_hi:[0,1]
	v_pk_mul_f32 v[108:109], v[114:115], v[136:137] op_sel_hi:[0,1]
	s_waitcnt vmcnt(1)
	v_pk_fma_f32 v[108:109], v[100:101], v[108:109], v[88:89]
	v_pk_fma_f32 v[106:107], v[98:99], v[106:107], v[86:87]
	v_pk_fma_f32 v[112:113], v[104:105], v[112:113], v[84:85]
	v_pk_fma_f32 v[110:111], v[102:103], v[110:111], v[82:83]
	v_cvt_pk_bf16_f32 v106, v106, v107
	v_cvt_pk_bf16_f32 v107, v108, v109
	v_cvt_pk_bf16_f32 v108, v110, v111
	v_cvt_pk_bf16_f32 v109, v112, v113
	global_store_dwordx4 v[128:129], v[106:109], off offset:1024 sc1

.LBB0_676:
	s_or_b64 exec, exec, s[8:9]
	s_ashr_i32 s43, s42, 31
	s_lshl_b64 s[8:9], s[42:43], 12
	s_add_u32 s2, s54, s8
	s_addc_u32 s9, s55, s9
	s_lshl_b32 s8, s16, 1
	s_add_u32 s8, s2, s8
	s_addc_u32 s9, s9, 0
	v_lshlrev_b32_e32 v114, 1, v116
	v_lshl_add_u64 v[128:129], s[8:9], 0, v[114:115]
	v_lshlrev_b32_e32 v108, 16, v22
	v_and_b32_e32 v109, 0xffff0000, v22
	v_lshlrev_b32_e32 v112, 16, v23
	v_and_b32_e32 v113, 0xffff0000, v23
	v_lshlrev_b32_e32 v110, 16, v24
	v_and_b32_e32 v111, 0xffff0000, v24
	v_lshlrev_b32_e32 v106, 16, v25
	v_and_b32_e32 v107, 0xffff0000, v25
	s_and_saveexec_b64 s[8:9], s[6:7]
	s_cbranch_execz .LBB0_678
	s_waitcnt vmcnt(2)
	v_cvt_f32_f16_sdwa v131, v54 dst_sel:DWORD dst_unused:UNUSED_PAD src0_sel:WORD_1
	v_cvt_f32_f16_e32 v130, v54
	s_waitcnt vmcnt(1)
	v_cvt_f32_f16_sdwa v133, v62 dst_sel:DWORD dst_unused:UNUSED_PAD src0_sel:WORD_1
	v_cvt_f32_f16_e32 v132, v62
	s_waitcnt vmcnt(0)
	v_cvt_f32_f16_sdwa v135, v70 dst_sel:DWORD dst_unused:UNUSED_PAD src0_sel:WORD_1
	v_cvt_f32_f16_e32 v134, v70
	v_cvt_f32_f16_sdwa v137, v55 dst_sel:DWORD dst_unused:UNUSED_PAD src0_sel:WORD_1
	v_cvt_f32_f16_e32 v136, v55
	v_pk_add_f32 v[108:109], v[108:109], v[130:131]
	v_cvt_f32_f16_sdwa v131, v63 dst_sel:DWORD dst_unused:UNUSED_PAD src0_sel:WORD_1
	v_cvt_f32_f16_e32 v130, v63
	v_pk_add_f32 v[108:109], v[108:109], v[132:133]
	v_cvt_f32_f16_sdwa v133, v71 dst_sel:DWORD dst_unused:UNUSED_PAD src0_sel:WORD_1
	v_cvt_f32_f16_e32 v132, v71
	v_pk_add_f32 v[108:109], v[108:109], v[134:135]
	v_cvt_f32_f16_sdwa v135, v56 dst_sel:DWORD dst_unused:UNUSED_PAD src0_sel:WORD_1
	v_cvt_f32_f16_e32 v134, v56
	v_pk_add_f32 v[112:113], v[112:113], v[136:137]
	v_cvt_f32_f16_sdwa v137, v64 dst_sel:DWORD dst_unused:UNUSED_PAD src0_sel:WORD_1
	v_cvt_f32_f16_e32 v136, v64
	v_pk_add_f32 v[112:113], v[112:113], v[130:131]
	v_pk_add_f32 v[110:111], v[110:111], v[134:135]
	v_pk_add_f32 v[112:113], v[112:113], v[132:133]
	v_cvt_f32_f16_sdwa v133, v57 dst_sel:DWORD dst_unused:UNUSED_PAD src0_sel:WORD_1
	v_cvt_f32_f16_e32 v132, v57
	v_cvt_f32_f16_sdwa v135, v65 dst_sel:DWORD dst_unused:UNUSED_PAD src0_sel:WORD_1
	v_cvt_f32_f16_e32 v134, v65
	v_pk_add_f32 v[110:111], v[110:111], v[136:137]
	v_cvt_f32_f16_sdwa v131, v72 dst_sel:DWORD dst_unused:UNUSED_PAD src0_sel:WORD_1
	v_cvt_f32_f16_e32 v130, v72
	v_cvt_f32_f16_sdwa v137, v73 dst_sel:DWORD dst_unused:UNUSED_PAD src0_sel:WORD_1
	v_cvt_f32_f16_e32 v136, v73
	v_pk_add_f32 v[106:107], v[106:107], v[132:133]
	v_pk_add_f32 v[110:111], v[110:111], v[130:131]
	v_pk_add_f32 v[106:107], v[106:107], v[134:135]
	v_cvt_pk_bf16_f32 v130, v108, v109
	v_pk_add_f32 v[106:107], v[106:107], v[136:137]
	v_cvt_pk_bf16_f32 v131, v112, v113
	v_cvt_pk_bf16_f32 v132, v110, v111
	v_cvt_pk_bf16_f32 v133, v106, v107
	global_store_dwordx4 v[128:129], v[130:133], off sc1
.LBB0_678:
	s_or_b64 exec, exec, s[8:9]
	s_nop 0
	v_lshlrev_b32_e32 v130, 16, v18
	v_and_b32_e32 v131, 0xffff0000, v18
	v_lshlrev_b32_e32 v136, 16, v19
	v_and_b32_e32 v137, 0xffff0000, v19
	v_lshlrev_b32_e32 v134, 16, v20
	v_and_b32_e32 v135, 0xffff0000, v20
	v_lshlrev_b32_e32 v132, 16, v21
	v_and_b32_e32 v133, 0xffff0000, v21
	s_and_saveexec_b64 s[6:7], s[4:5]
	s_cbranch_execz .LBB0_610
	s_waitcnt vmcnt(2)
	v_cvt_f32_f16_sdwa v139, v50 dst_sel:DWORD dst_unused:UNUSED_PAD src0_sel:WORD_1
	v_cvt_f32_f16_e32 v138, v50
	s_waitcnt vmcnt(1)
	v_cvt_f32_f16_sdwa v147, v58 dst_sel:DWORD dst_unused:UNUSED_PAD src0_sel:WORD_1
	v_cvt_f32_f16_e32 v146, v58
	s_waitcnt vmcnt(0)
	v_cvt_f32_f16_sdwa v149, v66 dst_sel:DWORD dst_unused:UNUSED_PAD src0_sel:WORD_1
	v_cvt_f32_f16_e32 v148, v66
	v_cvt_f32_f16_sdwa v151, v51 dst_sel:DWORD dst_unused:UNUSED_PAD src0_sel:WORD_1
	v_cvt_f32_f16_e32 v150, v51
	v_pk_add_f32 v[130:131], v[130:131], v[138:139]
	v_cvt_f32_f16_sdwa v139, v59 dst_sel:DWORD dst_unused:UNUSED_PAD src0_sel:WORD_1
	v_cvt_f32_f16_e32 v138, v59
	v_pk_add_f32 v[130:131], v[130:131], v[146:147]
	v_cvt_f32_f16_sdwa v147, v67 dst_sel:DWORD dst_unused:UNUSED_PAD src0_sel:WORD_1
	v_cvt_f32_f16_e32 v146, v67
	v_pk_add_f32 v[130:131], v[130:131], v[148:149]
	v_cvt_f32_f16_sdwa v149, v52 dst_sel:DWORD dst_unused:UNUSED_PAD src0_sel:WORD_1
	v_cvt_f32_f16_e32 v148, v52
	v_pk_add_f32 v[136:137], v[136:137], v[150:151]
	v_cvt_f32_f16_sdwa v151, v60 dst_sel:DWORD dst_unused:UNUSED_PAD src0_sel:WORD_1
	v_cvt_f32_f16_e32 v150, v60
	v_pk_add_f32 v[136:137], v[136:137], v[138:139]
	v_pk_add_f32 v[134:135], v[134:135], v[148:149]
	v_pk_add_f32 v[136:137], v[136:137], v[146:147]
	v_cvt_f32_f16_sdwa v147, v53 dst_sel:DWORD dst_unused:UNUSED_PAD src0_sel:WORD_1
	v_cvt_f32_f16_e32 v146, v53
	v_cvt_f32_f16_sdwa v149, v61 dst_sel:DWORD dst_unused:UNUSED_PAD src0_sel:WORD_1
	v_cvt_f32_f16_e32 v148, v61
	v_pk_add_f32 v[134:135], v[134:135], v[150:151]
	v_cvt_f32_f16_sdwa v139, v68 dst_sel:DWORD dst_unused:UNUSED_PAD src0_sel:WORD_1
	v_cvt_f32_f16_e32 v138, v68
	v_cvt_f32_f16_sdwa v151, v69 dst_sel:DWORD dst_unused:UNUSED_PAD src0_sel:WORD_1
	v_cvt_f32_f16_e32 v150, v69
	v_pk_add_f32 v[132:133], v[132:133], v[146:147]
	v_pk_add_f32 v[134:135], v[134:135], v[138:139]
	v_pk_add_f32 v[132:133], v[132:133], v[148:149]
	v_cvt_pk_bf16_f32 v146, v130, v131
	v_pk_add_f32 v[132:133], v[132:133], v[150:151]
	v_cvt_pk_bf16_f32 v147, v136, v137
	v_cvt_pk_bf16_f32 v148, v134, v135
	v_cvt_pk_bf16_f32 v149, v132, v133
	global_store_dwordx4 v[128:129], v[146:149], off offset:1024 sc1
	s_branch .LBB0_610

.LBB0_878:
	s_or_b64 exec, exec, s[0:1]
	v_mul_f32_e32 v114, v109, v109
	v_mul_f32_e32 v128, v113, v113
	v_fmac_f32_e32 v114, v108, v108
	v_fmac_f32_e32 v128, v112, v112
	v_add_f32_e32 v114, v114, v128
	v_mul_f32_e32 v128, v111, v111
	v_mul_f32_e32 v129, v107, v107
	v_fmac_f32_e32 v128, v110, v110
	v_fmac_f32_e32 v129, v106, v106
	v_add_f32_e32 v128, v128, v129
	v_mov_b32_e32 v138, v135
	v_mov_b32_e32 v139, v131
	v_add_f32_e32 v114, v128, v114
	v_mov_b32_e32 v128, v134
	v_mov_b32_e32 v129, v130
	v_pk_mul_f32 v[138:139], v[138:139], v[138:139]
	v_mov_b32_e32 v146, v133
	v_mov_b32_e32 v147, v137
	v_pk_fma_f32 v[128:129], v[128:129], v[128:129], v[138:139]
	v_mov_b32_e32 v138, v132
	v_mov_b32_e32 v139, v136
	v_pk_mul_f32 v[146:147], v[146:147], v[146:147]
	s_lshl_b64 s[0:1], s[44:45], 11
	v_pk_fma_f32 v[138:139], v[138:139], v[138:139], v[146:147]
	s_nop 0
	v_pk_add_f32 v[128:129], v[128:129], v[138:139]
	s_nop 0
	v_add_f32_e32 v114, v114, v129
	v_add_f32_e32 v114, v128, v114
	ds_bpermute_b32 v128, v117, v114
	s_waitcnt lgkmcnt(0)
	v_add_f32_e32 v114, v114, v128
	ds_bpermute_b32 v128, v140, v114
	s_waitcnt lgkmcnt(0)
	v_add_f32_e32 v114, v114, v128
	ds_bpermute_b32 v128, v141, v114
	s_waitcnt lgkmcnt(0)
	v_add_f32_e32 v114, v114, v128
	ds_bpermute_b32 v128, v142, v114
	s_waitcnt lgkmcnt(0)
	v_add_f32_e32 v114, v114, v128
	ds_bpermute_b32 v128, v143, v114
	s_waitcnt lgkmcnt(0)
	v_add_f32_e32 v114, v114, v128
	ds_bpermute_b32 v128, v144, v114
	s_waitcnt lgkmcnt(0)
	v_add_f32_e32 v114, v114, v128
	v_fmamk_f32 v114, v114, 0x3a800000, v145
	v_mul_f32_e32 v128, 0x4b800000, v114
	v_cmp_gt_f32_e32 vcc, s62, v114
	s_nop 1
	v_cndmask_b32_e32 v114, v114, v128, vcc
	v_rsq_f32_e32 v114, v114
	v_lshl_add_u64 v[128:129], v[122:123], 0, s[0:1]
	v_mul_f32_e32 v138, 0x45800000, v114
	v_cndmask_b32_e32 v114, v114, v138, vcc
	v_pk_mul_f32 v[108:109], v[114:115], v[108:109] op_sel_hi:[0,1]
	v_pk_mul_f32 v[112:113], v[114:115], v[112:113] op_sel_hi:[0,1]
	v_pk_mul_f32 v[110:111], v[114:115], v[110:111] op_sel_hi:[0,1]
	v_pk_mul_f32 v[106:107], v[114:115], v[106:107] op_sel_hi:[0,1]
	s_waitcnt vmcnt(3)
	v_pk_fma_f32 v[112:113], v[96:97], v[112:113], v[76:77]
	v_pk_fma_f32 v[108:109], v[94:95], v[108:109], v[74:75]
	s_waitcnt vmcnt(1)
	v_pk_fma_f32 v[138:139], v[92:93], v[106:107], v[84:85]
	v_pk_fma_f32 v[110:111], v[90:91], v[110:111], v[82:83]
	v_cvt_pk_bf16_f32 v106, v108, v109
	v_cvt_pk_bf16_f32 v107, v112, v113
	v_cvt_pk_bf16_f32 v108, v110, v111
	v_cvt_pk_bf16_f32 v109, v138, v139
	global_store_dwordx4 v[128:129], v[106:109], off sc1
	v_pk_mul_f32 v[110:111], v[114:115], v[134:135] op_sel_hi:[0,1]
	v_pk_mul_f32 v[112:113], v[114:115], v[132:133] op_sel_hi:[0,1]
	v_pk_mul_f32 v[106:107], v[114:115], v[130:131] op_sel_hi:[0,1]
	v_pk_mul_f32 v[108:109], v[114:115], v[136:137] op_sel_hi:[0,1]
	s_waitcnt vmcnt(1)
	v_pk_fma_f32 v[108:109], v[100:101], v[108:109], v[88:89]
	v_pk_fma_f32 v[106:107], v[98:99], v[106:107], v[86:87]
	v_pk_fma_f32 v[112:113], v[104:105], v[112:113], v[80:81]
	v_pk_fma_f32 v[110:111], v[102:103], v[110:111], v[78:79]
	v_cvt_pk_bf16_f32 v106, v106, v107
	v_cvt_pk_bf16_f32 v107, v108, v109
	v_cvt_pk_bf16_f32 v108, v110, v111
	v_cvt_pk_bf16_f32 v109, v112, v113
	global_store_dwordx4 v[128:129], v[106:109], off offset:1024 sc1

.LBB0_894:
	s_or_b64 exec, exec, s[0:1]
	s_waitcnt vmcnt(1)
	v_lshlrev_b32_e32 v130, 16, v110
	v_and_b32_e32 v131, 0xffff0000, v110
	v_lshlrev_b32_e32 v134, 16, v111
	v_and_b32_e32 v135, 0xffff0000, v111
	v_lshlrev_b32_e32 v132, 16, v112
	v_and_b32_e32 v133, 0xffff0000, v112
	v_lshlrev_b32_e32 v110, 16, v113
	v_and_b32_e32 v111, 0xffff0000, v113
	s_and_saveexec_b64 s[0:1], s[6:7]
	s_cbranch_execz .LBB0_896
	v_cvt_f32_f16_sdwa v113, v54 dst_sel:DWORD dst_unused:UNUSED_PAD src0_sel:WORD_1
	v_cvt_f32_f16_e32 v112, v54
	v_cvt_f32_f16_sdwa v137, v62 dst_sel:DWORD dst_unused:UNUSED_PAD src0_sel:WORD_1
	v_cvt_f32_f16_e32 v136, v62
	s_waitcnt vmcnt(0)
	v_cvt_f32_f16_sdwa v139, v70 dst_sel:DWORD dst_unused:UNUSED_PAD src0_sel:WORD_1
	v_cvt_f32_f16_e32 v138, v70
	v_cvt_f32_f16_sdwa v147, v55 dst_sel:DWORD dst_unused:UNUSED_PAD src0_sel:WORD_1
	v_cvt_f32_f16_e32 v146, v55
	v_pk_add_f32 v[112:113], v[130:131], v[112:113]
	s_nop 0
	v_pk_add_f32 v[112:113], v[112:113], v[136:137]
	v_cvt_f32_f16_sdwa v137, v71 dst_sel:DWORD dst_unused:UNUSED_PAD src0_sel:WORD_1
	v_pk_add_f32 v[130:131], v[112:113], v[138:139]
	v_pk_add_f32 v[112:113], v[134:135], v[146:147]
	v_cvt_f32_f16_sdwa v135, v63 dst_sel:DWORD dst_unused:UNUSED_PAD src0_sel:WORD_1
	v_cvt_f32_f16_e32 v134, v63
	v_cvt_f32_f16_e32 v136, v71
	v_cvt_f32_f16_sdwa v139, v56 dst_sel:DWORD dst_unused:UNUSED_PAD src0_sel:WORD_1
	v_cvt_f32_f16_e32 v138, v56
	v_cvt_f32_f16_sdwa v147, v64 dst_sel:DWORD dst_unused:UNUSED_PAD src0_sel:WORD_1
	v_cvt_f32_f16_e32 v146, v64
	v_pk_add_f32 v[112:113], v[112:113], v[134:135]
	s_nop 0
	v_pk_add_f32 v[134:135], v[112:113], v[136:137]
	v_cvt_f32_f16_sdwa v137, v57 dst_sel:DWORD dst_unused:UNUSED_PAD src0_sel:WORD_1
	v_cvt_f32_f16_e32 v136, v57
	v_pk_add_f32 v[112:113], v[132:133], v[138:139]
	v_cvt_f32_f16_sdwa v139, v65 dst_sel:DWORD dst_unused:UNUSED_PAD src0_sel:WORD_1
	v_cvt_f32_f16_e32 v138, v65
	v_pk_add_f32 v[112:113], v[112:113], v[146:147]
	v_cvt_f32_f16_sdwa v133, v72 dst_sel:DWORD dst_unused:UNUSED_PAD src0_sel:WORD_1
	v_cvt_f32_f16_e32 v132, v72
	v_cvt_f32_f16_sdwa v147, v73 dst_sel:DWORD dst_unused:UNUSED_PAD src0_sel:WORD_1
	v_cvt_f32_f16_e32 v146, v73
	v_pk_add_f32 v[110:111], v[110:111], v[136:137]
	v_pk_add_f32 v[132:133], v[112:113], v[132:133]
	v_pk_add_f32 v[110:111], v[110:111], v[138:139]
	v_cvt_pk_bf16_f32 v136, v130, v131
	v_pk_add_f32 v[110:111], v[110:111], v[146:147]
	v_cvt_pk_bf16_f32 v137, v134, v135
	v_cvt_pk_bf16_f32 v138, v132, v133
	v_cvt_pk_bf16_f32 v139, v110, v111
	global_store_dwordx4 v[128:129], v[136:139], off offset:-1024 sc1
.LBB0_896:
	s_or_b64 exec, exec, s[0:1]
	s_waitcnt vmcnt(0)
	v_lshlrev_b32_e32 v112, 16, v106
	v_and_b32_e32 v113, 0xffff0000, v106
	v_lshlrev_b32_e32 v138, 16, v107
	v_and_b32_e32 v139, 0xffff0000, v107
	v_lshlrev_b32_e32 v136, 16, v108
	v_and_b32_e32 v137, 0xffff0000, v108
	v_lshlrev_b32_e32 v106, 16, v109
	v_and_b32_e32 v107, 0xffff0000, v109
	s_and_saveexec_b64 s[0:1], s[4:5]
	s_cbranch_execz .LBB0_898
	v_cvt_f32_f16_sdwa v109, v50 dst_sel:DWORD dst_unused:UNUSED_PAD src0_sel:WORD_1
	v_cvt_f32_f16_e32 v108, v50
	v_cvt_f32_f16_sdwa v147, v58 dst_sel:DWORD dst_unused:UNUSED_PAD src0_sel:WORD_1
	v_cvt_f32_f16_e32 v146, v58
	v_cvt_f32_f16_sdwa v149, v66 dst_sel:DWORD dst_unused:UNUSED_PAD src0_sel:WORD_1
	v_cvt_f32_f16_e32 v148, v66
	v_cvt_f32_f16_sdwa v151, v51 dst_sel:DWORD dst_unused:UNUSED_PAD src0_sel:WORD_1
	v_cvt_f32_f16_e32 v150, v51
	v_pk_add_f32 v[108:109], v[112:113], v[108:109]
	s_nop 0
	v_pk_add_f32 v[108:109], v[108:109], v[146:147]
	v_cvt_f32_f16_sdwa v147, v67 dst_sel:DWORD dst_unused:UNUSED_PAD src0_sel:WORD_1
	v_pk_add_f32 v[112:113], v[108:109], v[148:149]
	v_pk_add_f32 v[108:109], v[138:139], v[150:151]
	v_cvt_f32_f16_sdwa v139, v59 dst_sel:DWORD dst_unused:UNUSED_PAD src0_sel:WORD_1
	v_cvt_f32_f16_e32 v138, v59
	v_cvt_f32_f16_e32 v146, v67
	v_cvt_f32_f16_sdwa v149, v52 dst_sel:DWORD dst_unused:UNUSED_PAD src0_sel:WORD_1
	v_cvt_f32_f16_e32 v148, v52
	v_cvt_f32_f16_sdwa v151, v60 dst_sel:DWORD dst_unused:UNUSED_PAD src0_sel:WORD_1
	v_cvt_f32_f16_e32 v150, v60
	v_pk_add_f32 v[108:109], v[108:109], v[138:139]
	s_nop 0
	v_pk_add_f32 v[138:139], v[108:109], v[146:147]
	v_cvt_f32_f16_sdwa v147, v53 dst_sel:DWORD dst_unused:UNUSED_PAD src0_sel:WORD_1
	v_cvt_f32_f16_e32 v146, v53
	v_pk_add_f32 v[108:109], v[136:137], v[148:149]
	v_cvt_f32_f16_sdwa v149, v61 dst_sel:DWORD dst_unused:UNUSED_PAD src0_sel:WORD_1
	v_cvt_f32_f16_e32 v148, v61
	v_pk_add_f32 v[108:109], v[108:109], v[150:151]
	v_cvt_f32_f16_sdwa v137, v68 dst_sel:DWORD dst_unused:UNUSED_PAD src0_sel:WORD_1
	v_cvt_f32_f16_e32 v136, v68
	v_cvt_f32_f16_sdwa v151, v69 dst_sel:DWORD dst_unused:UNUSED_PAD src0_sel:WORD_1
	v_cvt_f32_f16_e32 v150, v69
	v_pk_add_f32 v[106:107], v[106:107], v[146:147]
	v_pk_add_f32 v[136:137], v[108:109], v[136:137]
	v_pk_add_f32 v[106:107], v[106:107], v[148:149]
	v_cvt_pk_bf16_f32 v146, v112, v113
	v_pk_add_f32 v[106:107], v[106:107], v[150:151]
	v_cvt_pk_bf16_f32 v147, v138, v139
	v_cvt_pk_bf16_f32 v148, v136, v137
	v_cvt_pk_bf16_f32 v149, v106, v107
	global_store_dwordx4 v[128:129], v[146:149], off sc1
.LBB0_898:
	s_or_b64 exec, exec, s[0:1]
	v_mul_f32_e32 v108, v131, v131
	v_mul_f32_e32 v109, v135, v135
	v_fmac_f32_e32 v108, v130, v130
	v_fmac_f32_e32 v109, v134, v134
	v_add_f32_e32 v108, v108, v109
	v_mul_f32_e32 v109, v133, v133
	v_mul_f32_e32 v114, v111, v111
	v_fmac_f32_e32 v109, v132, v132
	v_fmac_f32_e32 v114, v110, v110
	v_add_f32_e32 v109, v109, v114
	v_mov_b32_e32 v128, v137
	v_mov_b32_e32 v129, v113
	v_add_f32_e32 v114, v109, v108
	v_mov_b32_e32 v108, v136
	v_mov_b32_e32 v109, v112
	v_pk_mul_f32 v[128:129], v[128:129], v[128:129]
	v_mov_b32_e32 v146, v107
	v_mov_b32_e32 v147, v139
	v_pk_fma_f32 v[108:109], v[108:109], v[108:109], v[128:129]
	v_mov_b32_e32 v128, v106
	v_mov_b32_e32 v129, v138
	v_pk_mul_f32 v[146:147], v[146:147], v[146:147]
	s_nop 0
	v_pk_fma_f32 v[128:129], v[128:129], v[128:129], v[146:147]
	s_nop 0
	v_pk_add_f32 v[108:109], v[108:109], v[128:129]
	s_nop 0
	v_add_f32_e32 v109, v114, v109
	v_add_f32_e32 v108, v108, v109
	ds_bpermute_b32 v109, v117, v108
	s_waitcnt lgkmcnt(0)
	v_add_f32_e32 v108, v108, v109
	ds_bpermute_b32 v109, v140, v108
	s_waitcnt lgkmcnt(0)
	v_add_f32_e32 v108, v108, v109
	ds_bpermute_b32 v109, v141, v108
	s_waitcnt lgkmcnt(0)
	v_add_f32_e32 v108, v108, v109
	ds_bpermute_b32 v109, v142, v108
	s_waitcnt lgkmcnt(0)
	v_add_f32_e32 v108, v108, v109
	ds_bpermute_b32 v109, v143, v108
	s_waitcnt lgkmcnt(0)
	v_add_f32_e32 v108, v108, v109
	ds_bpermute_b32 v109, v144, v108
	s_waitcnt lgkmcnt(0)
	v_add_f32_e32 v108, v108, v109
	v_fmamk_f32 v108, v108, 0x3a800000, v145
	v_mul_f32_e32 v109, 0x4b800000, v108
	v_cmp_gt_f32_e32 vcc, s62, v108
	s_nop 1
	v_cndmask_b32_e32 v108, v108, v109, vcc
	v_rsq_f32_e32 v108, v108
	s_nop 0
	v_mul_f32_e32 v109, 0x45800000, v108
	v_cndmask_b32_e32 v114, v108, v109, vcc
	v_pk_mul_f32 v[108:109], v[114:115], v[130:131] op_sel_hi:[0,1]
	v_pk_mul_f32 v[128:129], v[114:115], v[134:135] op_sel_hi:[0,1]
	v_pk_mul_f32 v[130:131], v[114:115], v[132:133] op_sel_hi:[0,1]
	v_pk_mul_f32 v[110:111], v[114:115], v[110:111] op_sel_hi:[0,1]
	v_pk_fma_f32 v[128:129], v[96:97], v[128:129], v[76:77]
	v_pk_fma_f32 v[108:109], v[94:95], v[108:109], v[74:75]
	v_pk_fma_f32 v[132:133], v[92:93], v[110:111], v[84:85]
	v_pk_fma_f32 v[110:111], v[90:91], v[130:131], v[82:83]
	v_cvt_pk_bf16_f32 v108, v108, v109
	v_cvt_pk_bf16_f32 v109, v128, v129
	v_cvt_pk_bf16_f32 v110, v110, v111
	v_cvt_pk_bf16_f32 v111, v132, v133
	global_store_dwordx4 v[124:125], v[108:111], off sc1
	v_pk_mul_f32 v[106:107], v[114:115], v[106:107] op_sel_hi:[0,1]
	v_pk_fma_f32 v[128:129], v[104:105], v[106:107], v[80:81]
	v_pk_mul_f32 v[110:111], v[114:115], v[138:139] op_sel_hi:[0,1]
	v_pk_mul_f32 v[108:109], v[114:115], v[112:113] op_sel_hi:[0,1]
	v_pk_fma_f32 v[110:111], v[100:101], v[110:111], v[88:89]
	v_pk_mul_f32 v[112:113], v[114:115], v[136:137] op_sel_hi:[0,1]
	v_pk_fma_f32 v[108:109], v[98:99], v[108:109], v[86:87]
	v_pk_fma_f32 v[112:113], v[102:103], v[112:113], v[78:79]
	v_cvt_pk_bf16_f32 v107, v110, v111
	v_cndmask_b32_e64 v110, 0, 1, s[8:9]
	v_cvt_pk_bf16_f32 v106, v108, v109
	v_cvt_pk_bf16_f32 v108, v112, v113
	v_cvt_pk_bf16_f32 v109, v128, v129
	v_cmp_ne_u32_e64 s[4:5], 1, v110
	s_andn2_b64 vcc, exec, s[8:9]
	global_store_dwordx4 v[124:125], v[106:109], off offset:1024 sc1
	s_cbranch_vccnz .LBB0_910
	s_ashr_i32 s2, s68, 12
	s_cmp_eq_u32 s2, s63
	s_cbranch_scc1 .LBB0_901
	s_mul_i32 s0, s2, 12
	s_ashr_i32 s1, s0, 31
	s_lshl_b64 s[0:1], s[0:1], 12
	v_lshl_add_u64 v[78:79], v[118:119], 0, s[0:1]
	v_add_co_u32_e32 v76, vcc, 0x6000, v78
	v_lshl_add_u64 v[74:75], v[78:79], 0, s[26:27]
	s_mov_b64 s[0:1], vcc
	v_add_co_u32_e32 v80, vcc, 0x7000, v78
	global_load_dwordx4 v[90:93], v[74:75], off offset:16
	s_nop 0
	v_addc_co_u32_e32 v81, vcc, 0, v79, vcc
	v_lshl_add_u64 v[74:75], v[78:79], 0, s[36:37]
	global_load_dwordx4 v[94:97], v[80:81], off
	global_load_dwordx4 v[98:101], v[80:81], off offset:2048
	global_load_dwordx4 v[102:105], v[74:75], off offset:16
	v_addc_co_u32_e64 v77, vcc, 0, v79, s[0:1]
	v_lshl_add_u64 v[86:87], v[78:79], 0, s[22:23]
	global_load_dwordx4 v[74:77], v[76:77], off
	s_nop 0
	global_load_dwordx4 v[78:81], v[86:87], off offset:2064
	global_load_dwordx4 v[82:85], v[86:87], off offset:16
	s_nop 0
	global_load_dwordx4 v[86:89], v[86:87], off offset:2048
	s_mov_b32 s63, s2
	s_waitcnt vmcnt(7)
	v_pk_add_f32 v[92:93], v[92:93], 1.0 op_sel_hi:[1,0]
	v_pk_add_f32 v[90:91], v[90:91], 1.0 op_sel_hi:[1,0]
	v_pk_mul_f32 v[92:93], v[12:13], v[92:93]
	s_waitcnt vmcnt(6)
	v_pk_add_f32 v[96:97], v[96:97], 1.0 op_sel_hi:[1,0]
	v_pk_add_f32 v[94:95], v[94:95], 1.0 op_sel_hi:[1,0]
	s_waitcnt vmcnt(5)
	v_pk_add_f32 v[100:101], v[100:101], 1.0 op_sel_hi:[1,0]
	v_pk_add_f32 v[98:99], v[98:99], 1.0 op_sel_hi:[1,0]
	s_waitcnt vmcnt(4)
	v_pk_add_f32 v[104:105], v[104:105], 1.0 op_sel_hi:[1,0]
	v_pk_add_f32 v[102:103], v[102:103], 1.0 op_sel_hi:[1,0]
	v_pk_mul_f32 v[90:91], v[10:11], v[90:91]
	v_pk_mul_f32 v[96:97], v[4:5], v[96:97]
	v_pk_mul_f32 v[94:95], v[2:3], v[94:95]
	v_pk_mul_f32 v[100:101], v[16:17], v[100:101]
	v_pk_mul_f32 v[98:99], v[14:15], v[98:99]
	v_pk_mul_f32 v[104:105], v[8:9], v[104:105]
	v_pk_mul_f32 v[102:103], v[6:7], v[102:103]

.LBB0_905:
	s_or_b64 exec, exec, s[0:1]
	s_ashr_i32 s69, s68, 31
	s_lshl_b64 s[0:1], s[68:69], 12
	s_add_u32 s0, s54, s0
	s_addc_u32 s1, s55, s1
	s_add_i32 s2, s15, 0x400
	s_and_b32 s2, s2, 0x400
	s_lshl_b32 s2, s2, 1
	s_add_u32 s0, s0, s2
	s_addc_u32 s1, s1, 0
	v_lshlrev_b32_e32 v114, 1, v116
	v_lshl_add_u64 v[128:129], s[0:1], 0, v[114:115]
	v_lshlrev_b32_e32 v108, 16, v46
	v_and_b32_e32 v109, 0xffff0000, v46
	v_lshlrev_b32_e32 v112, 16, v47
	v_and_b32_e32 v113, 0xffff0000, v47
	v_lshlrev_b32_e32 v110, 16, v48
	v_and_b32_e32 v111, 0xffff0000, v48
	v_lshlrev_b32_e32 v106, 16, v49
	v_and_b32_e32 v107, 0xffff0000, v49
	s_and_saveexec_b64 s[0:1], s[8:9]
	s_cbranch_execz .LBB0_907
	s_waitcnt vmcnt(2)
	v_cvt_f32_f16_sdwa v131, v54 dst_sel:DWORD dst_unused:UNUSED_PAD src0_sel:WORD_1
	v_cvt_f32_f16_e32 v130, v54
	s_waitcnt vmcnt(1)
	v_cvt_f32_f16_sdwa v133, v62 dst_sel:DWORD dst_unused:UNUSED_PAD src0_sel:WORD_1
	v_cvt_f32_f16_e32 v132, v62
	s_waitcnt vmcnt(0)
	v_cvt_f32_f16_sdwa v135, v70 dst_sel:DWORD dst_unused:UNUSED_PAD src0_sel:WORD_1
	v_cvt_f32_f16_e32 v134, v70
	v_cvt_f32_f16_sdwa v137, v55 dst_sel:DWORD dst_unused:UNUSED_PAD src0_sel:WORD_1
	v_cvt_f32_f16_e32 v136, v55
	v_pk_add_f32 v[108:109], v[108:109], v[130:131]
	v_cvt_f32_f16_sdwa v131, v63 dst_sel:DWORD dst_unused:UNUSED_PAD src0_sel:WORD_1
	v_cvt_f32_f16_e32 v130, v63
	v_pk_add_f32 v[108:109], v[108:109], v[132:133]
	v_cvt_f32_f16_sdwa v133, v71 dst_sel:DWORD dst_unused:UNUSED_PAD src0_sel:WORD_1
	v_cvt_f32_f16_e32 v132, v71
	v_pk_add_f32 v[108:109], v[108:109], v[134:135]
	v_cvt_f32_f16_sdwa v135, v56 dst_sel:DWORD dst_unused:UNUSED_PAD src0_sel:WORD_1
	v_cvt_f32_f16_e32 v134, v56
	v_pk_add_f32 v[112:113], v[112:113], v[136:137]
	v_cvt_f32_f16_sdwa v137, v64 dst_sel:DWORD dst_unused:UNUSED_PAD src0_sel:WORD_1
	v_cvt_f32_f16_e32 v136, v64
	v_pk_add_f32 v[112:113], v[112:113], v[130:131]
	v_pk_add_f32 v[110:111], v[110:111], v[134:135]
	v_pk_add_f32 v[112:113], v[112:113], v[132:133]
	v_cvt_f32_f16_sdwa v133, v57 dst_sel:DWORD dst_unused:UNUSED_PAD src0_sel:WORD_1
	v_cvt_f32_f16_e32 v132, v57
	v_cvt_f32_f16_sdwa v135, v65 dst_sel:DWORD dst_unused:UNUSED_PAD src0_sel:WORD_1
	v_cvt_f32_f16_e32 v134, v65
	v_pk_add_f32 v[110:111], v[110:111], v[136:137]
	v_cvt_f32_f16_sdwa v131, v72 dst_sel:DWORD dst_unused:UNUSED_PAD src0_sel:WORD_1
	v_cvt_f32_f16_e32 v130, v72
	v_cvt_f32_f16_sdwa v137, v73 dst_sel:DWORD dst_unused:UNUSED_PAD src0_sel:WORD_1
	v_cvt_f32_f16_e32 v136, v73
	v_pk_add_f32 v[106:107], v[106:107], v[132:133]
	v_pk_add_f32 v[110:111], v[110:111], v[130:131]
	v_pk_add_f32 v[106:107], v[106:107], v[134:135]
	v_cvt_pk_bf16_f32 v130, v108, v109
	v_pk_add_f32 v[106:107], v[106:107], v[136:137]
	v_cvt_pk_bf16_f32 v131, v112, v113
	v_cvt_pk_bf16_f32 v132, v110, v111
	v_cvt_pk_bf16_f32 v133, v106, v107
	global_store_dwordx4 v[128:129], v[130:133], off sc1
.LBB0_907:
	s_or_b64 exec, exec, s[0:1]
	s_nop 0
	v_lshlrev_b32_e32 v130, 16, v42
	v_and_b32_e32 v131, 0xffff0000, v42
	v_lshlrev_b32_e32 v136, 16, v43
	v_and_b32_e32 v137, 0xffff0000, v43
	v_lshlrev_b32_e32 v134, 16, v44
	v_and_b32_e32 v135, 0xffff0000, v44
	v_lshlrev_b32_e32 v132, 16, v45
	v_and_b32_e32 v133, 0xffff0000, v45
	s_and_saveexec_b64 s[0:1], s[6:7]
	s_cbranch_execz .LBB0_909
	s_waitcnt vmcnt(2)
	v_cvt_f32_f16_sdwa v139, v50 dst_sel:DWORD dst_unused:UNUSED_PAD src0_sel:WORD_1
	v_cvt_f32_f16_e32 v138, v50
	s_waitcnt vmcnt(1)
	v_cvt_f32_f16_sdwa v147, v58 dst_sel:DWORD dst_unused:UNUSED_PAD src0_sel:WORD_1
	v_cvt_f32_f16_e32 v146, v58
	s_waitcnt vmcnt(0)
	v_cvt_f32_f16_sdwa v149, v66 dst_sel:DWORD dst_unused:UNUSED_PAD src0_sel:WORD_1
	v_cvt_f32_f16_e32 v148, v66
	v_cvt_f32_f16_sdwa v151, v51 dst_sel:DWORD dst_unused:UNUSED_PAD src0_sel:WORD_1
	v_cvt_f32_f16_e32 v150, v51
	v_pk_add_f32 v[130:131], v[130:131], v[138:139]
	v_cvt_f32_f16_sdwa v139, v59 dst_sel:DWORD dst_unused:UNUSED_PAD src0_sel:WORD_1
	v_cvt_f32_f16_e32 v138, v59
	v_pk_add_f32 v[130:131], v[130:131], v[146:147]
	v_cvt_f32_f16_sdwa v147, v67 dst_sel:DWORD dst_unused:UNUSED_PAD src0_sel:WORD_1
	v_cvt_f32_f16_e32 v146, v67
	v_pk_add_f32 v[130:131], v[130:131], v[148:149]
	v_cvt_f32_f16_sdwa v149, v52 dst_sel:DWORD dst_unused:UNUSED_PAD src0_sel:WORD_1
	v_cvt_f32_f16_e32 v148, v52
	v_pk_add_f32 v[136:137], v[136:137], v[150:151]
	v_cvt_f32_f16_sdwa v151, v60 dst_sel:DWORD dst_unused:UNUSED_PAD src0_sel:WORD_1
	v_cvt_f32_f16_e32 v150, v60
	v_pk_add_f32 v[136:137], v[136:137], v[138:139]
	v_pk_add_f32 v[134:135], v[134:135], v[148:149]
	v_pk_add_f32 v[136:137], v[136:137], v[146:147]
	v_cvt_f32_f16_sdwa v147, v53 dst_sel:DWORD dst_unused:UNUSED_PAD src0_sel:WORD_1
	v_cvt_f32_f16_e32 v146, v53
	v_cvt_f32_f16_sdwa v149, v61 dst_sel:DWORD dst_unused:UNUSED_PAD src0_sel:WORD_1
	v_cvt_f32_f16_e32 v148, v61
	v_pk_add_f32 v[134:135], v[134:135], v[150:151]
	v_cvt_f32_f16_sdwa v139, v68 dst_sel:DWORD dst_unused:UNUSED_PAD src0_sel:WORD_1
	v_cvt_f32_f16_e32 v138, v68
	v_cvt_f32_f16_sdwa v151, v69 dst_sel:DWORD dst_unused:UNUSED_PAD src0_sel:WORD_1
	v_cvt_f32_f16_e32 v150, v69
	v_pk_add_f32 v[132:133], v[132:133], v[146:147]
	v_pk_add_f32 v[134:135], v[134:135], v[138:139]
	v_pk_add_f32 v[132:133], v[132:133], v[148:149]
	v_cvt_pk_bf16_f32 v146, v130, v131
	v_pk_add_f32 v[132:133], v[132:133], v[150:151]
	v_cvt_pk_bf16_f32 v147, v136, v137
	v_cvt_pk_bf16_f32 v148, v134, v135
	v_cvt_pk_bf16_f32 v149, v132, v133
	global_store_dwordx4 v[128:129], v[146:149], off offset:1024 sc1
.LBB0_909:
	s_or_b64 exec, exec, s[0:1]
	v_mul_f32_e32 v114, v109, v109
	v_mul_f32_e32 v128, v113, v113
	v_fmac_f32_e32 v114, v108, v108
	v_fmac_f32_e32 v128, v112, v112
	v_add_f32_e32 v114, v114, v128
	v_mul_f32_e32 v128, v111, v111
	v_mul_f32_e32 v129, v107, v107
	v_fmac_f32_e32 v128, v110, v110
	v_fmac_f32_e32 v129, v106, v106
	v_add_f32_e32 v128, v128, v129
	v_mov_b32_e32 v138, v135
	v_mov_b32_e32 v139, v131
	v_add_f32_e32 v114, v128, v114
	v_mov_b32_e32 v128, v134
	v_mov_b32_e32 v129, v130
	v_pk_mul_f32 v[138:139], v[138:139], v[138:139]
	v_mov_b32_e32 v146, v133
	v_mov_b32_e32 v147, v137
	v_pk_fma_f32 v[128:129], v[128:129], v[128:129], v[138:139]
	v_mov_b32_e32 v138, v132
	v_mov_b32_e32 v139, v136
	v_pk_mul_f32 v[146:147], v[146:147], v[146:147]
	s_lshl_b64 s[0:1], s[68:69], 11
	v_pk_fma_f32 v[138:139], v[138:139], v[138:139], v[146:147]
	s_nop 0
	v_pk_add_f32 v[128:129], v[128:129], v[138:139]
	s_nop 0
	v_add_f32_e32 v114, v114, v129
	v_add_f32_e32 v114, v128, v114
	ds_bpermute_b32 v128, v117, v114
	s_waitcnt lgkmcnt(0)
	v_add_f32_e32 v114, v114, v128
	ds_bpermute_b32 v128, v140, v114
	s_waitcnt lgkmcnt(0)
	v_add_f32_e32 v114, v114, v128
	ds_bpermute_b32 v128, v141, v114
	s_waitcnt lgkmcnt(0)
	v_add_f32_e32 v114, v114, v128
	ds_bpermute_b32 v128, v142, v114
	s_waitcnt lgkmcnt(0)
	v_add_f32_e32 v114, v114, v128
	ds_bpermute_b32 v128, v143, v114
	s_waitcnt lgkmcnt(0)
	v_add_f32_e32 v114, v114, v128
	ds_bpermute_b32 v128, v144, v114
	s_waitcnt lgkmcnt(0)
	v_add_f32_e32 v114, v114, v128
	v_fmamk_f32 v114, v114, 0x3a800000, v145
	v_mul_f32_e32 v128, 0x4b800000, v114
	v_cmp_gt_f32_e32 vcc, s62, v114
	s_nop 1
	v_cndmask_b32_e32 v114, v114, v128, vcc
	v_rsq_f32_e32 v114, v114
	v_lshl_add_u64 v[128:129], v[122:123], 0, s[0:1]
	v_mul_f32_e32 v138, 0x45800000, v114
	v_cndmask_b32_e32 v114, v114, v138, vcc
	v_pk_mul_f32 v[108:109], v[114:115], v[108:109] op_sel_hi:[0,1]
	v_pk_mul_f32 v[112:113], v[114:115], v[112:113] op_sel_hi:[0,1]
	v_pk_mul_f32 v[110:111], v[114:115], v[110:111] op_sel_hi:[0,1]
	v_pk_mul_f32 v[106:107], v[114:115], v[106:107] op_sel_hi:[0,1]
	s_waitcnt vmcnt(3)
	v_pk_fma_f32 v[112:113], v[96:97], v[112:113], v[76:77]
	v_pk_fma_f32 v[108:109], v[94:95], v[108:109], v[74:75]
	s_waitcnt vmcnt(1)
	v_pk_fma_f32 v[138:139], v[92:93], v[106:107], v[84:85]
	v_pk_fma_f32 v[110:111], v[90:91], v[110:111], v[82:83]
	v_cvt_pk_bf16_f32 v106, v108, v109
	v_cvt_pk_bf16_f32 v107, v112, v113
	v_cvt_pk_bf16_f32 v108, v110, v111
	v_cvt_pk_bf16_f32 v109, v138, v139
	global_store_dwordx4 v[128:129], v[106:109], off sc1
	v_pk_mul_f32 v[110:111], v[114:115], v[134:135] op_sel_hi:[0,1]
	v_pk_mul_f32 v[112:113], v[114:115], v[132:133] op_sel_hi:[0,1]
	v_pk_mul_f32 v[106:107], v[114:115], v[130:131] op_sel_hi:[0,1]
	v_pk_mul_f32 v[108:109], v[114:115], v[136:137] op_sel_hi:[0,1]
	s_waitcnt vmcnt(1)
	v_pk_fma_f32 v[108:109], v[100:101], v[108:109], v[88:89]
	v_pk_fma_f32 v[106:107], v[98:99], v[106:107], v[86:87]
	v_pk_fma_f32 v[112:113], v[104:105], v[112:113], v[80:81]
	v_pk_fma_f32 v[110:111], v[102:103], v[110:111], v[78:79]
	v_cvt_pk_bf16_f32 v106, v106, v107
	v_cvt_pk_bf16_f32 v107, v108, v109
	v_cvt_pk_bf16_f32 v108, v110, v111
	v_cvt_pk_bf16_f32 v109, v112, v113
	global_store_dwordx4 v[128:129], v[106:109], off offset:1024 sc1

.LBB0_918:
	s_or_b64 exec, exec, s[0:1]
	s_ashr_i32 s65, s64, 31
	s_lshl_b64 s[0:1], s[64:65], 12
	s_add_u32 s0, s54, s0
	s_addc_u32 s1, s55, s1
	s_lshl_b32 s2, s70, 1
	s_add_u32 s0, s0, s2
	s_addc_u32 s1, s1, 0
	v_lshlrev_b32_e32 v114, 1, v116
	v_lshl_add_u64 v[128:129], s[0:1], 0, v[114:115]
	v_lshlrev_b32_e32 v108, 16, v30
	v_and_b32_e32 v109, 0xffff0000, v30
	v_lshlrev_b32_e32 v112, 16, v31
	v_and_b32_e32 v113, 0xffff0000, v31
	v_lshlrev_b32_e32 v110, 16, v32
	v_and_b32_e32 v111, 0xffff0000, v32
	v_lshlrev_b32_e32 v106, 16, v33
	v_and_b32_e32 v107, 0xffff0000, v33
	s_and_saveexec_b64 s[0:1], s[8:9]
	s_cbranch_execz .LBB0_920
	s_waitcnt vmcnt(2)
	v_cvt_f32_f16_sdwa v131, v54 dst_sel:DWORD dst_unused:UNUSED_PAD src0_sel:WORD_1
	v_cvt_f32_f16_e32 v130, v54
	s_waitcnt vmcnt(1)
	v_cvt_f32_f16_sdwa v133, v62 dst_sel:DWORD dst_unused:UNUSED_PAD src0_sel:WORD_1
	v_cvt_f32_f16_e32 v132, v62
	s_waitcnt vmcnt(0)
	v_cvt_f32_f16_sdwa v135, v70 dst_sel:DWORD dst_unused:UNUSED_PAD src0_sel:WORD_1
	v_cvt_f32_f16_e32 v134, v70
	v_cvt_f32_f16_sdwa v137, v55 dst_sel:DWORD dst_unused:UNUSED_PAD src0_sel:WORD_1
	v_cvt_f32_f16_e32 v136, v55
	v_pk_add_f32 v[108:109], v[108:109], v[130:131]
	v_cvt_f32_f16_sdwa v131, v63 dst_sel:DWORD dst_unused:UNUSED_PAD src0_sel:WORD_1
	v_cvt_f32_f16_e32 v130, v63
	v_pk_add_f32 v[108:109], v[108:109], v[132:133]
	v_cvt_f32_f16_sdwa v133, v71 dst_sel:DWORD dst_unused:UNUSED_PAD src0_sel:WORD_1
	v_cvt_f32_f16_e32 v132, v71
	v_pk_add_f32 v[108:109], v[108:109], v[134:135]
	v_cvt_f32_f16_sdwa v135, v56 dst_sel:DWORD dst_unused:UNUSED_PAD src0_sel:WORD_1
	v_cvt_f32_f16_e32 v134, v56
	v_pk_add_f32 v[112:113], v[112:113], v[136:137]
	v_cvt_f32_f16_sdwa v137, v64 dst_sel:DWORD dst_unused:UNUSED_PAD src0_sel:WORD_1
	v_cvt_f32_f16_e32 v136, v64
	v_pk_add_f32 v[112:113], v[112:113], v[130:131]
	v_pk_add_f32 v[110:111], v[110:111], v[134:135]
	v_pk_add_f32 v[112:113], v[112:113], v[132:133]
	v_cvt_f32_f16_sdwa v133, v57 dst_sel:DWORD dst_unused:UNUSED_PAD src0_sel:WORD_1
	v_cvt_f32_f16_e32 v132, v57
	v_cvt_f32_f16_sdwa v135, v65 dst_sel:DWORD dst_unused:UNUSED_PAD src0_sel:WORD_1
	v_cvt_f32_f16_e32 v134, v65
	v_pk_add_f32 v[110:111], v[110:111], v[136:137]
	v_cvt_f32_f16_sdwa v131, v72 dst_sel:DWORD dst_unused:UNUSED_PAD src0_sel:WORD_1
	v_cvt_f32_f16_e32 v130, v72
	v_cvt_f32_f16_sdwa v137, v73 dst_sel:DWORD dst_unused:UNUSED_PAD src0_sel:WORD_1
	v_cvt_f32_f16_e32 v136, v73
	v_pk_add_f32 v[106:107], v[106:107], v[132:133]
	v_pk_add_f32 v[110:111], v[110:111], v[130:131]
	v_pk_add_f32 v[106:107], v[106:107], v[134:135]
	v_cvt_pk_bf16_f32 v130, v108, v109
	v_pk_add_f32 v[106:107], v[106:107], v[136:137]
	v_cvt_pk_bf16_f32 v131, v112, v113
	v_cvt_pk_bf16_f32 v132, v110, v111
	v_cvt_pk_bf16_f32 v133, v106, v107
	global_store_dwordx4 v[128:129], v[130:133], off sc1
.LBB0_920:
	s_or_b64 exec, exec, s[0:1]
	s_nop 0
	v_lshlrev_b32_e32 v130, 16, v26
	v_and_b32_e32 v131, 0xffff0000, v26
	v_lshlrev_b32_e32 v136, 16, v27
	v_and_b32_e32 v137, 0xffff0000, v27
	v_lshlrev_b32_e32 v134, 16, v28
	v_and_b32_e32 v135, 0xffff0000, v28
	v_lshlrev_b32_e32 v132, 16, v29
	v_and_b32_e32 v133, 0xffff0000, v29
	s_and_saveexec_b64 s[0:1], s[6:7]
	s_cbranch_execz .LBB0_922
	s_waitcnt vmcnt(2)
	v_cvt_f32_f16_sdwa v139, v50 dst_sel:DWORD dst_unused:UNUSED_PAD src0_sel:WORD_1
	v_cvt_f32_f16_e32 v138, v50
	s_waitcnt vmcnt(1)
	v_cvt_f32_f16_sdwa v147, v58 dst_sel:DWORD dst_unused:UNUSED_PAD src0_sel:WORD_1
	v_cvt_f32_f16_e32 v146, v58
	s_waitcnt vmcnt(0)
	v_cvt_f32_f16_sdwa v149, v66 dst_sel:DWORD dst_unused:UNUSED_PAD src0_sel:WORD_1
	v_cvt_f32_f16_e32 v148, v66
	v_cvt_f32_f16_sdwa v151, v51 dst_sel:DWORD dst_unused:UNUSED_PAD src0_sel:WORD_1
	v_cvt_f32_f16_e32 v150, v51
	v_pk_add_f32 v[130:131], v[130:131], v[138:139]
	v_cvt_f32_f16_sdwa v139, v59 dst_sel:DWORD dst_unused:UNUSED_PAD src0_sel:WORD_1
	v_cvt_f32_f16_e32 v138, v59
	v_pk_add_f32 v[130:131], v[130:131], v[146:147]
	v_cvt_f32_f16_sdwa v147, v67 dst_sel:DWORD dst_unused:UNUSED_PAD src0_sel:WORD_1
	v_cvt_f32_f16_e32 v146, v67
	v_pk_add_f32 v[130:131], v[130:131], v[148:149]
	v_cvt_f32_f16_sdwa v149, v52 dst_sel:DWORD dst_unused:UNUSED_PAD src0_sel:WORD_1
	v_cvt_f32_f16_e32 v148, v52
	v_pk_add_f32 v[136:137], v[136:137], v[150:151]
	v_cvt_f32_f16_sdwa v151, v60 dst_sel:DWORD dst_unused:UNUSED_PAD src0_sel:WORD_1
	v_cvt_f32_f16_e32 v150, v60
	v_pk_add_f32 v[136:137], v[136:137], v[138:139]
	v_pk_add_f32 v[134:135], v[134:135], v[148:149]
	v_pk_add_f32 v[136:137], v[136:137], v[146:147]
	v_cvt_f32_f16_sdwa v147, v53 dst_sel:DWORD dst_unused:UNUSED_PAD src0_sel:WORD_1
	v_cvt_f32_f16_e32 v146, v53
	v_cvt_f32_f16_sdwa v149, v61 dst_sel:DWORD dst_unused:UNUSED_PAD src0_sel:WORD_1
	v_cvt_f32_f16_e32 v148, v61
	v_pk_add_f32 v[134:135], v[134:135], v[150:151]
	v_cvt_f32_f16_sdwa v139, v68 dst_sel:DWORD dst_unused:UNUSED_PAD src0_sel:WORD_1
	v_cvt_f32_f16_e32 v138, v68
	v_cvt_f32_f16_sdwa v151, v69 dst_sel:DWORD dst_unused:UNUSED_PAD src0_sel:WORD_1
	v_cvt_f32_f16_e32 v150, v69
	v_pk_add_f32 v[132:133], v[132:133], v[146:147]
	v_pk_add_f32 v[134:135], v[134:135], v[138:139]
	v_pk_add_f32 v[132:133], v[132:133], v[148:149]
	v_cvt_pk_bf16_f32 v146, v130, v131
	v_pk_add_f32 v[132:133], v[132:133], v[150:151]
	v_cvt_pk_bf16_f32 v147, v136, v137
	v_cvt_pk_bf16_f32 v148, v134, v135
	v_cvt_pk_bf16_f32 v149, v132, v133
	global_store_dwordx4 v[128:129], v[146:149], off offset:1024 sc1
.LBB0_922:
	s_or_b64 exec, exec, s[0:1]
	v_mul_f32_e32 v114, v109, v109
	v_mul_f32_e32 v128, v113, v113
	v_fmac_f32_e32 v114, v108, v108
	v_fmac_f32_e32 v128, v112, v112
	v_add_f32_e32 v114, v114, v128
	v_mul_f32_e32 v128, v111, v111
	v_mul_f32_e32 v129, v107, v107
	v_fmac_f32_e32 v128, v110, v110
	v_fmac_f32_e32 v129, v106, v106
	v_add_f32_e32 v128, v128, v129
	v_mov_b32_e32 v138, v135
	v_mov_b32_e32 v139, v131
	v_add_f32_e32 v114, v128, v114
	v_mov_b32_e32 v128, v134
	v_mov_b32_e32 v129, v130
	v_pk_mul_f32 v[138:139], v[138:139], v[138:139]
	v_mov_b32_e32 v146, v133
	v_mov_b32_e32 v147, v137
	v_pk_fma_f32 v[128:129], v[128:129], v[128:129], v[138:139]
	v_mov_b32_e32 v138, v132
	v_mov_b32_e32 v139, v136
	v_pk_mul_f32 v[146:147], v[146:147], v[146:147]
	s_lshl_b64 s[0:1], s[64:65], 11
	v_pk_fma_f32 v[138:139], v[138:139], v[138:139], v[146:147]
	s_nop 0
	v_pk_add_f32 v[128:129], v[128:129], v[138:139]
	s_nop 0
	v_add_f32_e32 v114, v114, v129
	v_add_f32_e32 v114, v128, v114
	ds_bpermute_b32 v128, v117, v114
	s_waitcnt lgkmcnt(0)
	v_add_f32_e32 v114, v114, v128
	ds_bpermute_b32 v128, v140, v114
	s_waitcnt lgkmcnt(0)
	v_add_f32_e32 v114, v114, v128
	ds_bpermute_b32 v128, v141, v114
	s_waitcnt lgkmcnt(0)
	v_add_f32_e32 v114, v114, v128
	ds_bpermute_b32 v128, v142, v114
	s_waitcnt lgkmcnt(0)
	v_add_f32_e32 v114, v114, v128
	ds_bpermute_b32 v128, v143, v114
	s_waitcnt lgkmcnt(0)
	v_add_f32_e32 v114, v114, v128
	ds_bpermute_b32 v128, v144, v114
	s_waitcnt lgkmcnt(0)
	v_add_f32_e32 v114, v114, v128
	v_fmamk_f32 v114, v114, 0x3a800000, v145
	v_mul_f32_e32 v128, 0x4b800000, v114
	v_cmp_gt_f32_e32 vcc, s62, v114
	s_nop 1
	v_cndmask_b32_e32 v114, v114, v128, vcc
	v_rsq_f32_e32 v114, v114
	v_lshl_add_u64 v[128:129], v[122:123], 0, s[0:1]
	v_mul_f32_e32 v138, 0x45800000, v114
	v_cndmask_b32_e32 v114, v114, v138, vcc
	v_pk_mul_f32 v[108:109], v[114:115], v[108:109] op_sel_hi:[0,1]
	v_pk_mul_f32 v[112:113], v[114:115], v[112:113] op_sel_hi:[0,1]
	v_pk_mul_f32 v[110:111], v[114:115], v[110:111] op_sel_hi:[0,1]
	v_pk_mul_f32 v[106:107], v[114:115], v[106:107] op_sel_hi:[0,1]
	s_waitcnt vmcnt(3)
	v_pk_fma_f32 v[112:113], v[96:97], v[112:113], v[76:77]
	v_pk_fma_f32 v[108:109], v[94:95], v[108:109], v[74:75]
	s_waitcnt vmcnt(1)
	v_pk_fma_f32 v[138:139], v[92:93], v[106:107], v[84:85]
	v_pk_fma_f32 v[110:111], v[90:91], v[110:111], v[82:83]
	v_cvt_pk_bf16_f32 v106, v108, v109
	v_cvt_pk_bf16_f32 v107, v112, v113
	v_cvt_pk_bf16_f32 v108, v110, v111
	v_cvt_pk_bf16_f32 v109, v138, v139
	global_store_dwordx4 v[128:129], v[106:109], off sc1
	v_pk_mul_f32 v[110:111], v[114:115], v[134:135] op_sel_hi:[0,1]
	v_pk_mul_f32 v[112:113], v[114:115], v[132:133] op_sel_hi:[0,1]
	v_pk_mul_f32 v[106:107], v[114:115], v[130:131] op_sel_hi:[0,1]
	v_pk_mul_f32 v[108:109], v[114:115], v[136:137] op_sel_hi:[0,1]
	s_waitcnt vmcnt(1)
	v_pk_fma_f32 v[108:109], v[100:101], v[108:109], v[88:89]
	v_pk_fma_f32 v[106:107], v[98:99], v[106:107], v[86:87]
	v_pk_fma_f32 v[112:113], v[104:105], v[112:113], v[80:81]
	v_pk_fma_f32 v[110:111], v[102:103], v[110:111], v[78:79]
	v_cvt_pk_bf16_f32 v106, v106, v107
	v_cvt_pk_bf16_f32 v107, v108, v109
	v_cvt_pk_bf16_f32 v108, v110, v111
	v_cvt_pk_bf16_f32 v109, v112, v113
	global_store_dwordx4 v[128:129], v[106:109], off offset:1024 sc1

.LBB0_931:
	s_or_b64 exec, exec, s[0:1]
	s_ashr_i32 s49, s48, 31
	s_lshl_b64 s[0:1], s[48:49], 12
	s_add_u32 s0, s54, s0
	s_addc_u32 s1, s55, s1
	s_add_i32 s2, s15, 0xc00
	s_and_b32 s2, s2, 0x400
	s_lshl_b32 s2, s2, 1
	s_add_u32 s0, s0, s2
	s_addc_u32 s1, s1, 0
	v_lshlrev_b32_e32 v114, 1, v116
	v_lshl_add_u64 v[128:129], s[0:1], 0, v[114:115]
	v_lshlrev_b32_e32 v108, 16, v38
	v_and_b32_e32 v109, 0xffff0000, v38
	v_lshlrev_b32_e32 v112, 16, v39
	v_and_b32_e32 v113, 0xffff0000, v39
	v_lshlrev_b32_e32 v110, 16, v40
	v_and_b32_e32 v111, 0xffff0000, v40
	v_lshlrev_b32_e32 v106, 16, v41
	v_and_b32_e32 v107, 0xffff0000, v41
	s_and_saveexec_b64 s[0:1], s[8:9]
	s_cbranch_execz .LBB0_933
	s_waitcnt vmcnt(2)
	v_cvt_f32_f16_sdwa v131, v54 dst_sel:DWORD dst_unused:UNUSED_PAD src0_sel:WORD_1
	v_cvt_f32_f16_e32 v130, v54
	s_waitcnt vmcnt(1)
	v_cvt_f32_f16_sdwa v133, v62 dst_sel:DWORD dst_unused:UNUSED_PAD src0_sel:WORD_1
	v_cvt_f32_f16_e32 v132, v62
	s_waitcnt vmcnt(0)
	v_cvt_f32_f16_sdwa v135, v70 dst_sel:DWORD dst_unused:UNUSED_PAD src0_sel:WORD_1
	v_cvt_f32_f16_e32 v134, v70
	v_cvt_f32_f16_sdwa v137, v55 dst_sel:DWORD dst_unused:UNUSED_PAD src0_sel:WORD_1
	v_cvt_f32_f16_e32 v136, v55
	v_pk_add_f32 v[108:109], v[108:109], v[130:131]
	v_cvt_f32_f16_sdwa v131, v63 dst_sel:DWORD dst_unused:UNUSED_PAD src0_sel:WORD_1
	v_cvt_f32_f16_e32 v130, v63
	v_pk_add_f32 v[108:109], v[108:109], v[132:133]
	v_cvt_f32_f16_sdwa v133, v71 dst_sel:DWORD dst_unused:UNUSED_PAD src0_sel:WORD_1
	v_cvt_f32_f16_e32 v132, v71
	v_pk_add_f32 v[108:109], v[108:109], v[134:135]
	v_cvt_f32_f16_sdwa v135, v56 dst_sel:DWORD dst_unused:UNUSED_PAD src0_sel:WORD_1
	v_cvt_f32_f16_e32 v134, v56
	v_pk_add_f32 v[112:113], v[112:113], v[136:137]
	v_cvt_f32_f16_sdwa v137, v64 dst_sel:DWORD dst_unused:UNUSED_PAD src0_sel:WORD_1
	v_cvt_f32_f16_e32 v136, v64
	v_pk_add_f32 v[112:113], v[112:113], v[130:131]
	v_pk_add_f32 v[110:111], v[110:111], v[134:135]
	v_pk_add_f32 v[112:113], v[112:113], v[132:133]
	v_cvt_f32_f16_sdwa v133, v57 dst_sel:DWORD dst_unused:UNUSED_PAD src0_sel:WORD_1
	v_cvt_f32_f16_e32 v132, v57
	v_cvt_f32_f16_sdwa v135, v65 dst_sel:DWORD dst_unused:UNUSED_PAD src0_sel:WORD_1
	v_cvt_f32_f16_e32 v134, v65
	v_pk_add_f32 v[110:111], v[110:111], v[136:137]
	v_cvt_f32_f16_sdwa v131, v72 dst_sel:DWORD dst_unused:UNUSED_PAD src0_sel:WORD_1
	v_cvt_f32_f16_e32 v130, v72
	v_cvt_f32_f16_sdwa v137, v73 dst_sel:DWORD dst_unused:UNUSED_PAD src0_sel:WORD_1
	v_cvt_f32_f16_e32 v136, v73
	v_pk_add_f32 v[106:107], v[106:107], v[132:133]
	v_pk_add_f32 v[110:111], v[110:111], v[130:131]
	v_pk_add_f32 v[106:107], v[106:107], v[134:135]
	v_cvt_pk_bf16_f32 v130, v108, v109
	v_pk_add_f32 v[106:107], v[106:107], v[136:137]
	v_cvt_pk_bf16_f32 v131, v112, v113
	v_cvt_pk_bf16_f32 v132, v110, v111
	v_cvt_pk_bf16_f32 v133, v106, v107
	global_store_dwordx4 v[128:129], v[130:133], off sc1
.LBB0_933:
	s_or_b64 exec, exec, s[0:1]
	s_nop 0
	v_lshlrev_b32_e32 v130, 16, v34
	v_and_b32_e32 v131, 0xffff0000, v34
	v_lshlrev_b32_e32 v136, 16, v35
	v_and_b32_e32 v137, 0xffff0000, v35
	v_lshlrev_b32_e32 v134, 16, v36
	v_and_b32_e32 v135, 0xffff0000, v36
	v_lshlrev_b32_e32 v132, 16, v37
	v_and_b32_e32 v133, 0xffff0000, v37
	s_and_saveexec_b64 s[0:1], s[6:7]
	s_cbranch_execz .LBB0_935
	s_waitcnt vmcnt(2)
	v_cvt_f32_f16_sdwa v139, v50 dst_sel:DWORD dst_unused:UNUSED_PAD src0_sel:WORD_1
	v_cvt_f32_f16_e32 v138, v50
	s_waitcnt vmcnt(1)
	v_cvt_f32_f16_sdwa v147, v58 dst_sel:DWORD dst_unused:UNUSED_PAD src0_sel:WORD_1
	v_cvt_f32_f16_e32 v146, v58
	s_waitcnt vmcnt(0)
	v_cvt_f32_f16_sdwa v149, v66 dst_sel:DWORD dst_unused:UNUSED_PAD src0_sel:WORD_1
	v_cvt_f32_f16_e32 v148, v66
	v_cvt_f32_f16_sdwa v151, v51 dst_sel:DWORD dst_unused:UNUSED_PAD src0_sel:WORD_1
	v_cvt_f32_f16_e32 v150, v51
	v_pk_add_f32 v[130:131], v[130:131], v[138:139]
	v_cvt_f32_f16_sdwa v139, v59 dst_sel:DWORD dst_unused:UNUSED_PAD src0_sel:WORD_1
	v_cvt_f32_f16_e32 v138, v59
	v_pk_add_f32 v[130:131], v[130:131], v[146:147]
	v_cvt_f32_f16_sdwa v147, v67 dst_sel:DWORD dst_unused:UNUSED_PAD src0_sel:WORD_1
	v_cvt_f32_f16_e32 v146, v67
	v_pk_add_f32 v[130:131], v[130:131], v[148:149]
	v_cvt_f32_f16_sdwa v149, v52 dst_sel:DWORD dst_unused:UNUSED_PAD src0_sel:WORD_1
	v_cvt_f32_f16_e32 v148, v52
	v_pk_add_f32 v[136:137], v[136:137], v[150:151]
	v_cvt_f32_f16_sdwa v151, v60 dst_sel:DWORD dst_unused:UNUSED_PAD src0_sel:WORD_1
	v_cvt_f32_f16_e32 v150, v60
	v_pk_add_f32 v[136:137], v[136:137], v[138:139]
	v_pk_add_f32 v[134:135], v[134:135], v[148:149]
	v_pk_add_f32 v[136:137], v[136:137], v[146:147]
	v_cvt_f32_f16_sdwa v147, v53 dst_sel:DWORD dst_unused:UNUSED_PAD src0_sel:WORD_1
	v_cvt_f32_f16_e32 v146, v53
	v_cvt_f32_f16_sdwa v149, v61 dst_sel:DWORD dst_unused:UNUSED_PAD src0_sel:WORD_1
	v_cvt_f32_f16_e32 v148, v61
	v_pk_add_f32 v[134:135], v[134:135], v[150:151]
	v_cvt_f32_f16_sdwa v139, v68 dst_sel:DWORD dst_unused:UNUSED_PAD src0_sel:WORD_1
	v_cvt_f32_f16_e32 v138, v68
	v_cvt_f32_f16_sdwa v151, v69 dst_sel:DWORD dst_unused:UNUSED_PAD src0_sel:WORD_1
	v_cvt_f32_f16_e32 v150, v69
	v_pk_add_f32 v[132:133], v[132:133], v[146:147]
	v_pk_add_f32 v[134:135], v[134:135], v[138:139]
	v_pk_add_f32 v[132:133], v[132:133], v[148:149]
	v_cvt_pk_bf16_f32 v146, v130, v131
	v_pk_add_f32 v[132:133], v[132:133], v[150:151]
	v_cvt_pk_bf16_f32 v147, v136, v137
	v_cvt_pk_bf16_f32 v148, v134, v135
	v_cvt_pk_bf16_f32 v149, v132, v133
	global_store_dwordx4 v[128:129], v[146:149], off offset:1024 sc1
.LBB0_935:
	s_or_b64 exec, exec, s[0:1]
	v_mul_f32_e32 v114, v109, v109
	v_mul_f32_e32 v128, v113, v113
	v_fmac_f32_e32 v114, v108, v108
	v_fmac_f32_e32 v128, v112, v112
	v_add_f32_e32 v114, v114, v128
	v_mul_f32_e32 v128, v111, v111
	v_mul_f32_e32 v129, v107, v107
	v_fmac_f32_e32 v128, v110, v110
	v_fmac_f32_e32 v129, v106, v106
	v_add_f32_e32 v128, v128, v129
	v_mov_b32_e32 v138, v135
	v_mov_b32_e32 v139, v131
	v_add_f32_e32 v114, v128, v114
	v_mov_b32_e32 v128, v134
	v_mov_b32_e32 v129, v130
	v_pk_mul_f32 v[138:139], v[138:139], v[138:139]
	v_mov_b32_e32 v146, v133
	v_mov_b32_e32 v147, v137
	v_pk_fma_f32 v[128:129], v[128:129], v[128:129], v[138:139]
	v_mov_b32_e32 v138, v132
	v_mov_b32_e32 v139, v136
	v_pk_mul_f32 v[146:147], v[146:147], v[146:147]
	s_lshl_b64 s[0:1], s[48:49], 11
	v_pk_fma_f32 v[138:139], v[138:139], v[138:139], v[146:147]
	s_nop 0
	v_pk_add_f32 v[128:129], v[128:129], v[138:139]
	s_nop 0
	v_add_f32_e32 v114, v114, v129
	v_add_f32_e32 v114, v128, v114
	ds_bpermute_b32 v128, v117, v114
	s_waitcnt lgkmcnt(0)
	v_add_f32_e32 v114, v114, v128
	ds_bpermute_b32 v128, v140, v114
	s_waitcnt lgkmcnt(0)
	v_add_f32_e32 v114, v114, v128
	ds_bpermute_b32 v128, v141, v114
	s_waitcnt lgkmcnt(0)
	v_add_f32_e32 v114, v114, v128
	ds_bpermute_b32 v128, v142, v114
	s_waitcnt lgkmcnt(0)
	v_add_f32_e32 v114, v114, v128
	ds_bpermute_b32 v128, v143, v114
	s_waitcnt lgkmcnt(0)
	v_add_f32_e32 v114, v114, v128
	ds_bpermute_b32 v128, v144, v114
	s_waitcnt lgkmcnt(0)
	v_add_f32_e32 v114, v114, v128
	v_fmamk_f32 v114, v114, 0x3a800000, v145
	v_mul_f32_e32 v128, 0x4b800000, v114
	v_cmp_gt_f32_e32 vcc, s62, v114
	s_nop 1
	v_cndmask_b32_e32 v114, v114, v128, vcc
	v_rsq_f32_e32 v114, v114
	v_lshl_add_u64 v[128:129], v[122:123], 0, s[0:1]
	v_mul_f32_e32 v138, 0x45800000, v114
	v_cndmask_b32_e32 v114, v114, v138, vcc
	v_pk_mul_f32 v[108:109], v[114:115], v[108:109] op_sel_hi:[0,1]
	v_pk_mul_f32 v[112:113], v[114:115], v[112:113] op_sel_hi:[0,1]
	v_pk_mul_f32 v[110:111], v[114:115], v[110:111] op_sel_hi:[0,1]
	v_pk_mul_f32 v[106:107], v[114:115], v[106:107] op_sel_hi:[0,1]
	s_waitcnt vmcnt(3)
	v_pk_fma_f32 v[112:113], v[96:97], v[112:113], v[76:77]
	v_pk_fma_f32 v[108:109], v[94:95], v[108:109], v[74:75]
	s_waitcnt vmcnt(1)
	v_pk_fma_f32 v[138:139], v[92:93], v[106:107], v[84:85]
	v_pk_fma_f32 v[110:111], v[90:91], v[110:111], v[82:83]
	v_cvt_pk_bf16_f32 v106, v108, v109
	v_cvt_pk_bf16_f32 v107, v112, v113
	v_cvt_pk_bf16_f32 v108, v110, v111
	v_cvt_pk_bf16_f32 v109, v138, v139
	global_store_dwordx4 v[128:129], v[106:109], off sc1
	v_pk_mul_f32 v[110:111], v[114:115], v[134:135] op_sel_hi:[0,1]
	v_pk_mul_f32 v[112:113], v[114:115], v[132:133] op_sel_hi:[0,1]
	v_pk_mul_f32 v[106:107], v[114:115], v[130:131] op_sel_hi:[0,1]
	v_pk_mul_f32 v[108:109], v[114:115], v[136:137] op_sel_hi:[0,1]
	s_waitcnt vmcnt(1)
	v_pk_fma_f32 v[108:109], v[100:101], v[108:109], v[88:89]
	v_pk_fma_f32 v[106:107], v[98:99], v[106:107], v[86:87]
	v_pk_fma_f32 v[112:113], v[104:105], v[112:113], v[80:81]
	v_pk_fma_f32 v[110:111], v[102:103], v[110:111], v[78:79]
	v_cvt_pk_bf16_f32 v106, v106, v107
	v_cvt_pk_bf16_f32 v107, v108, v109
	v_cvt_pk_bf16_f32 v108, v110, v111
	v_cvt_pk_bf16_f32 v109, v112, v113
	global_store_dwordx4 v[128:129], v[106:109], off offset:1024 sc1

.LBB0_944:
	s_or_b64 exec, exec, s[0:1]
	s_ashr_i32 s45, s44, 31
	s_lshl_b64 s[0:1], s[44:45], 12
	s_add_u32 s0, s54, s0
	s_addc_u32 s1, s55, s1
	s_lshl_b32 s2, s70, 1
	s_add_u32 s0, s0, s2
	s_addc_u32 s1, s1, 0
	v_lshlrev_b32_e32 v114, 1, v116
	v_lshl_add_u64 v[128:129], s[0:1], 0, v[114:115]
	v_lshlrev_b32_e32 v108, 16, v22
	v_and_b32_e32 v109, 0xffff0000, v22
	v_lshlrev_b32_e32 v112, 16, v23
	v_and_b32_e32 v113, 0xffff0000, v23
	v_lshlrev_b32_e32 v110, 16, v24
	v_and_b32_e32 v111, 0xffff0000, v24
	v_lshlrev_b32_e32 v106, 16, v25
	v_and_b32_e32 v107, 0xffff0000, v25
	s_and_saveexec_b64 s[0:1], s[6:7]
	s_cbranch_execz .LBB0_946
	s_waitcnt vmcnt(2)
	v_cvt_f32_f16_sdwa v131, v54 dst_sel:DWORD dst_unused:UNUSED_PAD src0_sel:WORD_1
	v_cvt_f32_f16_e32 v130, v54
	s_waitcnt vmcnt(1)
	v_cvt_f32_f16_sdwa v133, v62 dst_sel:DWORD dst_unused:UNUSED_PAD src0_sel:WORD_1
	v_cvt_f32_f16_e32 v132, v62
	s_waitcnt vmcnt(0)
	v_cvt_f32_f16_sdwa v135, v70 dst_sel:DWORD dst_unused:UNUSED_PAD src0_sel:WORD_1
	v_cvt_f32_f16_e32 v134, v70
	v_cvt_f32_f16_sdwa v137, v55 dst_sel:DWORD dst_unused:UNUSED_PAD src0_sel:WORD_1
	v_cvt_f32_f16_e32 v136, v55
	v_pk_add_f32 v[108:109], v[108:109], v[130:131]
	v_cvt_f32_f16_sdwa v131, v63 dst_sel:DWORD dst_unused:UNUSED_PAD src0_sel:WORD_1
	v_cvt_f32_f16_e32 v130, v63
	v_pk_add_f32 v[108:109], v[108:109], v[132:133]
	v_cvt_f32_f16_sdwa v133, v71 dst_sel:DWORD dst_unused:UNUSED_PAD src0_sel:WORD_1
	v_cvt_f32_f16_e32 v132, v71
	v_pk_add_f32 v[108:109], v[108:109], v[134:135]
	v_cvt_f32_f16_sdwa v135, v56 dst_sel:DWORD dst_unused:UNUSED_PAD src0_sel:WORD_1
	v_cvt_f32_f16_e32 v134, v56
	v_pk_add_f32 v[112:113], v[112:113], v[136:137]
	v_cvt_f32_f16_sdwa v137, v64 dst_sel:DWORD dst_unused:UNUSED_PAD src0_sel:WORD_1
	v_cvt_f32_f16_e32 v136, v64
	v_pk_add_f32 v[112:113], v[112:113], v[130:131]
	v_pk_add_f32 v[110:111], v[110:111], v[134:135]
	v_pk_add_f32 v[112:113], v[112:113], v[132:133]
	v_cvt_f32_f16_sdwa v133, v57 dst_sel:DWORD dst_unused:UNUSED_PAD src0_sel:WORD_1
	v_cvt_f32_f16_e32 v132, v57
	v_cvt_f32_f16_sdwa v135, v65 dst_sel:DWORD dst_unused:UNUSED_PAD src0_sel:WORD_1
	v_cvt_f32_f16_e32 v134, v65
	v_pk_add_f32 v[110:111], v[110:111], v[136:137]
	v_cvt_f32_f16_sdwa v131, v72 dst_sel:DWORD dst_unused:UNUSED_PAD src0_sel:WORD_1
	v_cvt_f32_f16_e32 v130, v72
	v_cvt_f32_f16_sdwa v137, v73 dst_sel:DWORD dst_unused:UNUSED_PAD src0_sel:WORD_1
	v_cvt_f32_f16_e32 v136, v73
	v_pk_add_f32 v[106:107], v[106:107], v[132:133]
	v_pk_add_f32 v[110:111], v[110:111], v[130:131]
	v_pk_add_f32 v[106:107], v[106:107], v[134:135]
	v_cvt_pk_bf16_f32 v130, v108, v109
	v_pk_add_f32 v[106:107], v[106:107], v[136:137]
	v_cvt_pk_bf16_f32 v131, v112, v113
	v_cvt_pk_bf16_f32 v132, v110, v111
	v_cvt_pk_bf16_f32 v133, v106, v107
	global_store_dwordx4 v[128:129], v[130:133], off sc1
.LBB0_946:
	s_or_b64 exec, exec, s[0:1]
	s_nop 0
	v_lshlrev_b32_e32 v130, 16, v18
	v_and_b32_e32 v131, 0xffff0000, v18
	v_lshlrev_b32_e32 v136, 16, v19
	v_and_b32_e32 v137, 0xffff0000, v19
	v_lshlrev_b32_e32 v134, 16, v20
	v_and_b32_e32 v135, 0xffff0000, v20
	v_lshlrev_b32_e32 v132, 16, v21
	v_and_b32_e32 v133, 0xffff0000, v21
	s_and_saveexec_b64 s[0:1], s[4:5]
	s_cbranch_execz .LBB0_878
	s_waitcnt vmcnt(2)
	v_cvt_f32_f16_sdwa v139, v50 dst_sel:DWORD dst_unused:UNUSED_PAD src0_sel:WORD_1
	v_cvt_f32_f16_e32 v138, v50
	s_waitcnt vmcnt(1)
	v_cvt_f32_f16_sdwa v147, v58 dst_sel:DWORD dst_unused:UNUSED_PAD src0_sel:WORD_1
	v_cvt_f32_f16_e32 v146, v58
	s_waitcnt vmcnt(0)
	v_cvt_f32_f16_sdwa v149, v66 dst_sel:DWORD dst_unused:UNUSED_PAD src0_sel:WORD_1
	v_cvt_f32_f16_e32 v148, v66
	v_cvt_f32_f16_sdwa v151, v51 dst_sel:DWORD dst_unused:UNUSED_PAD src0_sel:WORD_1
	v_cvt_f32_f16_e32 v150, v51
	v_pk_add_f32 v[130:131], v[130:131], v[138:139]
	v_cvt_f32_f16_sdwa v139, v59 dst_sel:DWORD dst_unused:UNUSED_PAD src0_sel:WORD_1
	v_cvt_f32_f16_e32 v138, v59
	v_pk_add_f32 v[130:131], v[130:131], v[146:147]
	v_cvt_f32_f16_sdwa v147, v67 dst_sel:DWORD dst_unused:UNUSED_PAD src0_sel:WORD_1
	v_cvt_f32_f16_e32 v146, v67
	v_pk_add_f32 v[130:131], v[130:131], v[148:149]
	v_cvt_f32_f16_sdwa v149, v52 dst_sel:DWORD dst_unused:UNUSED_PAD src0_sel:WORD_1
	v_cvt_f32_f16_e32 v148, v52
	v_pk_add_f32 v[136:137], v[136:137], v[150:151]
	v_cvt_f32_f16_sdwa v151, v60 dst_sel:DWORD dst_unused:UNUSED_PAD src0_sel:WORD_1
	v_cvt_f32_f16_e32 v150, v60
	v_pk_add_f32 v[136:137], v[136:137], v[138:139]
	v_pk_add_f32 v[134:135], v[134:135], v[148:149]
	v_pk_add_f32 v[136:137], v[136:137], v[146:147]
	v_cvt_f32_f16_sdwa v147, v53 dst_sel:DWORD dst_unused:UNUSED_PAD src0_sel:WORD_1
	v_cvt_f32_f16_e32 v146, v53
	v_cvt_f32_f16_sdwa v149, v61 dst_sel:DWORD dst_unused:UNUSED_PAD src0_sel:WORD_1
	v_cvt_f32_f16_e32 v148, v61
	v_pk_add_f32 v[134:135], v[134:135], v[150:151]
	v_cvt_f32_f16_sdwa v139, v68 dst_sel:DWORD dst_unused:UNUSED_PAD src0_sel:WORD_1
	v_cvt_f32_f16_e32 v138, v68
	v_cvt_f32_f16_sdwa v151, v69 dst_sel:DWORD dst_unused:UNUSED_PAD src0_sel:WORD_1
	v_cvt_f32_f16_e32 v150, v69
	v_pk_add_f32 v[132:133], v[132:133], v[146:147]
	v_pk_add_f32 v[134:135], v[134:135], v[138:139]
	v_pk_add_f32 v[132:133], v[132:133], v[148:149]
	v_cvt_pk_bf16_f32 v146, v130, v131
	v_pk_add_f32 v[132:133], v[132:133], v[150:151]
	v_cvt_pk_bf16_f32 v147, v136, v137
	v_cvt_pk_bf16_f32 v148, v134, v135
	v_cvt_pk_bf16_f32 v149, v132, v133
	global_store_dwordx4 v[128:129], v[146:149], off offset:1024 sc1
	s_branch .LBB0_878

.LBB0_1485:
	s_or_b64 exec, exec, s[0:1]
	v_mul_f32_e32 v114, v109, v109
	v_mul_f32_e32 v128, v113, v113
	v_fmac_f32_e32 v114, v108, v108
	v_fmac_f32_e32 v128, v112, v112
	v_add_f32_e32 v114, v114, v128
	v_mul_f32_e32 v128, v111, v111
	v_mul_f32_e32 v129, v107, v107
	v_fmac_f32_e32 v128, v110, v110
	v_fmac_f32_e32 v129, v106, v106
	v_add_f32_e32 v128, v128, v129
	v_mov_b32_e32 v138, v135
	v_mov_b32_e32 v139, v131
	v_add_f32_e32 v114, v128, v114
	v_mov_b32_e32 v128, v134
	v_mov_b32_e32 v129, v130
	v_pk_mul_f32 v[138:139], v[138:139], v[138:139]
	v_mov_b32_e32 v146, v133
	v_mov_b32_e32 v147, v137
	v_pk_fma_f32 v[128:129], v[128:129], v[128:129], v[138:139]
	v_mov_b32_e32 v138, v132
	v_mov_b32_e32 v139, v136
	v_pk_mul_f32 v[146:147], v[146:147], v[146:147]
	s_lshl_b64 s[0:1], s[36:37], 11
	v_pk_fma_f32 v[138:139], v[138:139], v[138:139], v[146:147]
	s_nop 0
	v_pk_add_f32 v[128:129], v[128:129], v[138:139]
	s_nop 0
	v_add_f32_e32 v114, v114, v129
	v_add_f32_e32 v114, v128, v114
	ds_bpermute_b32 v128, v117, v114
	s_waitcnt lgkmcnt(0)
	v_add_f32_e32 v114, v114, v128
	ds_bpermute_b32 v128, v140, v114
	s_waitcnt lgkmcnt(0)
	v_add_f32_e32 v114, v114, v128
	ds_bpermute_b32 v128, v141, v114
	s_waitcnt lgkmcnt(0)
	v_add_f32_e32 v114, v114, v128
	ds_bpermute_b32 v128, v142, v114
	s_waitcnt lgkmcnt(0)
	v_add_f32_e32 v114, v114, v128
	ds_bpermute_b32 v128, v143, v114
	s_waitcnt lgkmcnt(0)
	v_add_f32_e32 v114, v114, v128
	ds_bpermute_b32 v128, v144, v114
	s_waitcnt lgkmcnt(0)
	v_add_f32_e32 v114, v114, v128
	v_fmamk_f32 v114, v114, 0x3a800000, v145
	v_mul_f32_e32 v128, 0x4b800000, v114
	v_cmp_gt_f32_e32 vcc, s50, v114
	s_nop 1
	v_cndmask_b32_e32 v114, v114, v128, vcc
	v_rsq_f32_e32 v114, v114
	v_lshl_add_u64 v[128:129], v[122:123], 0, s[0:1]
	v_mul_f32_e32 v138, 0x45800000, v114
	v_cndmask_b32_e32 v114, v114, v138, vcc
	v_pk_mul_f32 v[108:109], v[114:115], v[108:109] op_sel_hi:[0,1]
	v_pk_mul_f32 v[112:113], v[114:115], v[112:113] op_sel_hi:[0,1]
	v_pk_mul_f32 v[110:111], v[114:115], v[110:111] op_sel_hi:[0,1]
	v_pk_mul_f32 v[106:107], v[114:115], v[106:107] op_sel_hi:[0,1]
	s_waitcnt vmcnt(3)
	v_pk_fma_f32 v[112:113], v[96:97], v[112:113], v[76:77]
	v_pk_fma_f32 v[108:109], v[94:95], v[108:109], v[74:75]
	s_waitcnt vmcnt(1)
	v_pk_fma_f32 v[138:139], v[92:93], v[106:107], v[84:85]
	v_pk_fma_f32 v[110:111], v[90:91], v[110:111], v[82:83]
	v_cvt_pk_bf16_f32 v106, v108, v109
	v_cvt_pk_bf16_f32 v107, v112, v113
	v_cvt_pk_bf16_f32 v108, v110, v111
	v_cvt_pk_bf16_f32 v109, v138, v139
	global_store_dwordx4 v[128:129], v[106:109], off sc1
	v_pk_mul_f32 v[110:111], v[114:115], v[134:135] op_sel_hi:[0,1]
	v_pk_mul_f32 v[112:113], v[114:115], v[132:133] op_sel_hi:[0,1]
	v_pk_mul_f32 v[106:107], v[114:115], v[130:131] op_sel_hi:[0,1]
	v_pk_mul_f32 v[108:109], v[114:115], v[136:137] op_sel_hi:[0,1]
	s_waitcnt vmcnt(1)
	v_pk_fma_f32 v[108:109], v[100:101], v[108:109], v[88:89]
	v_pk_fma_f32 v[106:107], v[98:99], v[106:107], v[86:87]
	v_pk_fma_f32 v[112:113], v[104:105], v[112:113], v[80:81]
	v_pk_fma_f32 v[110:111], v[102:103], v[110:111], v[78:79]
	v_cvt_pk_bf16_f32 v106, v106, v107
	v_cvt_pk_bf16_f32 v107, v108, v109
	v_cvt_pk_bf16_f32 v108, v110, v111
	v_cvt_pk_bf16_f32 v109, v112, v113
	global_store_dwordx4 v[128:129], v[106:109], off offset:1024 sc1

.LBB0_1505:
	s_or_b64 exec, exec, s[0:1]
	v_mul_f32_e32 v108, v131, v131
	v_mul_f32_e32 v109, v135, v135
	v_fmac_f32_e32 v108, v130, v130
	v_fmac_f32_e32 v109, v134, v134
	v_add_f32_e32 v108, v108, v109
	v_mul_f32_e32 v109, v133, v133
	v_mul_f32_e32 v114, v111, v111
	v_fmac_f32_e32 v109, v132, v132
	v_fmac_f32_e32 v114, v110, v110
	v_add_f32_e32 v109, v109, v114
	v_mov_b32_e32 v128, v137
	v_mov_b32_e32 v129, v113
	v_add_f32_e32 v114, v109, v108
	v_mov_b32_e32 v108, v136
	v_mov_b32_e32 v109, v112
	v_pk_mul_f32 v[128:129], v[128:129], v[128:129]
	v_mov_b32_e32 v146, v107
	v_mov_b32_e32 v147, v139
	v_pk_fma_f32 v[108:109], v[108:109], v[108:109], v[128:129]
	v_mov_b32_e32 v128, v106
	v_mov_b32_e32 v129, v138
	v_pk_mul_f32 v[146:147], v[146:147], v[146:147]
	s_nop 0
	v_pk_fma_f32 v[128:129], v[128:129], v[128:129], v[146:147]
	s_nop 0
	v_pk_add_f32 v[108:109], v[108:109], v[128:129]
	s_nop 0
	v_add_f32_e32 v109, v114, v109
	v_add_f32_e32 v108, v108, v109
	ds_bpermute_b32 v109, v117, v108
	s_waitcnt lgkmcnt(0)
	v_add_f32_e32 v108, v108, v109
	ds_bpermute_b32 v109, v140, v108
	s_waitcnt lgkmcnt(0)
	v_add_f32_e32 v108, v108, v109
	ds_bpermute_b32 v109, v141, v108
	s_waitcnt lgkmcnt(0)
	v_add_f32_e32 v108, v108, v109
	ds_bpermute_b32 v109, v142, v108
	s_waitcnt lgkmcnt(0)
	v_add_f32_e32 v108, v108, v109
	ds_bpermute_b32 v109, v143, v108
	s_waitcnt lgkmcnt(0)
	v_add_f32_e32 v108, v108, v109
	ds_bpermute_b32 v109, v144, v108
	s_waitcnt lgkmcnt(0)
	v_add_f32_e32 v108, v108, v109
	v_fmamk_f32 v108, v108, 0x3a800000, v145
	v_mul_f32_e32 v109, 0x4b800000, v108
	v_cmp_gt_f32_e32 vcc, s50, v108
	s_nop 1
	v_cndmask_b32_e32 v108, v108, v109, vcc
	v_rsq_f32_e32 v108, v108
	s_nop 0
	v_mul_f32_e32 v109, 0x45800000, v108
	v_cndmask_b32_e32 v114, v108, v109, vcc
	v_pk_mul_f32 v[108:109], v[114:115], v[130:131] op_sel_hi:[0,1]
	v_pk_mul_f32 v[128:129], v[114:115], v[134:135] op_sel_hi:[0,1]
	v_pk_mul_f32 v[130:131], v[114:115], v[132:133] op_sel_hi:[0,1]
	v_pk_mul_f32 v[110:111], v[114:115], v[110:111] op_sel_hi:[0,1]
	v_pk_fma_f32 v[128:129], v[96:97], v[128:129], v[76:77]
	v_pk_fma_f32 v[108:109], v[94:95], v[108:109], v[74:75]
	v_pk_fma_f32 v[132:133], v[92:93], v[110:111], v[84:85]
	v_pk_fma_f32 v[110:111], v[90:91], v[130:131], v[82:83]
	v_cvt_pk_bf16_f32 v108, v108, v109
	v_cvt_pk_bf16_f32 v109, v128, v129
	v_cvt_pk_bf16_f32 v110, v110, v111
	v_cvt_pk_bf16_f32 v111, v132, v133
	global_store_dwordx4 v[124:125], v[108:111], off sc1
	v_pk_mul_f32 v[106:107], v[114:115], v[106:107] op_sel_hi:[0,1]
	v_pk_fma_f32 v[128:129], v[104:105], v[106:107], v[80:81]
	v_pk_mul_f32 v[110:111], v[114:115], v[138:139] op_sel_hi:[0,1]
	v_pk_mul_f32 v[108:109], v[114:115], v[112:113] op_sel_hi:[0,1]
	v_pk_fma_f32 v[110:111], v[100:101], v[110:111], v[88:89]
	v_pk_mul_f32 v[112:113], v[114:115], v[136:137] op_sel_hi:[0,1]
	v_pk_fma_f32 v[108:109], v[98:99], v[108:109], v[86:87]
	v_pk_fma_f32 v[112:113], v[102:103], v[112:113], v[78:79]
	v_cvt_pk_bf16_f32 v107, v110, v111
	v_cndmask_b32_e64 v110, 0, 1, s[8:9]
	v_cvt_pk_bf16_f32 v106, v108, v109
	v_cvt_pk_bf16_f32 v108, v112, v113
	v_cvt_pk_bf16_f32 v109, v128, v129
	v_cmp_ne_u32_e64 s[4:5], 1, v110
	s_andn2_b64 vcc, exec, s[8:9]
	global_store_dwordx4 v[124:125], v[106:109], off offset:1024 sc1
	s_cbranch_vccnz .LBB0_1517
	s_ashr_i32 s2, s48, 12
	s_cmp_eq_u32 s2, s51
	s_cbranch_scc1 .LBB0_1508
	s_mul_i32 s0, s2, 12
	s_ashr_i32 s1, s0, 31
	s_lshl_b64 s[0:1], s[0:1], 12
	v_lshl_add_u64 v[78:79], v[118:119], 0, s[0:1]
	v_add_co_u32_e32 v76, vcc, 0x6000, v78
	v_lshl_add_u64 v[74:75], v[78:79], 0, s[24:25]
	s_mov_b64 s[0:1], vcc
	v_add_co_u32_e32 v80, vcc, 0x7000, v78
	global_load_dwordx4 v[90:93], v[74:75], off offset:16
	s_nop 0
	v_addc_co_u32_e32 v81, vcc, 0, v79, vcc
	v_lshl_add_u64 v[74:75], v[78:79], 0, s[26:27]
	global_load_dwordx4 v[94:97], v[80:81], off
	global_load_dwordx4 v[98:101], v[80:81], off offset:2048
	global_load_dwordx4 v[102:105], v[74:75], off offset:16
	v_addc_co_u32_e64 v77, vcc, 0, v79, s[0:1]
	v_lshl_add_u64 v[86:87], v[78:79], 0, s[22:23]
	global_load_dwordx4 v[74:77], v[76:77], off
	s_nop 0
	global_load_dwordx4 v[78:81], v[86:87], off offset:2064
	global_load_dwordx4 v[82:85], v[86:87], off offset:16
	s_nop 0
	global_load_dwordx4 v[86:89], v[86:87], off offset:2048
	s_mov_b32 s51, s2
	s_waitcnt vmcnt(7)
	v_pk_add_f32 v[92:93], v[92:93], 1.0 op_sel_hi:[1,0]
	v_pk_add_f32 v[90:91], v[90:91], 1.0 op_sel_hi:[1,0]
	v_pk_mul_f32 v[92:93], v[12:13], v[92:93]
	s_waitcnt vmcnt(6)
	v_pk_add_f32 v[96:97], v[96:97], 1.0 op_sel_hi:[1,0]
	v_pk_add_f32 v[94:95], v[94:95], 1.0 op_sel_hi:[1,0]
	s_waitcnt vmcnt(5)
	v_pk_add_f32 v[100:101], v[100:101], 1.0 op_sel_hi:[1,0]
	v_pk_add_f32 v[98:99], v[98:99], 1.0 op_sel_hi:[1,0]
	s_waitcnt vmcnt(4)
	v_pk_add_f32 v[104:105], v[104:105], 1.0 op_sel_hi:[1,0]
	v_pk_add_f32 v[102:103], v[102:103], 1.0 op_sel_hi:[1,0]
	v_pk_mul_f32 v[90:91], v[10:11], v[90:91]
	v_pk_mul_f32 v[96:97], v[4:5], v[96:97]
	v_pk_mul_f32 v[94:95], v[2:3], v[94:95]
	v_pk_mul_f32 v[100:101], v[16:17], v[100:101]
	v_pk_mul_f32 v[98:99], v[14:15], v[98:99]
	v_pk_mul_f32 v[104:105], v[8:9], v[104:105]
	v_pk_mul_f32 v[102:103], v[6:7], v[102:103]

.LBB0_1512:
	s_or_b64 exec, exec, s[0:1]
	s_ashr_i32 s49, s48, 31
	s_lshl_b64 s[0:1], s[48:49], 12
	s_add_u32 s0, s54, s0
	s_addc_u32 s1, s55, s1
	s_add_i32 s2, s15, 0x400
	s_and_b32 s2, s2, 0x400
	s_lshl_b32 s2, s2, 1
	s_add_u32 s0, s0, s2
	s_addc_u32 s1, s1, 0
	v_lshlrev_b32_e32 v114, 1, v116
	v_lshl_add_u64 v[128:129], s[0:1], 0, v[114:115]
	v_lshlrev_b32_e32 v108, 16, v46
	v_and_b32_e32 v109, 0xffff0000, v46
	v_lshlrev_b32_e32 v112, 16, v47
	v_and_b32_e32 v113, 0xffff0000, v47
	v_lshlrev_b32_e32 v110, 16, v48
	v_and_b32_e32 v111, 0xffff0000, v48
	v_lshlrev_b32_e32 v106, 16, v49
	v_and_b32_e32 v107, 0xffff0000, v49
	s_and_saveexec_b64 s[0:1], s[8:9]
	s_cbranch_execz .LBB0_1514
	s_waitcnt vmcnt(2)
	v_cvt_f32_f16_sdwa v131, v54 dst_sel:DWORD dst_unused:UNUSED_PAD src0_sel:WORD_1
	v_cvt_f32_f16_e32 v130, v54
	s_waitcnt vmcnt(1)
	v_cvt_f32_f16_sdwa v133, v62 dst_sel:DWORD dst_unused:UNUSED_PAD src0_sel:WORD_1
	v_cvt_f32_f16_e32 v132, v62
	s_waitcnt vmcnt(0)
	v_cvt_f32_f16_sdwa v135, v70 dst_sel:DWORD dst_unused:UNUSED_PAD src0_sel:WORD_1
	v_cvt_f32_f16_e32 v134, v70
	v_cvt_f32_f16_sdwa v137, v55 dst_sel:DWORD dst_unused:UNUSED_PAD src0_sel:WORD_1
	v_cvt_f32_f16_e32 v136, v55
	v_pk_add_f32 v[108:109], v[108:109], v[130:131]
	v_cvt_f32_f16_sdwa v131, v63 dst_sel:DWORD dst_unused:UNUSED_PAD src0_sel:WORD_1
	v_cvt_f32_f16_e32 v130, v63
	v_pk_add_f32 v[108:109], v[108:109], v[132:133]
	v_cvt_f32_f16_sdwa v133, v71 dst_sel:DWORD dst_unused:UNUSED_PAD src0_sel:WORD_1
	v_cvt_f32_f16_e32 v132, v71
	v_pk_add_f32 v[108:109], v[108:109], v[134:135]
	v_cvt_f32_f16_sdwa v135, v56 dst_sel:DWORD dst_unused:UNUSED_PAD src0_sel:WORD_1
	v_cvt_f32_f16_e32 v134, v56
	v_pk_add_f32 v[112:113], v[112:113], v[136:137]
	v_cvt_f32_f16_sdwa v137, v64 dst_sel:DWORD dst_unused:UNUSED_PAD src0_sel:WORD_1
	v_cvt_f32_f16_e32 v136, v64
	v_pk_add_f32 v[112:113], v[112:113], v[130:131]
	v_pk_add_f32 v[110:111], v[110:111], v[134:135]
	v_pk_add_f32 v[112:113], v[112:113], v[132:133]
	v_cvt_f32_f16_sdwa v133, v57 dst_sel:DWORD dst_unused:UNUSED_PAD src0_sel:WORD_1
	v_cvt_f32_f16_e32 v132, v57
	v_cvt_f32_f16_sdwa v135, v65 dst_sel:DWORD dst_unused:UNUSED_PAD src0_sel:WORD_1
	v_cvt_f32_f16_e32 v134, v65
	v_pk_add_f32 v[110:111], v[110:111], v[136:137]
	v_cvt_f32_f16_sdwa v131, v72 dst_sel:DWORD dst_unused:UNUSED_PAD src0_sel:WORD_1
	v_cvt_f32_f16_e32 v130, v72
	v_cvt_f32_f16_sdwa v137, v73 dst_sel:DWORD dst_unused:UNUSED_PAD src0_sel:WORD_1
	v_cvt_f32_f16_e32 v136, v73
	v_pk_add_f32 v[106:107], v[106:107], v[132:133]
	v_pk_add_f32 v[110:111], v[110:111], v[130:131]
	v_pk_add_f32 v[106:107], v[106:107], v[134:135]
	v_cvt_pk_bf16_f32 v130, v108, v109
	v_pk_add_f32 v[106:107], v[106:107], v[136:137]
	v_cvt_pk_bf16_f32 v131, v112, v113
	v_cvt_pk_bf16_f32 v132, v110, v111
	v_cvt_pk_bf16_f32 v133, v106, v107
	global_store_dwordx4 v[128:129], v[130:133], off sc1

.LBB0_1516:
	s_or_b64 exec, exec, s[0:1]
	v_mul_f32_e32 v114, v109, v109
	v_mul_f32_e32 v128, v113, v113
	v_fmac_f32_e32 v114, v108, v108
	v_fmac_f32_e32 v128, v112, v112
	v_add_f32_e32 v114, v114, v128
	v_mul_f32_e32 v128, v111, v111
	v_mul_f32_e32 v129, v107, v107
	v_fmac_f32_e32 v128, v110, v110
	v_fmac_f32_e32 v129, v106, v106
	v_add_f32_e32 v128, v128, v129
	v_mov_b32_e32 v138, v135
	v_mov_b32_e32 v139, v131
	v_add_f32_e32 v114, v128, v114
	v_mov_b32_e32 v128, v134
	v_mov_b32_e32 v129, v130
	v_pk_mul_f32 v[138:139], v[138:139], v[138:139]
	v_mov_b32_e32 v146, v133
	v_mov_b32_e32 v147, v137
	v_pk_fma_f32 v[128:129], v[128:129], v[128:129], v[138:139]
	v_mov_b32_e32 v138, v132
	v_mov_b32_e32 v139, v136
	v_pk_mul_f32 v[146:147], v[146:147], v[146:147]
	s_lshl_b64 s[0:1], s[48:49], 11
	v_pk_fma_f32 v[138:139], v[138:139], v[138:139], v[146:147]
	s_nop 0
	v_pk_add_f32 v[128:129], v[128:129], v[138:139]
	s_nop 0
	v_add_f32_e32 v114, v114, v129
	v_add_f32_e32 v114, v128, v114
	ds_bpermute_b32 v128, v117, v114
	s_waitcnt lgkmcnt(0)
	v_add_f32_e32 v114, v114, v128
	ds_bpermute_b32 v128, v140, v114
	s_waitcnt lgkmcnt(0)
	v_add_f32_e32 v114, v114, v128
	ds_bpermute_b32 v128, v141, v114
	s_waitcnt lgkmcnt(0)
	v_add_f32_e32 v114, v114, v128
	ds_bpermute_b32 v128, v142, v114
	s_waitcnt lgkmcnt(0)
	v_add_f32_e32 v114, v114, v128
	ds_bpermute_b32 v128, v143, v114
	s_waitcnt lgkmcnt(0)
	v_add_f32_e32 v114, v114, v128
	ds_bpermute_b32 v128, v144, v114
	s_waitcnt lgkmcnt(0)
	v_add_f32_e32 v114, v114, v128
	v_fmamk_f32 v114, v114, 0x3a800000, v145
	v_mul_f32_e32 v128, 0x4b800000, v114
	v_cmp_gt_f32_e32 vcc, s50, v114
	s_nop 1
	v_cndmask_b32_e32 v114, v114, v128, vcc
	v_rsq_f32_e32 v114, v114
	v_lshl_add_u64 v[128:129], v[122:123], 0, s[0:1]
	v_mul_f32_e32 v138, 0x45800000, v114
	v_cndmask_b32_e32 v114, v114, v138, vcc
	v_pk_mul_f32 v[108:109], v[114:115], v[108:109] op_sel_hi:[0,1]
	v_pk_mul_f32 v[112:113], v[114:115], v[112:113] op_sel_hi:[0,1]
	v_pk_mul_f32 v[110:111], v[114:115], v[110:111] op_sel_hi:[0,1]
	v_pk_mul_f32 v[106:107], v[114:115], v[106:107] op_sel_hi:[0,1]
	s_waitcnt vmcnt(3)
	v_pk_fma_f32 v[112:113], v[96:97], v[112:113], v[76:77]
	v_pk_fma_f32 v[108:109], v[94:95], v[108:109], v[74:75]
	s_waitcnt vmcnt(1)
	v_pk_fma_f32 v[138:139], v[92:93], v[106:107], v[84:85]
	v_pk_fma_f32 v[110:111], v[90:91], v[110:111], v[82:83]
	v_cvt_pk_bf16_f32 v106, v108, v109
	v_cvt_pk_bf16_f32 v107, v112, v113
	v_cvt_pk_bf16_f32 v108, v110, v111
	v_cvt_pk_bf16_f32 v109, v138, v139
	global_store_dwordx4 v[128:129], v[106:109], off sc1
	v_pk_mul_f32 v[110:111], v[114:115], v[134:135] op_sel_hi:[0,1]
	v_pk_mul_f32 v[112:113], v[114:115], v[132:133] op_sel_hi:[0,1]
	v_pk_mul_f32 v[106:107], v[114:115], v[130:131] op_sel_hi:[0,1]
	v_pk_mul_f32 v[108:109], v[114:115], v[136:137] op_sel_hi:[0,1]
	s_waitcnt vmcnt(1)
	v_pk_fma_f32 v[108:109], v[100:101], v[108:109], v[88:89]
	v_pk_fma_f32 v[106:107], v[98:99], v[106:107], v[86:87]
	v_pk_fma_f32 v[112:113], v[104:105], v[112:113], v[80:81]
	v_pk_fma_f32 v[110:111], v[102:103], v[110:111], v[78:79]
	v_cvt_pk_bf16_f32 v106, v106, v107
	v_cvt_pk_bf16_f32 v107, v108, v109
	v_cvt_pk_bf16_f32 v108, v110, v111
	v_cvt_pk_bf16_f32 v109, v112, v113
	global_store_dwordx4 v[128:129], v[106:109], off offset:1024 sc1

.LBB0_1525:
	s_or_b64 exec, exec, s[0:1]
	s_ashr_i32 s45, s44, 31
	s_lshl_b64 s[0:1], s[44:45], 12
	s_add_u32 s0, s54, s0
	s_addc_u32 s1, s55, s1
	s_lshl_b32 s2, s62, 1
	s_add_u32 s0, s0, s2
	s_addc_u32 s1, s1, 0
	v_lshlrev_b32_e32 v114, 1, v116
	v_lshl_add_u64 v[128:129], s[0:1], 0, v[114:115]
	v_lshlrev_b32_e32 v108, 16, v30
	v_and_b32_e32 v109, 0xffff0000, v30
	v_lshlrev_b32_e32 v112, 16, v31
	v_and_b32_e32 v113, 0xffff0000, v31
	v_lshlrev_b32_e32 v110, 16, v32
	v_and_b32_e32 v111, 0xffff0000, v32
	v_lshlrev_b32_e32 v106, 16, v33
	v_and_b32_e32 v107, 0xffff0000, v33
	s_and_saveexec_b64 s[0:1], s[8:9]
	s_cbranch_execz .LBB0_1527
	s_waitcnt vmcnt(2)
	v_cvt_f32_f16_sdwa v131, v54 dst_sel:DWORD dst_unused:UNUSED_PAD src0_sel:WORD_1
	v_cvt_f32_f16_e32 v130, v54
	s_waitcnt vmcnt(1)
	v_cvt_f32_f16_sdwa v133, v62 dst_sel:DWORD dst_unused:UNUSED_PAD src0_sel:WORD_1
	v_cvt_f32_f16_e32 v132, v62
	s_waitcnt vmcnt(0)
	v_cvt_f32_f16_sdwa v135, v70 dst_sel:DWORD dst_unused:UNUSED_PAD src0_sel:WORD_1
	v_cvt_f32_f16_e32 v134, v70
	v_cvt_f32_f16_sdwa v137, v55 dst_sel:DWORD dst_unused:UNUSED_PAD src0_sel:WORD_1
	v_cvt_f32_f16_e32 v136, v55
	v_pk_add_f32 v[108:109], v[108:109], v[130:131]
	v_cvt_f32_f16_sdwa v131, v63 dst_sel:DWORD dst_unused:UNUSED_PAD src0_sel:WORD_1
	v_cvt_f32_f16_e32 v130, v63
	v_pk_add_f32 v[108:109], v[108:109], v[132:133]
	v_cvt_f32_f16_sdwa v133, v71 dst_sel:DWORD dst_unused:UNUSED_PAD src0_sel:WORD_1
	v_cvt_f32_f16_e32 v132, v71
	v_pk_add_f32 v[108:109], v[108:109], v[134:135]
	v_cvt_f32_f16_sdwa v135, v56 dst_sel:DWORD dst_unused:UNUSED_PAD src0_sel:WORD_1
	v_cvt_f32_f16_e32 v134, v56
	v_pk_add_f32 v[112:113], v[112:113], v[136:137]
	v_cvt_f32_f16_sdwa v137, v64 dst_sel:DWORD dst_unused:UNUSED_PAD src0_sel:WORD_1
	v_cvt_f32_f16_e32 v136, v64
	v_pk_add_f32 v[112:113], v[112:113], v[130:131]
	v_pk_add_f32 v[110:111], v[110:111], v[134:135]
	v_pk_add_f32 v[112:113], v[112:113], v[132:133]
	v_cvt_f32_f16_sdwa v133, v57 dst_sel:DWORD dst_unused:UNUSED_PAD src0_sel:WORD_1
	v_cvt_f32_f16_e32 v132, v57
	v_cvt_f32_f16_sdwa v135, v65 dst_sel:DWORD dst_unused:UNUSED_PAD src0_sel:WORD_1
	v_cvt_f32_f16_e32 v134, v65
	v_pk_add_f32 v[110:111], v[110:111], v[136:137]
	v_cvt_f32_f16_sdwa v131, v72 dst_sel:DWORD dst_unused:UNUSED_PAD src0_sel:WORD_1
	v_cvt_f32_f16_e32 v130, v72
	v_cvt_f32_f16_sdwa v137, v73 dst_sel:DWORD dst_unused:UNUSED_PAD src0_sel:WORD_1
	v_cvt_f32_f16_e32 v136, v73
	v_pk_add_f32 v[106:107], v[106:107], v[132:133]
	v_pk_add_f32 v[110:111], v[110:111], v[130:131]
	v_pk_add_f32 v[106:107], v[106:107], v[134:135]
	v_cvt_pk_bf16_f32 v130, v108, v109
	v_pk_add_f32 v[106:107], v[106:107], v[136:137]
	v_cvt_pk_bf16_f32 v131, v112, v113
	v_cvt_pk_bf16_f32 v132, v110, v111
	v_cvt_pk_bf16_f32 v133, v106, v107
	global_store_dwordx4 v[128:129], v[130:133], off sc1

.LBB0_1529:
	s_or_b64 exec, exec, s[0:1]
	v_mul_f32_e32 v114, v109, v109
	v_mul_f32_e32 v128, v113, v113
	v_fmac_f32_e32 v114, v108, v108
	v_fmac_f32_e32 v128, v112, v112
	v_add_f32_e32 v114, v114, v128
	v_mul_f32_e32 v128, v111, v111
	v_mul_f32_e32 v129, v107, v107
	v_fmac_f32_e32 v128, v110, v110
	v_fmac_f32_e32 v129, v106, v106
	v_add_f32_e32 v128, v128, v129
	v_mov_b32_e32 v138, v135
	v_mov_b32_e32 v139, v131
	v_add_f32_e32 v114, v128, v114
	v_mov_b32_e32 v128, v134
	v_mov_b32_e32 v129, v130
	v_pk_mul_f32 v[138:139], v[138:139], v[138:139]
	v_mov_b32_e32 v146, v133
	v_mov_b32_e32 v147, v137
	v_pk_fma_f32 v[128:129], v[128:129], v[128:129], v[138:139]
	v_mov_b32_e32 v138, v132
	v_mov_b32_e32 v139, v136
	v_pk_mul_f32 v[146:147], v[146:147], v[146:147]
	s_lshl_b64 s[0:1], s[44:45], 11
	v_pk_fma_f32 v[138:139], v[138:139], v[138:139], v[146:147]
	s_nop 0
	v_pk_add_f32 v[128:129], v[128:129], v[138:139]
	s_nop 0
	v_add_f32_e32 v114, v114, v129
	v_add_f32_e32 v114, v128, v114
	ds_bpermute_b32 v128, v117, v114
	s_waitcnt lgkmcnt(0)
	v_add_f32_e32 v114, v114, v128
	ds_bpermute_b32 v128, v140, v114
	s_waitcnt lgkmcnt(0)
	v_add_f32_e32 v114, v114, v128
	ds_bpermute_b32 v128, v141, v114
	s_waitcnt lgkmcnt(0)
	v_add_f32_e32 v114, v114, v128
	ds_bpermute_b32 v128, v142, v114
	s_waitcnt lgkmcnt(0)
	v_add_f32_e32 v114, v114, v128
	ds_bpermute_b32 v128, v143, v114
	s_waitcnt lgkmcnt(0)
	v_add_f32_e32 v114, v114, v128
	ds_bpermute_b32 v128, v144, v114
	s_waitcnt lgkmcnt(0)
	v_add_f32_e32 v114, v114, v128
	v_fmamk_f32 v114, v114, 0x3a800000, v145
	v_mul_f32_e32 v128, 0x4b800000, v114
	v_cmp_gt_f32_e32 vcc, s50, v114
	s_nop 1
	v_cndmask_b32_e32 v114, v114, v128, vcc
	v_rsq_f32_e32 v114, v114
	v_lshl_add_u64 v[128:129], v[122:123], 0, s[0:1]
	v_mul_f32_e32 v138, 0x45800000, v114
	v_cndmask_b32_e32 v114, v114, v138, vcc
	v_pk_mul_f32 v[108:109], v[114:115], v[108:109] op_sel_hi:[0,1]
	v_pk_mul_f32 v[112:113], v[114:115], v[112:113] op_sel_hi:[0,1]
	v_pk_mul_f32 v[110:111], v[114:115], v[110:111] op_sel_hi:[0,1]
	v_pk_mul_f32 v[106:107], v[114:115], v[106:107] op_sel_hi:[0,1]
	s_waitcnt vmcnt(3)
	v_pk_fma_f32 v[112:113], v[96:97], v[112:113], v[76:77]
	v_pk_fma_f32 v[108:109], v[94:95], v[108:109], v[74:75]
	s_waitcnt vmcnt(1)
	v_pk_fma_f32 v[138:139], v[92:93], v[106:107], v[84:85]
	v_pk_fma_f32 v[110:111], v[90:91], v[110:111], v[82:83]
	v_cvt_pk_bf16_f32 v106, v108, v109
	v_cvt_pk_bf16_f32 v107, v112, v113
	v_cvt_pk_bf16_f32 v108, v110, v111
	v_cvt_pk_bf16_f32 v109, v138, v139
	global_store_dwordx4 v[128:129], v[106:109], off sc1
	v_pk_mul_f32 v[110:111], v[114:115], v[134:135] op_sel_hi:[0,1]
	v_pk_mul_f32 v[112:113], v[114:115], v[132:133] op_sel_hi:[0,1]
	v_pk_mul_f32 v[106:107], v[114:115], v[130:131] op_sel_hi:[0,1]
	v_pk_mul_f32 v[108:109], v[114:115], v[136:137] op_sel_hi:[0,1]
	s_waitcnt vmcnt(1)
	v_pk_fma_f32 v[108:109], v[100:101], v[108:109], v[88:89]
	v_pk_fma_f32 v[106:107], v[98:99], v[106:107], v[86:87]
	v_pk_fma_f32 v[112:113], v[104:105], v[112:113], v[80:81]
	v_pk_fma_f32 v[110:111], v[102:103], v[110:111], v[78:79]
	v_cvt_pk_bf16_f32 v106, v106, v107
	v_cvt_pk_bf16_f32 v107, v108, v109
	v_cvt_pk_bf16_f32 v108, v110, v111
	v_cvt_pk_bf16_f32 v109, v112, v113
	global_store_dwordx4 v[128:129], v[106:109], off offset:1024 sc1

.LBB0_1538:
	s_or_b64 exec, exec, s[0:1]
	s_ashr_i32 s41, s40, 31
	s_lshl_b64 s[0:1], s[40:41], 12
	s_add_u32 s0, s54, s0
	s_addc_u32 s1, s55, s1
	s_add_i32 s2, s15, 0xc00
	s_and_b32 s2, s2, 0x400
	s_lshl_b32 s2, s2, 1
	s_add_u32 s0, s0, s2
	s_addc_u32 s1, s1, 0
	v_lshlrev_b32_e32 v114, 1, v116
	v_lshl_add_u64 v[128:129], s[0:1], 0, v[114:115]
	v_lshlrev_b32_e32 v108, 16, v38
	v_and_b32_e32 v109, 0xffff0000, v38
	v_lshlrev_b32_e32 v112, 16, v39
	v_and_b32_e32 v113, 0xffff0000, v39
	v_lshlrev_b32_e32 v110, 16, v40
	v_and_b32_e32 v111, 0xffff0000, v40
	v_lshlrev_b32_e32 v106, 16, v41
	v_and_b32_e32 v107, 0xffff0000, v41
	s_and_saveexec_b64 s[0:1], s[8:9]
	s_cbranch_execz .LBB0_1540
	s_waitcnt vmcnt(2)
	v_cvt_f32_f16_sdwa v131, v54 dst_sel:DWORD dst_unused:UNUSED_PAD src0_sel:WORD_1
	v_cvt_f32_f16_e32 v130, v54
	s_waitcnt vmcnt(1)
	v_cvt_f32_f16_sdwa v133, v62 dst_sel:DWORD dst_unused:UNUSED_PAD src0_sel:WORD_1
	v_cvt_f32_f16_e32 v132, v62
	s_waitcnt vmcnt(0)
	v_cvt_f32_f16_sdwa v135, v70 dst_sel:DWORD dst_unused:UNUSED_PAD src0_sel:WORD_1
	v_cvt_f32_f16_e32 v134, v70
	v_cvt_f32_f16_sdwa v137, v55 dst_sel:DWORD dst_unused:UNUSED_PAD src0_sel:WORD_1
	v_cvt_f32_f16_e32 v136, v55
	v_pk_add_f32 v[108:109], v[108:109], v[130:131]
	v_cvt_f32_f16_sdwa v131, v63 dst_sel:DWORD dst_unused:UNUSED_PAD src0_sel:WORD_1
	v_cvt_f32_f16_e32 v130, v63
	v_pk_add_f32 v[108:109], v[108:109], v[132:133]
	v_cvt_f32_f16_sdwa v133, v71 dst_sel:DWORD dst_unused:UNUSED_PAD src0_sel:WORD_1
	v_cvt_f32_f16_e32 v132, v71
	v_pk_add_f32 v[108:109], v[108:109], v[134:135]
	v_cvt_f32_f16_sdwa v135, v56 dst_sel:DWORD dst_unused:UNUSED_PAD src0_sel:WORD_1
	v_cvt_f32_f16_e32 v134, v56
	v_pk_add_f32 v[112:113], v[112:113], v[136:137]
	v_cvt_f32_f16_sdwa v137, v64 dst_sel:DWORD dst_unused:UNUSED_PAD src0_sel:WORD_1
	v_cvt_f32_f16_e32 v136, v64
	v_pk_add_f32 v[112:113], v[112:113], v[130:131]
	v_pk_add_f32 v[110:111], v[110:111], v[134:135]
	v_pk_add_f32 v[112:113], v[112:113], v[132:133]
	v_cvt_f32_f16_sdwa v133, v57 dst_sel:DWORD dst_unused:UNUSED_PAD src0_sel:WORD_1
	v_cvt_f32_f16_e32 v132, v57
	v_cvt_f32_f16_sdwa v135, v65 dst_sel:DWORD dst_unused:UNUSED_PAD src0_sel:WORD_1
	v_cvt_f32_f16_e32 v134, v65
	v_pk_add_f32 v[110:111], v[110:111], v[136:137]
	v_cvt_f32_f16_sdwa v131, v72 dst_sel:DWORD dst_unused:UNUSED_PAD src0_sel:WORD_1
	v_cvt_f32_f16_e32 v130, v72
	v_cvt_f32_f16_sdwa v137, v73 dst_sel:DWORD dst_unused:UNUSED_PAD src0_sel:WORD_1
	v_cvt_f32_f16_e32 v136, v73
	v_pk_add_f32 v[106:107], v[106:107], v[132:133]
	v_pk_add_f32 v[110:111], v[110:111], v[130:131]
	v_pk_add_f32 v[106:107], v[106:107], v[134:135]
	v_cvt_pk_bf16_f32 v130, v108, v109
	v_pk_add_f32 v[106:107], v[106:107], v[136:137]
	v_cvt_pk_bf16_f32 v131, v112, v113
	v_cvt_pk_bf16_f32 v132, v110, v111
	v_cvt_pk_bf16_f32 v133, v106, v107
	global_store_dwordx4 v[128:129], v[130:133], off sc1

.LBB0_1542:
	s_or_b64 exec, exec, s[0:1]
	v_mul_f32_e32 v114, v109, v109
	v_mul_f32_e32 v128, v113, v113
	v_fmac_f32_e32 v114, v108, v108
	v_fmac_f32_e32 v128, v112, v112
	v_add_f32_e32 v114, v114, v128
	v_mul_f32_e32 v128, v111, v111
	v_mul_f32_e32 v129, v107, v107
	v_fmac_f32_e32 v128, v110, v110
	v_fmac_f32_e32 v129, v106, v106
	v_add_f32_e32 v128, v128, v129
	v_mov_b32_e32 v138, v135
	v_mov_b32_e32 v139, v131
	v_add_f32_e32 v114, v128, v114
	v_mov_b32_e32 v128, v134
	v_mov_b32_e32 v129, v130
	v_pk_mul_f32 v[138:139], v[138:139], v[138:139]
	v_mov_b32_e32 v146, v133
	v_mov_b32_e32 v147, v137
	v_pk_fma_f32 v[128:129], v[128:129], v[128:129], v[138:139]
	v_mov_b32_e32 v138, v132
	v_mov_b32_e32 v139, v136
	v_pk_mul_f32 v[146:147], v[146:147], v[146:147]
	s_lshl_b64 s[0:1], s[40:41], 11
	v_pk_fma_f32 v[138:139], v[138:139], v[138:139], v[146:147]
	s_nop 0
	v_pk_add_f32 v[128:129], v[128:129], v[138:139]
	s_nop 0
	v_add_f32_e32 v114, v114, v129
	v_add_f32_e32 v114, v128, v114
	ds_bpermute_b32 v128, v117, v114
	s_waitcnt lgkmcnt(0)
	v_add_f32_e32 v114, v114, v128
	ds_bpermute_b32 v128, v140, v114
	s_waitcnt lgkmcnt(0)
	v_add_f32_e32 v114, v114, v128
	ds_bpermute_b32 v128, v141, v114
	s_waitcnt lgkmcnt(0)
	v_add_f32_e32 v114, v114, v128
	ds_bpermute_b32 v128, v142, v114
	s_waitcnt lgkmcnt(0)
	v_add_f32_e32 v114, v114, v128
	ds_bpermute_b32 v128, v143, v114
	s_waitcnt lgkmcnt(0)
	v_add_f32_e32 v114, v114, v128
	ds_bpermute_b32 v128, v144, v114
	s_waitcnt lgkmcnt(0)
	v_add_f32_e32 v114, v114, v128
	v_fmamk_f32 v114, v114, 0x3a800000, v145
	v_mul_f32_e32 v128, 0x4b800000, v114
	v_cmp_gt_f32_e32 vcc, s50, v114
	s_nop 1
	v_cndmask_b32_e32 v114, v114, v128, vcc
	v_rsq_f32_e32 v114, v114
	v_lshl_add_u64 v[128:129], v[122:123], 0, s[0:1]
	v_mul_f32_e32 v138, 0x45800000, v114
	v_cndmask_b32_e32 v114, v114, v138, vcc
	v_pk_mul_f32 v[108:109], v[114:115], v[108:109] op_sel_hi:[0,1]
	v_pk_mul_f32 v[112:113], v[114:115], v[112:113] op_sel_hi:[0,1]
	v_pk_mul_f32 v[110:111], v[114:115], v[110:111] op_sel_hi:[0,1]
	v_pk_mul_f32 v[106:107], v[114:115], v[106:107] op_sel_hi:[0,1]
	s_waitcnt vmcnt(3)
	v_pk_fma_f32 v[112:113], v[96:97], v[112:113], v[76:77]
	v_pk_fma_f32 v[108:109], v[94:95], v[108:109], v[74:75]
	s_waitcnt vmcnt(1)
	v_pk_fma_f32 v[138:139], v[92:93], v[106:107], v[84:85]
	v_pk_fma_f32 v[110:111], v[90:91], v[110:111], v[82:83]
	v_cvt_pk_bf16_f32 v106, v108, v109
	v_cvt_pk_bf16_f32 v107, v112, v113
	v_cvt_pk_bf16_f32 v108, v110, v111
	v_cvt_pk_bf16_f32 v109, v138, v139
	global_store_dwordx4 v[128:129], v[106:109], off sc1
	v_pk_mul_f32 v[110:111], v[114:115], v[134:135] op_sel_hi:[0,1]
	v_pk_mul_f32 v[112:113], v[114:115], v[132:133] op_sel_hi:[0,1]
	v_pk_mul_f32 v[106:107], v[114:115], v[130:131] op_sel_hi:[0,1]
	v_pk_mul_f32 v[108:109], v[114:115], v[136:137] op_sel_hi:[0,1]
	s_waitcnt vmcnt(1)
	v_pk_fma_f32 v[108:109], v[100:101], v[108:109], v[88:89]
	v_pk_fma_f32 v[106:107], v[98:99], v[106:107], v[86:87]
	v_pk_fma_f32 v[112:113], v[104:105], v[112:113], v[80:81]
	v_pk_fma_f32 v[110:111], v[102:103], v[110:111], v[78:79]
	v_cvt_pk_bf16_f32 v106, v106, v107
	v_cvt_pk_bf16_f32 v107, v108, v109
	v_cvt_pk_bf16_f32 v108, v110, v111
	v_cvt_pk_bf16_f32 v109, v112, v113
	global_store_dwordx4 v[128:129], v[106:109], off offset:1024 sc1

.LBB0_1551:
	s_or_b64 exec, exec, s[0:1]
	s_ashr_i32 s37, s36, 31
	s_lshl_b64 s[0:1], s[36:37], 12
	s_add_u32 s0, s54, s0
	s_addc_u32 s1, s55, s1
	s_lshl_b32 s2, s62, 1
	s_add_u32 s0, s0, s2
	s_addc_u32 s1, s1, 0
	v_lshlrev_b32_e32 v114, 1, v116
	v_lshl_add_u64 v[128:129], s[0:1], 0, v[114:115]
	v_lshlrev_b32_e32 v108, 16, v22
	v_and_b32_e32 v109, 0xffff0000, v22
	v_lshlrev_b32_e32 v112, 16, v23
	v_and_b32_e32 v113, 0xffff0000, v23
	v_lshlrev_b32_e32 v110, 16, v24
	v_and_b32_e32 v111, 0xffff0000, v24
	v_lshlrev_b32_e32 v106, 16, v25
	v_and_b32_e32 v107, 0xffff0000, v25
	s_and_saveexec_b64 s[0:1], s[6:7]
	s_cbranch_execz .LBB0_1553
	s_waitcnt vmcnt(2)
	v_cvt_f32_f16_sdwa v131, v54 dst_sel:DWORD dst_unused:UNUSED_PAD src0_sel:WORD_1
	v_cvt_f32_f16_e32 v130, v54
	s_waitcnt vmcnt(1)
	v_cvt_f32_f16_sdwa v133, v62 dst_sel:DWORD dst_unused:UNUSED_PAD src0_sel:WORD_1
	v_cvt_f32_f16_e32 v132, v62
	s_waitcnt vmcnt(0)
	v_cvt_f32_f16_sdwa v135, v70 dst_sel:DWORD dst_unused:UNUSED_PAD src0_sel:WORD_1
	v_cvt_f32_f16_e32 v134, v70
	v_cvt_f32_f16_sdwa v137, v55 dst_sel:DWORD dst_unused:UNUSED_PAD src0_sel:WORD_1
	v_cvt_f32_f16_e32 v136, v55
	v_pk_add_f32 v[108:109], v[108:109], v[130:131]
	v_cvt_f32_f16_sdwa v131, v63 dst_sel:DWORD dst_unused:UNUSED_PAD src0_sel:WORD_1
	v_cvt_f32_f16_e32 v130, v63
	v_pk_add_f32 v[108:109], v[108:109], v[132:133]
	v_cvt_f32_f16_sdwa v133, v71 dst_sel:DWORD dst_unused:UNUSED_PAD src0_sel:WORD_1
	v_cvt_f32_f16_e32 v132, v71
	v_pk_add_f32 v[108:109], v[108:109], v[134:135]
	v_cvt_f32_f16_sdwa v135, v56 dst_sel:DWORD dst_unused:UNUSED_PAD src0_sel:WORD_1
	v_cvt_f32_f16_e32 v134, v56
	v_pk_add_f32 v[112:113], v[112:113], v[136:137]
	v_cvt_f32_f16_sdwa v137, v64 dst_sel:DWORD dst_unused:UNUSED_PAD src0_sel:WORD_1
	v_cvt_f32_f16_e32 v136, v64
	v_pk_add_f32 v[112:113], v[112:113], v[130:131]
	v_pk_add_f32 v[110:111], v[110:111], v[134:135]
	v_pk_add_f32 v[112:113], v[112:113], v[132:133]
	v_cvt_f32_f16_sdwa v133, v57 dst_sel:DWORD dst_unused:UNUSED_PAD src0_sel:WORD_1
	v_cvt_f32_f16_e32 v132, v57
	v_cvt_f32_f16_sdwa v135, v65 dst_sel:DWORD dst_unused:UNUSED_PAD src0_sel:WORD_1
	v_cvt_f32_f16_e32 v134, v65
	v_pk_add_f32 v[110:111], v[110:111], v[136:137]
	v_cvt_f32_f16_sdwa v131, v72 dst_sel:DWORD dst_unused:UNUSED_PAD src0_sel:WORD_1
	v_cvt_f32_f16_e32 v130, v72
	v_cvt_f32_f16_sdwa v137, v73 dst_sel:DWORD dst_unused:UNUSED_PAD src0_sel:WORD_1
	v_cvt_f32_f16_e32 v136, v73
	v_pk_add_f32 v[106:107], v[106:107], v[132:133]
	v_pk_add_f32 v[110:111], v[110:111], v[130:131]
	v_pk_add_f32 v[106:107], v[106:107], v[134:135]
	v_cvt_pk_bf16_f32 v130, v108, v109
	v_pk_add_f32 v[106:107], v[106:107], v[136:137]
	v_cvt_pk_bf16_f32 v131, v112, v113
	v_cvt_pk_bf16_f32 v132, v110, v111
	v_cvt_pk_bf16_f32 v133, v106, v107
	global_store_dwordx4 v[128:129], v[130:133], off sc1
